# speedup vs baseline: 1.0390x; 1.0145x over previous
; __device__ __forceinline__ void conv_item(const Params& p, int l, int item) {
;     ...
;         const int c = tid;
;         float wj[31];
; #pragma unroll
;         for (int j = 0; j < 31; ++j) wj[j] = p.conv_w[(l * 31 + j) * 512 + c];
;         const float bias = p.conv_b[l * 512 + c];
;         float win[62];
; #pragma unroll
;         for (int i = 0; i < 62; ++i) win[i] = __builtin_bit_cast(float, (unsigned)U[i * 512 + c] << 16);
.LBB0_170:
	s_or_b64 exec, exec, s[0:1]
	s_waitcnt vmcnt(0)
	v_add_u32_e32 v4, s2, v30
	v_ashrrev_i32_e32 v5, 31, v4
	v_lshl_add_u64 v[8:9], v[4:5], 2, s[56:57]
	v_add_u32_e32 v4, s2, v31
	v_ashrrev_i32_e32 v5, 31, v4
	v_lshl_add_u64 v[10:11], v[4:5], 2, s[56:57]
	v_add_u32_e32 v4, s2, v32
	v_ashrrev_i32_e32 v5, 31, v4
	v_add_u32_e32 v24, s2, v29
	v_lshl_add_u64 v[12:13], v[4:5], 2, s[56:57]
	v_add_u32_e32 v4, s2, v33
	v_add_u32_e32 v2, 0x400, v24
	v_ashrrev_i32_e32 v5, 31, v4
	v_ashrrev_i32_e32 v25, 31, v24
	v_ashrrev_i32_e32 v3, 31, v2
	v_lshl_add_u64 v[14:15], v[4:5], 2, s[56:57]
	v_add_u32_e32 v4, s2, v34
	v_lshl_add_u64 v[0:1], v[24:25], 2, s[56:57]
	v_lshl_add_u64 v[2:3], v[2:3], 2, s[56:57]
	v_ashrrev_i32_e32 v5, 31, v4
	s_waitcnt lgkmcnt(0)
	s_barrier
	v_lshl_add_u64 v[16:17], v[4:5], 2, s[56:57]
	global_load_dword v7, v[0:1], off
	global_load_dword v6, v[0:1], off offset:2048
	global_load_dword v5, v[2:3], off
	global_load_dword v4, v[8:9], off
	s_nop 0
	global_load_dword v3, v[10:11], off
	global_load_dword v2, v[12:13], off
	global_load_dword v1, v[14:15], off
	global_load_dword v0, v[16:17], off
	v_add_u32_e32 v14, 0x1600, v24
	v_ashrrev_i32_e32 v15, 31, v14
	v_lshl_add_u64 v[16:17], v[14:15], 2, s[56:57]
	v_add_u32_e32 v14, 0x1800, v24
	v_ashrrev_i32_e32 v15, 31, v14
	v_lshl_add_u64 v[18:19], v[14:15], 2, s[56:57]
	v_add_u32_e32 v14, 0x1a00, v24
	v_ashrrev_i32_e32 v15, 31, v14
	v_lshl_add_u64 v[20:21], v[14:15], 2, s[56:57]
	v_add_u32_e32 v14, 0x1c00, v24
	v_add_u32_e32 v8, 0x1000, v24
	v_add_u32_e32 v10, 0x1200, v24
	v_add_u32_e32 v12, 0x1400, v24
	v_ashrrev_i32_e32 v15, 31, v14
	v_ashrrev_i32_e32 v9, 31, v8
	v_ashrrev_i32_e32 v11, 31, v10
	v_ashrrev_i32_e32 v13, 31, v12
	v_lshl_add_u64 v[22:23], v[14:15], 2, s[56:57]
	v_add_u32_e32 v14, 0x1e00, v24
	v_lshl_add_u64 v[8:9], v[8:9], 2, s[56:57]
	v_lshl_add_u64 v[10:11], v[10:11], 2, s[56:57]
	v_lshl_add_u64 v[12:13], v[12:13], 2, s[56:57]
	v_ashrrev_i32_e32 v15, 31, v14
	v_lshl_add_u64 v[26:27], v[14:15], 2, s[56:57]
	global_load_dword v15, v[8:9], off
	global_load_dword v14, v[10:11], off
	s_nop 0
	global_load_dword v13, v[12:13], off
	s_nop 0
	global_load_dword v12, v[16:17], off
	global_load_dword v11, v[18:19], off
	global_load_dword v10, v[20:21], off
	global_load_dword v9, v[22:23], off
	global_load_dword v8, v[26:27], off
	v_add_u32_e32 v22, 0x2600, v24
	v_ashrrev_i32_e32 v23, 31, v22
	v_lshl_add_u64 v[26:27], v[22:23], 2, s[56:57]
	v_add_u32_e32 v22, 0x2800, v24
	v_ashrrev_i32_e32 v23, 31, v22
	v_lshl_add_u64 v[30:31], v[22:23], 2, s[56:57]
	v_add_u32_e32 v22, 0x2a00, v24
	v_ashrrev_i32_e32 v23, 31, v22
	v_lshl_add_u64 v[32:33], v[22:23], 2, s[56:57]
	v_add_u32_e32 v22, 0x2c00, v24
	v_add_u32_e32 v16, 0x2000, v24
	v_add_u32_e32 v18, 0x2200, v24
	v_add_u32_e32 v20, 0x2400, v24
	v_ashrrev_i32_e32 v23, 31, v22
	v_ashrrev_i32_e32 v17, 31, v16
	v_ashrrev_i32_e32 v19, 31, v18
	v_ashrrev_i32_e32 v21, 31, v20
	v_lshl_add_u64 v[34:35], v[22:23], 2, s[56:57]
	v_add_u32_e32 v22, 0x2e00, v24
	v_lshl_add_u64 v[16:17], v[16:17], 2, s[56:57]
	v_lshl_add_u64 v[18:19], v[18:19], 2, s[56:57]
	v_lshl_add_u64 v[20:21], v[20:21], 2, s[56:57]
	v_ashrrev_i32_e32 v23, 31, v22
	v_lshl_add_u64 v[36:37], v[22:23], 2, s[56:57]
	global_load_dword v23, v[16:17], off
	global_load_dword v22, v[18:19], off
	s_nop 0
	global_load_dword v21, v[20:21], off
	s_nop 0
	global_load_dword v20, v[26:27], off
	global_load_dword v19, v[30:31], off
	global_load_dword v18, v[32:33], off
	global_load_dword v17, v[34:35], off
	global_load_dword v16, v[36:37], off
	v_add_u32_e32 v32, 0x3400, v24
	v_ashrrev_i32_e32 v33, 31, v32
	v_lshl_add_u64 v[34:35], v[32:33], 2, s[56:57]
	v_add_u32_e32 v32, 0x3600, v24
	v_ashrrev_i32_e32 v33, 31, v32
	v_lshl_add_u64 v[36:37], v[32:33], 2, s[56:57]
	v_add_u32_e32 v32, 0x3800, v24
	v_add_u32_e32 v26, 0x3000, v24
	v_add_u32_e32 v30, 0x3200, v24
	v_ashrrev_i32_e32 v33, 31, v32
	v_ashrrev_i32_e32 v27, 31, v26
	v_ashrrev_i32_e32 v31, 31, v30
	v_lshl_add_u64 v[38:39], v[32:33], 2, s[56:57]
	v_add_u32_e32 v32, 0x3a00, v24
	v_add_u32_e32 v24, 0x3c00, v24
	v_lshl_add_u64 v[26:27], v[26:27], 2, s[56:57]
	v_lshl_add_u64 v[30:31], v[30:31], 2, s[56:57]
	v_ashrrev_i32_e32 v33, 31, v32
	v_ashrrev_i32_e32 v25, 31, v24
	v_lshl_add_u64 v[40:41], v[32:33], 2, s[56:57]
	v_lshl_add_u64 v[42:43], v[24:25], 2, s[56:57]
	global_load_dword v33, v[26:27], off
	s_nop 0
	global_load_dword v31, v[30:31], off
	s_nop 0
	global_load_dword v30, v[34:35], off
	global_load_dword v27, v[36:37], off
	global_load_dword v26, v[38:39], off
	global_load_dword v25, v[40:41], off
	global_load_dword v24, v[42:43], off
	v_add_u32_e32 v34, s72, v29
	v_ashrrev_i32_e32 v35, 31, v34
	v_lshl_add_u64 v[34:35], v[34:35], 2, s[58:59]
	global_load_dword v32, v[34:35], off
	v_lshl_add_u32 v34, v29, 1, 0
	ds_read_u16 v35, v34
	ds_read_u16 v36, v34 offset:1024
	ds_read_u16 v37, v34 offset:57344
	ds_read_u16 v38, v34 offset:58368
	ds_read_u16 v90, v34 offset:59392
	ds_read_u16 v91, v34 offset:60416
	ds_read_u16 v92, v34 offset:61440
	ds_read_u16 v93, v34 offset:62464
	s_waitcnt lgkmcnt(7)
	v_lshlrev_b32_e32 v94, 16, v35
	s_waitcnt lgkmcnt(6)
	v_lshlrev_b32_e32 v95, 16, v36
	ds_read_u16 v35, v34 offset:2048
	ds_read_u16 v36, v34 offset:3072
	ds_read_u16 v39, v34 offset:4096
	ds_read_u16 v40, v34 offset:5120
	ds_read_u16 v41, v34 offset:6144
	ds_read_u16 v42, v34 offset:7168
	ds_read_u16 v43, v34 offset:8192
	ds_read_u16 v44, v34 offset:9216
	s_waitcnt lgkmcnt(7)
	v_lshlrev_b32_e32 v96, 16, v35
	s_waitcnt lgkmcnt(6)
	v_lshlrev_b32_e32 v97, 16, v36
	s_waitcnt lgkmcnt(5)
	v_lshlrev_b32_e32 v98, 16, v39
	s_waitcnt lgkmcnt(4)
; __device__ __forceinline__ void conv_item(const Params& p, int l, int item) {
;     ...
;         float win[62];
; #pragma unroll
;         for (int i = 0; i < 62; ++i) win[i] = __builtin_bit_cast(float, (unsigned)U[i * 512 + c] << 16);
	v_lshlrev_b32_e32 v99, 16, v40
	s_waitcnt lgkmcnt(3)
	v_lshlrev_b32_e32 v100, 16, v41
	s_waitcnt lgkmcnt(2)
	v_lshlrev_b32_e32 v89, 16, v42
	s_waitcnt lgkmcnt(1)
	v_lshlrev_b32_e32 v88, 16, v43
	s_waitcnt lgkmcnt(0)
	v_lshlrev_b32_e32 v87, 16, v44
	ds_read_u16 v35, v34 offset:10240
	ds_read_u16 v36, v34 offset:11264
	ds_read_u16 v39, v34 offset:12288
	ds_read_u16 v40, v34 offset:13312
	ds_read_u16 v41, v34 offset:14336
	ds_read_u16 v42, v34 offset:15360
	ds_read_u16 v43, v34 offset:16384
	ds_read_u16 v44, v34 offset:17408
	s_waitcnt lgkmcnt(7)
	v_lshlrev_b32_e32 v86, 16, v35
	s_waitcnt lgkmcnt(6)
	v_lshlrev_b32_e32 v85, 16, v36
	s_waitcnt lgkmcnt(5)
	v_lshlrev_b32_e32 v84, 16, v39
	s_waitcnt lgkmcnt(4)
	v_lshlrev_b32_e32 v83, 16, v40
	s_waitcnt lgkmcnt(3)
	v_lshlrev_b32_e32 v82, 16, v41
	s_waitcnt lgkmcnt(2)
	v_lshlrev_b32_e32 v81, 16, v42
	s_waitcnt lgkmcnt(1)
	v_lshlrev_b32_e32 v80, 16, v43
	s_waitcnt lgkmcnt(0)
	v_lshlrev_b32_e32 v79, 16, v44
	ds_read_u16 v35, v34 offset:18432
	ds_read_u16 v36, v34 offset:19456
	ds_read_u16 v39, v34 offset:20480
	ds_read_u16 v40, v34 offset:21504
	ds_read_u16 v41, v34 offset:22528
	ds_read_u16 v42, v34 offset:23552
	ds_read_u16 v43, v34 offset:24576
	ds_read_u16 v44, v34 offset:25600
	s_waitcnt lgkmcnt(7)
	v_lshlrev_b32_e32 v78, 16, v35
	s_waitcnt lgkmcnt(6)
	v_lshlrev_b32_e32 v77, 16, v36
	s_waitcnt lgkmcnt(5)
	v_lshlrev_b32_e32 v76, 16, v39
	s_waitcnt lgkmcnt(4)
	v_lshlrev_b32_e32 v75, 16, v40
	s_waitcnt lgkmcnt(3)
	v_lshlrev_b32_e32 v74, 16, v41
	s_waitcnt lgkmcnt(2)
	v_lshlrev_b32_e32 v73, 16, v42
	ds_read_u16 v35, v34 offset:26624
	ds_read_u16 v36, v34 offset:27648
	ds_read_u16 v39, v34 offset:28672
	ds_read_u16 v40, v34 offset:29696
	ds_read_u16 v41, v34 offset:30720
	ds_read_u16 v42, v34 offset:31744
	s_waitcnt lgkmcnt(7)
	v_lshlrev_b32_e32 v72, 16, v43
	s_waitcnt lgkmcnt(6)
	v_lshlrev_b32_e32 v71, 16, v44
	s_waitcnt lgkmcnt(5)
	v_lshlrev_b32_e32 v70, 16, v35
	s_waitcnt lgkmcnt(4)
	v_lshlrev_b32_e32 v69, 16, v36
	s_waitcnt lgkmcnt(3)
	v_lshlrev_b32_e32 v68, 16, v39
	s_waitcnt lgkmcnt(2)
	v_lshlrev_b32_e32 v67, 16, v40
	s_waitcnt lgkmcnt(1)
	v_lshlrev_b32_e32 v66, 16, v41
	s_waitcnt lgkmcnt(0)
	v_lshlrev_b32_e32 v41, 16, v42
	ds_read_u16 v35, v34 offset:32768
	ds_read_u16 v36, v34 offset:33792
	ds_read_u16 v39, v34 offset:34816
	ds_read_u16 v40, v34 offset:35840
	ds_read_u16 v42, v34 offset:36864
	ds_read_u16 v43, v34 offset:37888
	ds_read_u16 v44, v34 offset:38912
	ds_read_u16 v46, v34 offset:39936
	s_waitcnt lgkmcnt(7)
	v_lshlrev_b32_e32 v63, 16, v35
	s_waitcnt lgkmcnt(6)
	v_lshlrev_b32_e32 v60, 16, v36
	s_waitcnt lgkmcnt(5)
	v_lshlrev_b32_e32 v57, 16, v39
	s_waitcnt lgkmcnt(4)
	v_lshlrev_b32_e32 v54, 16, v40
	s_waitcnt lgkmcnt(3)
	v_lshlrev_b32_e32 v51, 16, v42
	s_waitcnt lgkmcnt(2)
	v_lshlrev_b32_e32 v48, 16, v43
	s_waitcnt lgkmcnt(1)
	v_lshlrev_b32_e32 v45, 16, v44
	s_waitcnt lgkmcnt(0)
	v_lshlrev_b32_e32 v42, 16, v46
	ds_read_u16 v35, v34 offset:40960
	ds_read_u16 v36, v34 offset:41984
	ds_read_u16 v39, v34 offset:43008
	ds_read_u16 v40, v34 offset:44032
	ds_read_u16 v43, v34 offset:45056
	ds_read_u16 v44, v34 offset:46080
	ds_read_u16 v46, v34 offset:47104
	ds_read_u16 v47, v34 offset:48128
	s_waitcnt lgkmcnt(7)
	v_lshlrev_b32_e32 v64, 16, v35
	s_waitcnt lgkmcnt(6)
	v_lshlrev_b32_e32 v61, 16, v36
	s_waitcnt lgkmcnt(5)
	v_lshlrev_b32_e32 v58, 16, v39
	s_waitcnt lgkmcnt(4)
	v_lshlrev_b32_e32 v55, 16, v40
	s_waitcnt lgkmcnt(3)
	v_lshlrev_b32_e32 v52, 16, v43
	s_waitcnt lgkmcnt(2)
	v_lshlrev_b32_e32 v49, 16, v44
	s_waitcnt lgkmcnt(0)
	v_lshlrev_b32_e32 v43, 16, v47
	ds_read_u16 v35, v34 offset:49152
	ds_read_u16 v36, v34 offset:50176
	ds_read_u16 v39, v34 offset:51200
	ds_read_u16 v40, v34 offset:52224
	ds_read_u16 v44, v34 offset:53248
	ds_read_u16 v47, v34 offset:54272
	ds_read_u16 v101, v34 offset:55296
	ds_read_u16 v34, v34 offset:56320
	s_waitcnt lgkmcnt(4)
	v_lshlrev_b32_e32 v56, 16, v40
	v_lshlrev_b32_e32 v40, 16, v37
	v_lshlrev_b32_e32 v37, 16, v91
	v_lshlrev_b32_e32 v59, 16, v39
	v_lshlrev_b32_e32 v39, 16, v38
	v_lshlrev_b32_e32 v38, 16, v90
	v_lshl_add_u32 v90, v29, 2, 0
	v_lshlrev_b32_e32 v62, 16, v36
	v_add_u32_e32 v36, 0xf800, v90
	v_lshlrev_b32_e32 v46, 16, v46
	v_lshlrev_b32_e32 v65, 16, v35
	s_waitcnt lgkmcnt(3)
	v_lshlrev_b32_e32 v53, 16, v44
	s_waitcnt lgkmcnt(2)
	v_lshlrev_b32_e32 v50, 16, v47
	s_waitcnt lgkmcnt(1)
	v_lshlrev_b32_e32 v47, 16, v101
	s_waitcnt lgkmcnt(0)
	v_lshlrev_b32_e32 v44, 16, v34
	v_lshlrev_b32_e32 v35, 16, v92
	s_movk_i32 s0, 0x1000
	v_lshlrev_b32_e32 v34, 16, v93
	s_mov_b64 s[10:11], 0x1000
	s_mov_b32 s12, 0x3b000000
	s_waitcnt vmcnt(0)
; __device__ __forceinline__ void conv_item(const Params& p, int l, int item) {
;     ...
; #pragma unroll
;         for (int t = 0; t < 32; ++t) {
;             float a = bias;
; #pragma unroll
;             for (int j = 0; j < 31; ++j) a = fmaf(wj[j], win[t + j], a);
;             CV[t * 512 + c] = a;
;         }
;     ...
;             bf16_t* gp = P1 + (long)(R0 + t) * P1W + 2048 + lane * 8;
;             uint4 gv = ld_nt_u4(gp);
	v_lshrrev_b32_e32 v156, 6, v208
	v_lshl_add_u32 v156, v156, 2, s3
	v_lshlrev_b32_e32 v156, 13, v156
	v_and_b32_e32 v157, 63, v208
	v_lshl_add_u32 v156, v157, 4, v156
	v_add_u32_e32 v156, 0x1000, v156
	global_load_dwordx4 v[140:143], v156, s[78:79] nt
	v_add_u32_e32 v156, 0x2000, v156
	global_load_dwordx4 v[144:147], v156, s[78:79] nt
	v_add_u32_e32 v156, 0x2000, v156
	global_load_dwordx4 v[148:151], v156, s[78:79] nt
	v_add_u32_e32 v156, 0x2000, v156
	global_load_dwordx4 v[152:155], v156, s[78:79] nt
	v_fma_f32 v91, v7, v94, v32
	v_fmac_f32_e32 v91, v6, v95
	v_fmac_f32_e32 v91, v5, v96
	v_fmac_f32_e32 v91, v4, v97
	v_fmac_f32_e32 v91, v3, v98
	v_fmac_f32_e32 v91, v2, v99
	v_fmac_f32_e32 v91, v1, v100
	v_fmac_f32_e32 v91, v0, v89
	v_fmac_f32_e32 v91, v15, v88
	v_fmac_f32_e32 v91, v14, v87
	v_fmac_f32_e32 v91, v13, v86
	v_fmac_f32_e32 v91, v12, v85
	v_fmac_f32_e32 v91, v11, v84
	v_fmac_f32_e32 v91, v10, v83
	v_fmac_f32_e32 v91, v9, v82
	v_fmac_f32_e32 v91, v8, v81
	v_fmac_f32_e32 v91, v23, v80
	v_fmac_f32_e32 v91, v22, v79
	v_fmac_f32_e32 v91, v21, v78
	v_fmac_f32_e32 v91, v20, v77
	v_fmac_f32_e32 v91, v19, v76
	v_fmac_f32_e32 v91, v18, v75
	v_fmac_f32_e32 v91, v17, v74
	v_fmac_f32_e32 v91, v16, v73
	v_fmac_f32_e32 v91, v33, v72
	v_fmac_f32_e32 v91, v31, v71
	v_fmac_f32_e32 v91, v30, v70
	v_fmac_f32_e32 v91, v27, v69
	v_fmac_f32_e32 v91, v26, v68
	v_fmac_f32_e32 v91, v25, v67
	v_fmac_f32_e32 v91, v24, v66
	ds_write_b32 v90, v91 offset:63488
	v_fma_f32 v90, v7, v95, v32
	v_fma_f32 v91, v7, v96, v32
	v_fmac_f32_e32 v90, v6, v96
	v_fmac_f32_e32 v91, v6, v97
	v_fmac_f32_e32 v90, v5, v97
	v_fmac_f32_e32 v91, v5, v98
	v_fmac_f32_e32 v90, v4, v98
	v_fmac_f32_e32 v91, v4, v99
	v_fmac_f32_e32 v90, v3, v99
	v_fmac_f32_e32 v91, v3, v100
	v_fmac_f32_e32 v90, v2, v100
	v_fmac_f32_e32 v91, v2, v89
	v_fmac_f32_e32 v90, v1, v89
	v_fmac_f32_e32 v91, v1, v88
	v_fmac_f32_e32 v90, v0, v88
	v_fmac_f32_e32 v91, v0, v87
	v_fmac_f32_e32 v90, v15, v87
	v_fmac_f32_e32 v91, v15, v86
	v_fmac_f32_e32 v90, v14, v86
	v_fmac_f32_e32 v91, v14, v85
	v_fmac_f32_e32 v90, v13, v85
	v_fmac_f32_e32 v91, v13, v84
	v_fmac_f32_e32 v90, v12, v84
	v_fmac_f32_e32 v91, v12, v83
	v_fmac_f32_e32 v90, v11, v83
	v_fmac_f32_e32 v91, v11, v82
	v_fmac_f32_e32 v90, v10, v82
	v_fmac_f32_e32 v91, v10, v81
	v_fmac_f32_e32 v90, v9, v81
	v_fmac_f32_e32 v91, v9, v80
	v_fmac_f32_e32 v90, v8, v80
	v_fmac_f32_e32 v91, v8, v79
	v_fmac_f32_e32 v90, v23, v79
	v_fmac_f32_e32 v91, v23, v78
	v_fmac_f32_e32 v90, v22, v78
	v_fmac_f32_e32 v91, v22, v77
	v_fmac_f32_e32 v90, v21, v77
	v_fmac_f32_e32 v91, v21, v76
	v_fmac_f32_e32 v90, v20, v76
	v_fmac_f32_e32 v91, v20, v75
	v_fmac_f32_e32 v90, v19, v75
	v_fmac_f32_e32 v91, v19, v74
	v_fmac_f32_e32 v90, v18, v74
	v_fmac_f32_e32 v91, v18, v73
	v_fmac_f32_e32 v90, v17, v73
	v_fmac_f32_e32 v91, v17, v72
	v_fmac_f32_e32 v90, v16, v72
	v_fmac_f32_e32 v91, v16, v71
	v_fmac_f32_e32 v90, v33, v71
	v_fmac_f32_e32 v91, v33, v70
	v_fmac_f32_e32 v90, v31, v70
	v_fmac_f32_e32 v91, v31, v69
	v_fmac_f32_e32 v90, v30, v69
	v_fmac_f32_e32 v91, v30, v68
	v_fmac_f32_e32 v90, v27, v68
	v_fmac_f32_e32 v91, v27, v67
	v_fmac_f32_e32 v90, v26, v67
	v_fmac_f32_e32 v91, v26, v66
	v_fmac_f32_e32 v90, v25, v66
	v_fmac_f32_e32 v91, v25, v41
	v_fmac_f32_e32 v90, v24, v41
	v_fmac_f32_e32 v91, v24, v63
	ds_write2st64_b32 v36, v90, v91 offset0:8 offset1:16
	v_fma_f32 v90, v7, v97, v32
	v_fma_f32 v91, v7, v98, v32
	v_fmac_f32_e32 v90, v6, v98
	v_fmac_f32_e32 v91, v6, v99
	v_fmac_f32_e32 v90, v5, v99
	v_fmac_f32_e32 v91, v5, v100
	v_fmac_f32_e32 v90, v4, v100
	v_fmac_f32_e32 v91, v4, v89
	v_fmac_f32_e32 v90, v3, v89
	v_fmac_f32_e32 v91, v3, v88
	v_fmac_f32_e32 v90, v2, v88
	v_fmac_f32_e32 v91, v2, v87
	v_fmac_f32_e32 v90, v1, v87
	v_fmac_f32_e32 v91, v1, v86
	v_fmac_f32_e32 v90, v0, v86
	v_fmac_f32_e32 v91, v0, v85
	v_fmac_f32_e32 v90, v15, v85
	v_fmac_f32_e32 v91, v15, v84
	v_fmac_f32_e32 v90, v14, v84
	v_fmac_f32_e32 v91, v14, v83
	v_fmac_f32_e32 v90, v13, v83
	v_fmac_f32_e32 v91, v13, v82
	v_fmac_f32_e32 v90, v12, v82
	v_fmac_f32_e32 v91, v12, v81
	v_fmac_f32_e32 v90, v11, v81
	v_fmac_f32_e32 v91, v11, v80
	v_fmac_f32_e32 v90, v10, v80
	v_fmac_f32_e32 v91, v10, v79
	v_fmac_f32_e32 v90, v9, v79
	v_fmac_f32_e32 v91, v9, v78
	v_fmac_f32_e32 v90, v8, v78
	v_fmac_f32_e32 v91, v8, v77
	v_fmac_f32_e32 v90, v23, v77
	v_fmac_f32_e32 v91, v23, v76
	v_fmac_f32_e32 v90, v22, v76
	v_fmac_f32_e32 v91, v22, v75
	v_fmac_f32_e32 v90, v21, v75
	v_fmac_f32_e32 v91, v21, v74
	v_fmac_f32_e32 v90, v20, v74
	v_fmac_f32_e32 v91, v20, v73
	v_fmac_f32_e32 v90, v19, v73
	v_fmac_f32_e32 v91, v19, v72
	v_fmac_f32_e32 v90, v18, v72
	v_fmac_f32_e32 v91, v18, v71
	v_fmac_f32_e32 v90, v17, v71
	v_fmac_f32_e32 v91, v17, v70
	v_fmac_f32_e32 v90, v16, v70
	v_fmac_f32_e32 v91, v16, v69
	v_fmac_f32_e32 v90, v33, v69
	v_fmac_f32_e32 v91, v33, v68
	v_fmac_f32_e32 v90, v31, v68
	v_fmac_f32_e32 v91, v31, v67
	v_fmac_f32_e32 v90, v30, v67
	v_fmac_f32_e32 v91, v30, v66
	v_fmac_f32_e32 v90, v27, v66
	v_fmac_f32_e32 v91, v27, v41
	v_fmac_f32_e32 v90, v26, v41
	v_fmac_f32_e32 v91, v26, v63
	v_fmac_f32_e32 v90, v25, v63
	v_fmac_f32_e32 v91, v25, v60
	v_fmac_f32_e32 v90, v24, v60
	v_fmac_f32_e32 v91, v24, v57
	ds_write2st64_b32 v36, v90, v91 offset0:24 offset1:32
	v_fma_f32 v90, v7, v99, v32
	v_fmac_f32_e32 v90, v6, v100
	v_fma_f32 v91, v7, v100, v32
	v_fmac_f32_e32 v90, v5, v89
	v_fmac_f32_e32 v91, v6, v89
	v_fma_f32 v89, v7, v89, v32
	v_fmac_f32_e32 v90, v4, v88
	v_fmac_f32_e32 v91, v5, v88
	v_fmac_f32_e32 v89, v6, v88
	v_fma_f32 v88, v7, v88, v32
	v_fmac_f32_e32 v90, v3, v87
	v_fmac_f32_e32 v91, v4, v87
	v_fmac_f32_e32 v89, v5, v87
; __device__ __forceinline__ void conv_item(const Params& p, int l, int item) {
;     ...
; #pragma unroll
;         for (int t = 0; t < 32; ++t) {
;             float a = bias;
; #pragma unroll
;             for (int j = 0; j < 31; ++j) a = fmaf(wj[j], win[t + j], a);
;             CV[t * 512 + c] = a;
;         }
	v_fmac_f32_e32 v88, v6, v87
	v_fma_f32 v87, v7, v87, v32
	v_fmac_f32_e32 v90, v2, v86
	v_fmac_f32_e32 v91, v3, v86
	v_fmac_f32_e32 v89, v4, v86
	v_fmac_f32_e32 v88, v5, v86
	v_fmac_f32_e32 v87, v6, v86
	v_fma_f32 v86, v7, v86, v32
	v_fmac_f32_e32 v90, v1, v85
	v_fmac_f32_e32 v91, v2, v85
	v_fmac_f32_e32 v89, v3, v85
	v_fmac_f32_e32 v88, v4, v85
	v_fmac_f32_e32 v87, v5, v85
	v_fmac_f32_e32 v86, v6, v85
	v_fma_f32 v85, v7, v85, v32
	v_fmac_f32_e32 v90, v0, v84
	v_fmac_f32_e32 v91, v1, v84
	v_fmac_f32_e32 v89, v2, v84
	v_fmac_f32_e32 v88, v3, v84
	v_fmac_f32_e32 v87, v4, v84
	v_fmac_f32_e32 v86, v5, v84
	v_fmac_f32_e32 v85, v6, v84
	v_fma_f32 v84, v7, v84, v32
	v_fmac_f32_e32 v90, v15, v83
	v_fmac_f32_e32 v91, v0, v83
	v_fmac_f32_e32 v89, v1, v83
	v_fmac_f32_e32 v88, v2, v83
	v_fmac_f32_e32 v87, v3, v83
	v_fmac_f32_e32 v86, v4, v83
	v_fmac_f32_e32 v85, v5, v83
	v_fmac_f32_e32 v84, v6, v83
	v_fma_f32 v83, v7, v83, v32
	v_fmac_f32_e32 v90, v14, v82
	v_fmac_f32_e32 v91, v15, v82
	v_fmac_f32_e32 v89, v0, v82
	v_fmac_f32_e32 v88, v1, v82
	v_fmac_f32_e32 v87, v2, v82
	v_fmac_f32_e32 v86, v3, v82
	v_fmac_f32_e32 v85, v4, v82
	v_fmac_f32_e32 v84, v5, v82
	v_fmac_f32_e32 v83, v6, v82
	v_fma_f32 v82, v7, v82, v32
	v_fmac_f32_e32 v90, v13, v81
	v_fmac_f32_e32 v91, v14, v81
	v_fmac_f32_e32 v89, v15, v81
	v_fmac_f32_e32 v88, v0, v81
	v_fmac_f32_e32 v87, v1, v81
	v_fmac_f32_e32 v86, v2, v81
	v_fmac_f32_e32 v85, v3, v81
	v_fmac_f32_e32 v84, v4, v81
	v_fmac_f32_e32 v83, v5, v81
	v_fmac_f32_e32 v82, v6, v81
	v_fma_f32 v81, v7, v81, v32
	v_fmac_f32_e32 v90, v12, v80
	v_fmac_f32_e32 v91, v13, v80
	v_fmac_f32_e32 v89, v14, v80
	v_fmac_f32_e32 v88, v15, v80
	v_fmac_f32_e32 v87, v0, v80
	v_fmac_f32_e32 v86, v1, v80
	v_fmac_f32_e32 v85, v2, v80
	v_fmac_f32_e32 v84, v3, v80
	v_fmac_f32_e32 v83, v4, v80
	v_fmac_f32_e32 v82, v5, v80
	v_fmac_f32_e32 v81, v6, v80
	v_fma_f32 v80, v7, v80, v32
	v_fmac_f32_e32 v90, v11, v79
	v_fmac_f32_e32 v91, v12, v79
	v_fmac_f32_e32 v89, v13, v79
	v_fmac_f32_e32 v88, v14, v79
	v_fmac_f32_e32 v87, v15, v79
	v_fmac_f32_e32 v86, v0, v79
	v_fmac_f32_e32 v85, v1, v79
	v_fmac_f32_e32 v84, v2, v79
	v_fmac_f32_e32 v83, v3, v79
	v_fmac_f32_e32 v82, v4, v79
	v_fmac_f32_e32 v81, v5, v79
	v_fmac_f32_e32 v80, v6, v79
	v_fma_f32 v79, v7, v79, v32
	v_fmac_f32_e32 v90, v10, v78
	v_fmac_f32_e32 v91, v11, v78
	v_fmac_f32_e32 v89, v12, v78
	v_fmac_f32_e32 v88, v13, v78
	v_fmac_f32_e32 v87, v14, v78
	v_fmac_f32_e32 v86, v15, v78
	v_fmac_f32_e32 v85, v0, v78
	v_fmac_f32_e32 v84, v1, v78
	v_fmac_f32_e32 v83, v2, v78
	v_fmac_f32_e32 v82, v3, v78
	v_fmac_f32_e32 v81, v4, v78
	v_fmac_f32_e32 v80, v5, v78
	v_fmac_f32_e32 v79, v6, v78
	v_fma_f32 v78, v7, v78, v32
	v_fmac_f32_e32 v90, v9, v77
	v_fmac_f32_e32 v91, v10, v77
	v_fmac_f32_e32 v89, v11, v77
	v_fmac_f32_e32 v88, v12, v77
	v_fmac_f32_e32 v87, v13, v77
	v_fmac_f32_e32 v86, v14, v77
	v_fmac_f32_e32 v85, v15, v77
	v_fmac_f32_e32 v84, v0, v77
	v_fmac_f32_e32 v83, v1, v77
	v_fmac_f32_e32 v82, v2, v77
	v_fmac_f32_e32 v81, v3, v77
	v_fmac_f32_e32 v80, v4, v77
	v_fmac_f32_e32 v79, v5, v77
	v_fmac_f32_e32 v78, v6, v77
	v_fma_f32 v77, v7, v77, v32
	v_fmac_f32_e32 v90, v8, v76
	v_fmac_f32_e32 v91, v9, v76
	v_fmac_f32_e32 v89, v10, v76
	v_fmac_f32_e32 v88, v11, v76
	v_fmac_f32_e32 v87, v12, v76
	v_fmac_f32_e32 v86, v13, v76
	v_fmac_f32_e32 v85, v14, v76
	v_fmac_f32_e32 v84, v15, v76
	v_fmac_f32_e32 v83, v0, v76
	v_fmac_f32_e32 v82, v1, v76
	v_fmac_f32_e32 v81, v2, v76
	v_fmac_f32_e32 v80, v3, v76
	v_fmac_f32_e32 v79, v4, v76
	v_fmac_f32_e32 v78, v5, v76
	v_fmac_f32_e32 v77, v6, v76
	v_fma_f32 v76, v7, v76, v32
	v_fmac_f32_e32 v90, v23, v75
	v_fmac_f32_e32 v91, v8, v75
	v_fmac_f32_e32 v89, v9, v75
	v_fmac_f32_e32 v88, v10, v75
	v_fmac_f32_e32 v87, v11, v75
	v_fmac_f32_e32 v86, v12, v75
	v_fmac_f32_e32 v85, v13, v75
	v_fmac_f32_e32 v84, v14, v75
	v_fmac_f32_e32 v83, v15, v75
	v_fmac_f32_e32 v82, v0, v75
	v_fmac_f32_e32 v81, v1, v75
	v_fmac_f32_e32 v80, v2, v75
	v_fmac_f32_e32 v79, v3, v75
	v_fmac_f32_e32 v78, v4, v75
	v_fmac_f32_e32 v77, v5, v75
	v_fmac_f32_e32 v76, v6, v75
	v_fma_f32 v75, v7, v75, v32
	v_fmac_f32_e32 v90, v22, v74
	v_fmac_f32_e32 v91, v23, v74
	v_fmac_f32_e32 v89, v8, v74
	v_fmac_f32_e32 v88, v9, v74
	v_fmac_f32_e32 v87, v10, v74
	v_fmac_f32_e32 v86, v11, v74
	v_fmac_f32_e32 v85, v12, v74
	v_fmac_f32_e32 v84, v13, v74
	v_fmac_f32_e32 v83, v14, v74
	v_fmac_f32_e32 v82, v15, v74
	v_fmac_f32_e32 v81, v0, v74
	v_fmac_f32_e32 v80, v1, v74
	v_fmac_f32_e32 v79, v2, v74
	v_fmac_f32_e32 v78, v3, v74
	v_fmac_f32_e32 v77, v4, v74
	v_fmac_f32_e32 v76, v5, v74
	v_fmac_f32_e32 v75, v6, v74
	v_fma_f32 v74, v7, v74, v32
	v_fmac_f32_e32 v90, v21, v73
	v_fmac_f32_e32 v91, v22, v73
	v_fmac_f32_e32 v89, v23, v73
	v_fmac_f32_e32 v88, v8, v73
	v_fmac_f32_e32 v87, v9, v73
	v_fmac_f32_e32 v86, v10, v73
	v_fmac_f32_e32 v85, v11, v73
	v_fmac_f32_e32 v84, v12, v73
	v_fmac_f32_e32 v83, v13, v73
	v_fmac_f32_e32 v82, v14, v73
	v_fmac_f32_e32 v81, v15, v73
	v_fmac_f32_e32 v80, v0, v73
	v_fmac_f32_e32 v79, v1, v73
	v_fmac_f32_e32 v78, v2, v73
	v_fmac_f32_e32 v77, v3, v73
	v_fmac_f32_e32 v76, v4, v73
	v_fmac_f32_e32 v75, v5, v73
	v_fmac_f32_e32 v74, v6, v73
	v_fma_f32 v73, v7, v73, v32
	v_fmac_f32_e32 v90, v20, v72
	v_fmac_f32_e32 v91, v21, v72
	v_fmac_f32_e32 v89, v22, v72
	v_fmac_f32_e32 v88, v23, v72
	v_fmac_f32_e32 v87, v8, v72
	v_fmac_f32_e32 v86, v9, v72
	v_fmac_f32_e32 v85, v10, v72
	v_fmac_f32_e32 v84, v11, v72
	v_fmac_f32_e32 v83, v12, v72
	v_fmac_f32_e32 v82, v13, v72
	v_fmac_f32_e32 v81, v14, v72
	v_fmac_f32_e32 v80, v15, v72
	v_fmac_f32_e32 v79, v0, v72
	v_fmac_f32_e32 v78, v1, v72
	v_fmac_f32_e32 v77, v2, v72
; __device__ __forceinline__ void conv_item(const Params& p, int l, int item) {
;     ...
; #pragma unroll
;         for (int t = 0; t < 32; ++t) {
;             float a = bias;
; #pragma unroll
;             for (int j = 0; j < 31; ++j) a = fmaf(wj[j], win[t + j], a);
;             CV[t * 512 + c] = a;
;         }
	v_fmac_f32_e32 v76, v3, v72
	v_fmac_f32_e32 v75, v4, v72
	v_fmac_f32_e32 v74, v5, v72
	v_fmac_f32_e32 v73, v6, v72
	v_fma_f32 v72, v7, v72, v32
	v_fmac_f32_e32 v90, v19, v71
	v_fmac_f32_e32 v91, v20, v71
	v_fmac_f32_e32 v89, v21, v71
	v_fmac_f32_e32 v88, v22, v71
	v_fmac_f32_e32 v87, v23, v71
	v_fmac_f32_e32 v86, v8, v71
	v_fmac_f32_e32 v85, v9, v71
	v_fmac_f32_e32 v84, v10, v71
	v_fmac_f32_e32 v83, v11, v71
	v_fmac_f32_e32 v82, v12, v71
	v_fmac_f32_e32 v81, v13, v71
	v_fmac_f32_e32 v80, v14, v71
	v_fmac_f32_e32 v79, v15, v71
	v_fmac_f32_e32 v78, v0, v71
	v_fmac_f32_e32 v77, v1, v71
	v_fmac_f32_e32 v76, v2, v71
	v_fmac_f32_e32 v75, v3, v71
	v_fmac_f32_e32 v74, v4, v71
	v_fmac_f32_e32 v73, v5, v71
	v_fmac_f32_e32 v72, v6, v71
	v_fma_f32 v71, v7, v71, v32
	v_fmac_f32_e32 v90, v18, v70
	v_fmac_f32_e32 v91, v19, v70
	v_fmac_f32_e32 v89, v20, v70
	v_fmac_f32_e32 v88, v21, v70
	v_fmac_f32_e32 v87, v22, v70
	v_fmac_f32_e32 v86, v23, v70
	v_fmac_f32_e32 v85, v8, v70
	v_fmac_f32_e32 v84, v9, v70
	v_fmac_f32_e32 v83, v10, v70
	v_fmac_f32_e32 v82, v11, v70
	v_fmac_f32_e32 v81, v12, v70
	v_fmac_f32_e32 v80, v13, v70
	v_fmac_f32_e32 v79, v14, v70
	v_fmac_f32_e32 v78, v15, v70
	v_fmac_f32_e32 v77, v0, v70
	v_fmac_f32_e32 v76, v1, v70
	v_fmac_f32_e32 v75, v2, v70
	v_fmac_f32_e32 v74, v3, v70
	v_fmac_f32_e32 v73, v4, v70
	v_fmac_f32_e32 v72, v5, v70
	v_fmac_f32_e32 v71, v6, v70
	v_fma_f32 v70, v7, v70, v32
	v_fmac_f32_e32 v90, v17, v69
	v_fmac_f32_e32 v91, v18, v69
	v_fmac_f32_e32 v89, v19, v69
	v_fmac_f32_e32 v88, v20, v69
	v_fmac_f32_e32 v87, v21, v69
	v_fmac_f32_e32 v86, v22, v69
	v_fmac_f32_e32 v85, v23, v69
	v_fmac_f32_e32 v84, v8, v69
	v_fmac_f32_e32 v83, v9, v69
	v_fmac_f32_e32 v82, v10, v69
	v_fmac_f32_e32 v81, v11, v69
	v_fmac_f32_e32 v80, v12, v69
	v_fmac_f32_e32 v79, v13, v69
	v_fmac_f32_e32 v78, v14, v69
	v_fmac_f32_e32 v77, v15, v69
	v_fmac_f32_e32 v76, v0, v69
	v_fmac_f32_e32 v75, v1, v69
	v_fmac_f32_e32 v74, v2, v69
	v_fmac_f32_e32 v73, v3, v69
	v_fmac_f32_e32 v72, v4, v69
	v_fmac_f32_e32 v71, v5, v69
	v_fmac_f32_e32 v70, v6, v69
	v_fma_f32 v69, v7, v69, v32
	v_fmac_f32_e32 v90, v16, v68
	v_fmac_f32_e32 v91, v17, v68
	v_fmac_f32_e32 v89, v18, v68
	v_fmac_f32_e32 v88, v19, v68
	v_fmac_f32_e32 v87, v20, v68
	v_fmac_f32_e32 v86, v21, v68
	v_fmac_f32_e32 v85, v22, v68
	v_fmac_f32_e32 v84, v23, v68
	v_fmac_f32_e32 v83, v8, v68
	v_fmac_f32_e32 v82, v9, v68
	v_fmac_f32_e32 v81, v10, v68
	v_fmac_f32_e32 v80, v11, v68
	v_fmac_f32_e32 v79, v12, v68
	v_fmac_f32_e32 v78, v13, v68
	v_fmac_f32_e32 v77, v14, v68
	v_fmac_f32_e32 v76, v15, v68
	v_fmac_f32_e32 v75, v0, v68
	v_fmac_f32_e32 v74, v1, v68
	v_fmac_f32_e32 v73, v2, v68
	v_fmac_f32_e32 v72, v3, v68
	v_fmac_f32_e32 v71, v4, v68
	v_fmac_f32_e32 v70, v5, v68
	v_fmac_f32_e32 v69, v6, v68
	v_fma_f32 v68, v7, v68, v32
	v_fmac_f32_e32 v90, v33, v67
	v_fmac_f32_e32 v91, v16, v67
	v_fmac_f32_e32 v89, v17, v67
	v_fmac_f32_e32 v88, v18, v67
	v_fmac_f32_e32 v87, v19, v67
	v_fmac_f32_e32 v86, v20, v67
	v_fmac_f32_e32 v85, v21, v67
	v_fmac_f32_e32 v84, v22, v67
	v_fmac_f32_e32 v83, v23, v67
	v_fmac_f32_e32 v82, v8, v67
	v_fmac_f32_e32 v81, v9, v67
	v_fmac_f32_e32 v80, v10, v67
	v_fmac_f32_e32 v79, v11, v67
	v_fmac_f32_e32 v78, v12, v67
	v_fmac_f32_e32 v77, v13, v67
	v_fmac_f32_e32 v76, v14, v67
	v_fmac_f32_e32 v75, v15, v67
	v_fmac_f32_e32 v74, v0, v67
	v_fmac_f32_e32 v73, v1, v67
	v_fmac_f32_e32 v72, v2, v67
	v_fmac_f32_e32 v71, v3, v67
	v_fmac_f32_e32 v70, v4, v67
	v_fmac_f32_e32 v69, v5, v67
	v_fmac_f32_e32 v68, v6, v67
	v_fma_f32 v67, v7, v67, v32
	v_fmac_f32_e32 v90, v31, v66
	v_fmac_f32_e32 v91, v33, v66
	v_fmac_f32_e32 v89, v16, v66
	v_fmac_f32_e32 v88, v17, v66
	v_fmac_f32_e32 v87, v18, v66
	v_fmac_f32_e32 v86, v19, v66
	v_fmac_f32_e32 v85, v20, v66
	v_fmac_f32_e32 v84, v21, v66
	v_fmac_f32_e32 v83, v22, v66
	v_fmac_f32_e32 v82, v23, v66
	v_fmac_f32_e32 v81, v8, v66
	v_fmac_f32_e32 v80, v9, v66
	v_fmac_f32_e32 v79, v10, v66
	v_fmac_f32_e32 v78, v11, v66
	v_fmac_f32_e32 v77, v12, v66
	v_fmac_f32_e32 v76, v13, v66
	v_fmac_f32_e32 v75, v14, v66
	v_fmac_f32_e32 v74, v15, v66
	v_fmac_f32_e32 v73, v0, v66
	v_fmac_f32_e32 v72, v1, v66
	v_fmac_f32_e32 v71, v2, v66
	v_fmac_f32_e32 v70, v3, v66
	v_fmac_f32_e32 v69, v4, v66
	v_fmac_f32_e32 v68, v5, v66
	v_fmac_f32_e32 v67, v6, v66
	v_fma_f32 v66, v7, v66, v32
	v_fmac_f32_e32 v32, v7, v41
	v_fmac_f32_e32 v66, v6, v41
	v_fmac_f32_e32 v32, v6, v63
	v_fmac_f32_e32 v67, v5, v41
	v_fmac_f32_e32 v66, v5, v63
	v_fmac_f32_e32 v32, v5, v60
	v_fmac_f32_e32 v68, v4, v41
	v_fmac_f32_e32 v67, v4, v63
	v_fmac_f32_e32 v66, v4, v60
	v_fmac_f32_e32 v32, v4, v57
	v_fmac_f32_e32 v69, v3, v41
	v_fmac_f32_e32 v68, v3, v63
	v_fmac_f32_e32 v67, v3, v60
	v_fmac_f32_e32 v66, v3, v57
	v_fmac_f32_e32 v32, v3, v54
	v_fmac_f32_e32 v70, v2, v41
	v_fmac_f32_e32 v69, v2, v63
	v_fmac_f32_e32 v68, v2, v60
	v_fmac_f32_e32 v67, v2, v57
	v_fmac_f32_e32 v66, v2, v54
	v_fmac_f32_e32 v32, v2, v51
	v_fmac_f32_e32 v71, v1, v41
	v_fmac_f32_e32 v70, v1, v63
	v_fmac_f32_e32 v69, v1, v60
	v_fmac_f32_e32 v68, v1, v57
	v_fmac_f32_e32 v67, v1, v54
	v_fmac_f32_e32 v66, v1, v51
	v_fmac_f32_e32 v32, v1, v48
	v_fmac_f32_e32 v72, v0, v41
	v_fmac_f32_e32 v71, v0, v63
	v_fmac_f32_e32 v70, v0, v60
	v_fmac_f32_e32 v69, v0, v57
	v_fmac_f32_e32 v68, v0, v54
	v_fmac_f32_e32 v67, v0, v51
	v_fmac_f32_e32 v66, v0, v48
	v_fmac_f32_e32 v32, v0, v45
	v_fmac_f32_e32 v73, v15, v41
	v_fmac_f32_e32 v72, v15, v63
	v_fmac_f32_e32 v71, v15, v60
	v_fmac_f32_e32 v70, v15, v57
	v_fmac_f32_e32 v69, v15, v54
	v_fmac_f32_e32 v68, v15, v51
	v_fmac_f32_e32 v67, v15, v48
	v_fmac_f32_e32 v66, v15, v45
	v_fmac_f32_e32 v32, v15, v42
; __device__ __forceinline__ void conv_item(const Params& p, int l, int item) {
;     ...
; #pragma unroll
;         for (int t = 0; t < 32; ++t) {
;             float a = bias;
; #pragma unroll
;             for (int j = 0; j < 31; ++j) a = fmaf(wj[j], win[t + j], a);
;             CV[t * 512 + c] = a;
;         }
	v_fmac_f32_e32 v74, v14, v41
	v_fmac_f32_e32 v73, v14, v63
	v_fmac_f32_e32 v72, v14, v60
	v_fmac_f32_e32 v71, v14, v57
	v_fmac_f32_e32 v70, v14, v54
	v_fmac_f32_e32 v69, v14, v51
	v_fmac_f32_e32 v68, v14, v48
	v_fmac_f32_e32 v67, v14, v45
	v_fmac_f32_e32 v66, v14, v42
	v_fmac_f32_e32 v32, v14, v64
	v_fmac_f32_e32 v75, v13, v41
	v_fmac_f32_e32 v74, v13, v63
	v_fmac_f32_e32 v73, v13, v60
	v_fmac_f32_e32 v72, v13, v57
	v_fmac_f32_e32 v71, v13, v54
	v_fmac_f32_e32 v70, v13, v51
	v_fmac_f32_e32 v69, v13, v48
	v_fmac_f32_e32 v68, v13, v45
	v_fmac_f32_e32 v67, v13, v42
	v_fmac_f32_e32 v66, v13, v64
	v_fmac_f32_e32 v32, v13, v61
	v_fmac_f32_e32 v76, v12, v41
	v_fmac_f32_e32 v75, v12, v63
	v_fmac_f32_e32 v74, v12, v60
	v_fmac_f32_e32 v73, v12, v57
	v_fmac_f32_e32 v72, v12, v54
	v_fmac_f32_e32 v71, v12, v51
	v_fmac_f32_e32 v70, v12, v48
	v_fmac_f32_e32 v69, v12, v45
	v_fmac_f32_e32 v68, v12, v42
	v_fmac_f32_e32 v67, v12, v64
	v_fmac_f32_e32 v66, v12, v61
	v_fmac_f32_e32 v32, v12, v58
	v_fmac_f32_e32 v77, v11, v41
	v_fmac_f32_e32 v76, v11, v63
	v_fmac_f32_e32 v75, v11, v60
	v_fmac_f32_e32 v74, v11, v57
	v_fmac_f32_e32 v73, v11, v54
	v_fmac_f32_e32 v72, v11, v51
	v_fmac_f32_e32 v71, v11, v48
	v_fmac_f32_e32 v70, v11, v45
	v_fmac_f32_e32 v69, v11, v42
	v_fmac_f32_e32 v68, v11, v64
	v_fmac_f32_e32 v67, v11, v61
	v_fmac_f32_e32 v66, v11, v58
	v_fmac_f32_e32 v32, v11, v55
	v_fmac_f32_e32 v78, v10, v41
	v_fmac_f32_e32 v77, v10, v63
	v_fmac_f32_e32 v76, v10, v60
	v_fmac_f32_e32 v75, v10, v57
	v_fmac_f32_e32 v74, v10, v54
	v_fmac_f32_e32 v73, v10, v51
	v_fmac_f32_e32 v72, v10, v48
	v_fmac_f32_e32 v71, v10, v45
	v_fmac_f32_e32 v70, v10, v42
	v_fmac_f32_e32 v69, v10, v64
	v_fmac_f32_e32 v68, v10, v61
	v_fmac_f32_e32 v67, v10, v58
	v_fmac_f32_e32 v66, v10, v55
	v_fmac_f32_e32 v32, v10, v52
	v_fmac_f32_e32 v79, v9, v41
	v_fmac_f32_e32 v78, v9, v63
	v_fmac_f32_e32 v77, v9, v60
	v_fmac_f32_e32 v76, v9, v57
	v_fmac_f32_e32 v75, v9, v54
	v_fmac_f32_e32 v74, v9, v51
	v_fmac_f32_e32 v73, v9, v48
	v_fmac_f32_e32 v72, v9, v45
	v_fmac_f32_e32 v71, v9, v42
	v_fmac_f32_e32 v70, v9, v64
	v_fmac_f32_e32 v69, v9, v61
	v_fmac_f32_e32 v68, v9, v58
	v_fmac_f32_e32 v67, v9, v55
	v_fmac_f32_e32 v66, v9, v52
	v_fmac_f32_e32 v32, v9, v49
	v_fmac_f32_e32 v80, v8, v41
	v_fmac_f32_e32 v79, v8, v63
	v_fmac_f32_e32 v78, v8, v60
	v_fmac_f32_e32 v77, v8, v57
	v_fmac_f32_e32 v76, v8, v54
	v_fmac_f32_e32 v75, v8, v51
	v_fmac_f32_e32 v74, v8, v48
	v_fmac_f32_e32 v73, v8, v45
	v_fmac_f32_e32 v72, v8, v42
	v_fmac_f32_e32 v71, v8, v64
	v_fmac_f32_e32 v70, v8, v61
	v_fmac_f32_e32 v69, v8, v58
	v_fmac_f32_e32 v68, v8, v55
	v_fmac_f32_e32 v67, v8, v52
	v_fmac_f32_e32 v66, v8, v49
	v_fmac_f32_e32 v32, v8, v46
	v_fmac_f32_e32 v81, v23, v41
	v_fmac_f32_e32 v80, v23, v63
	v_fmac_f32_e32 v79, v23, v60
	v_fmac_f32_e32 v78, v23, v57
	v_fmac_f32_e32 v77, v23, v54
	v_fmac_f32_e32 v76, v23, v51
	v_fmac_f32_e32 v75, v23, v48
	v_fmac_f32_e32 v74, v23, v45
	v_fmac_f32_e32 v73, v23, v42
	v_fmac_f32_e32 v72, v23, v64
	v_fmac_f32_e32 v71, v23, v61
	v_fmac_f32_e32 v70, v23, v58
	v_fmac_f32_e32 v69, v23, v55
	v_fmac_f32_e32 v68, v23, v52
	v_fmac_f32_e32 v67, v23, v49
	v_fmac_f32_e32 v66, v23, v46
	v_fmac_f32_e32 v32, v23, v43
	v_fmac_f32_e32 v82, v22, v41
	v_fmac_f32_e32 v81, v22, v63
	v_fmac_f32_e32 v80, v22, v60
	v_fmac_f32_e32 v79, v22, v57
	v_fmac_f32_e32 v78, v22, v54
	v_fmac_f32_e32 v77, v22, v51
	v_fmac_f32_e32 v76, v22, v48
	v_fmac_f32_e32 v75, v22, v45
	v_fmac_f32_e32 v74, v22, v42
	v_fmac_f32_e32 v73, v22, v64
	v_fmac_f32_e32 v72, v22, v61
	v_fmac_f32_e32 v71, v22, v58
	v_fmac_f32_e32 v70, v22, v55
	v_fmac_f32_e32 v69, v22, v52
	v_fmac_f32_e32 v68, v22, v49
	v_fmac_f32_e32 v67, v22, v46
	v_fmac_f32_e32 v66, v22, v43
	v_fmac_f32_e32 v32, v22, v65
	v_fmac_f32_e32 v83, v21, v41
	v_fmac_f32_e32 v82, v21, v63
	v_fmac_f32_e32 v81, v21, v60
	v_fmac_f32_e32 v80, v21, v57
	v_fmac_f32_e32 v79, v21, v54
	v_fmac_f32_e32 v78, v21, v51
	v_fmac_f32_e32 v77, v21, v48
	v_fmac_f32_e32 v76, v21, v45
	v_fmac_f32_e32 v75, v21, v42
	v_fmac_f32_e32 v74, v21, v64
	v_fmac_f32_e32 v73, v21, v61
	v_fmac_f32_e32 v72, v21, v58
	v_fmac_f32_e32 v71, v21, v55
	v_fmac_f32_e32 v70, v21, v52
	v_fmac_f32_e32 v69, v21, v49
	v_fmac_f32_e32 v68, v21, v46
	v_fmac_f32_e32 v67, v21, v43
	v_fmac_f32_e32 v66, v21, v65
	v_fmac_f32_e32 v32, v21, v62
	v_fmac_f32_e32 v84, v20, v41
	v_fmac_f32_e32 v83, v20, v63
	v_fmac_f32_e32 v82, v20, v60
	v_fmac_f32_e32 v81, v20, v57
	v_fmac_f32_e32 v80, v20, v54
	v_fmac_f32_e32 v79, v20, v51
	v_fmac_f32_e32 v78, v20, v48
	v_fmac_f32_e32 v77, v20, v45
	v_fmac_f32_e32 v76, v20, v42
	v_fmac_f32_e32 v75, v20, v64
	v_fmac_f32_e32 v74, v20, v61
	v_fmac_f32_e32 v73, v20, v58
	v_fmac_f32_e32 v72, v20, v55
	v_fmac_f32_e32 v71, v20, v52
	v_fmac_f32_e32 v70, v20, v49
	v_fmac_f32_e32 v69, v20, v46
	v_fmac_f32_e32 v68, v20, v43
	v_fmac_f32_e32 v67, v20, v65
	v_fmac_f32_e32 v66, v20, v62
	v_fmac_f32_e32 v32, v20, v59
	v_fmac_f32_e32 v85, v19, v41
	v_fmac_f32_e32 v84, v19, v63
	v_fmac_f32_e32 v83, v19, v60
	v_fmac_f32_e32 v82, v19, v57
	v_fmac_f32_e32 v81, v19, v54
	v_fmac_f32_e32 v80, v19, v51
	v_fmac_f32_e32 v79, v19, v48
	v_fmac_f32_e32 v78, v19, v45
	v_fmac_f32_e32 v77, v19, v42
	v_fmac_f32_e32 v76, v19, v64
	v_fmac_f32_e32 v75, v19, v61
	v_fmac_f32_e32 v74, v19, v58
	v_fmac_f32_e32 v73, v19, v55
	v_fmac_f32_e32 v72, v19, v52
	v_fmac_f32_e32 v71, v19, v49
	v_fmac_f32_e32 v70, v19, v46
	v_fmac_f32_e32 v69, v19, v43
	v_fmac_f32_e32 v68, v19, v65
	v_fmac_f32_e32 v67, v19, v62
	v_fmac_f32_e32 v66, v19, v59
	v_fmac_f32_e32 v32, v19, v56
	v_fmac_f32_e32 v86, v18, v41
	v_fmac_f32_e32 v85, v18, v63
	v_fmac_f32_e32 v84, v18, v60
; __device__ __forceinline__ void conv_item(const Params& p, int l, int item) {
;     ...
; #pragma unroll
;         for (int t = 0; t < 32; ++t) {
;             float a = bias;
; #pragma unroll
;             for (int j = 0; j < 31; ++j) a = fmaf(wj[j], win[t + j], a);
;             CV[t * 512 + c] = a;
;         }
	v_fmac_f32_e32 v83, v18, v57
	v_fmac_f32_e32 v82, v18, v54
	v_fmac_f32_e32 v81, v18, v51
	v_fmac_f32_e32 v80, v18, v48
	v_fmac_f32_e32 v79, v18, v45
	v_fmac_f32_e32 v78, v18, v42
	v_fmac_f32_e32 v77, v18, v64
	v_fmac_f32_e32 v76, v18, v61
	v_fmac_f32_e32 v75, v18, v58
	v_fmac_f32_e32 v74, v18, v55
	v_fmac_f32_e32 v73, v18, v52
	v_fmac_f32_e32 v72, v18, v49
	v_fmac_f32_e32 v71, v18, v46
	v_fmac_f32_e32 v70, v18, v43
	v_fmac_f32_e32 v69, v18, v65
	v_fmac_f32_e32 v68, v18, v62
	v_fmac_f32_e32 v67, v18, v59
	v_fmac_f32_e32 v66, v18, v56
	v_fmac_f32_e32 v32, v18, v53
	v_fmac_f32_e32 v87, v17, v41
	v_fmac_f32_e32 v86, v17, v63
	v_fmac_f32_e32 v85, v17, v60
	v_fmac_f32_e32 v84, v17, v57
	v_fmac_f32_e32 v83, v17, v54
	v_fmac_f32_e32 v82, v17, v51
	v_fmac_f32_e32 v81, v17, v48
	v_fmac_f32_e32 v80, v17, v45
	v_fmac_f32_e32 v79, v17, v42
	v_fmac_f32_e32 v78, v17, v64
	v_fmac_f32_e32 v77, v17, v61
	v_fmac_f32_e32 v76, v17, v58
	v_fmac_f32_e32 v75, v17, v55
	v_fmac_f32_e32 v74, v17, v52
	v_fmac_f32_e32 v73, v17, v49
	v_fmac_f32_e32 v72, v17, v46
	v_fmac_f32_e32 v71, v17, v43
	v_fmac_f32_e32 v70, v17, v65
	v_fmac_f32_e32 v69, v17, v62
	v_fmac_f32_e32 v68, v17, v59
	v_fmac_f32_e32 v67, v17, v56
	v_fmac_f32_e32 v66, v17, v53
	v_fmac_f32_e32 v32, v17, v50
	v_fmac_f32_e32 v88, v16, v41
	v_fmac_f32_e32 v87, v16, v63
	v_fmac_f32_e32 v86, v16, v60
	v_fmac_f32_e32 v85, v16, v57
	v_fmac_f32_e32 v84, v16, v54
	v_fmac_f32_e32 v83, v16, v51
	v_fmac_f32_e32 v82, v16, v48
	v_fmac_f32_e32 v81, v16, v45
	v_fmac_f32_e32 v80, v16, v42
	v_fmac_f32_e32 v79, v16, v64
	v_fmac_f32_e32 v78, v16, v61
	v_fmac_f32_e32 v77, v16, v58
	v_fmac_f32_e32 v76, v16, v55
	v_fmac_f32_e32 v75, v16, v52
	v_fmac_f32_e32 v74, v16, v49
	v_fmac_f32_e32 v73, v16, v46
	v_fmac_f32_e32 v72, v16, v43
	v_fmac_f32_e32 v71, v16, v65
	v_fmac_f32_e32 v70, v16, v62
	v_fmac_f32_e32 v69, v16, v59
	v_fmac_f32_e32 v68, v16, v56
	v_fmac_f32_e32 v67, v16, v53
	v_fmac_f32_e32 v66, v16, v50
	v_fmac_f32_e32 v32, v16, v47
	v_fmac_f32_e32 v89, v33, v41
	v_fmac_f32_e32 v88, v33, v63
	v_fmac_f32_e32 v87, v33, v60
	v_fmac_f32_e32 v86, v33, v57
	v_fmac_f32_e32 v85, v33, v54
	v_fmac_f32_e32 v84, v33, v51
	v_fmac_f32_e32 v83, v33, v48
	v_fmac_f32_e32 v82, v33, v45
	v_fmac_f32_e32 v81, v33, v42
	v_fmac_f32_e32 v80, v33, v64
	v_fmac_f32_e32 v79, v33, v61
	v_fmac_f32_e32 v78, v33, v58
	v_fmac_f32_e32 v77, v33, v55
	v_fmac_f32_e32 v76, v33, v52
	v_fmac_f32_e32 v75, v33, v49
	v_fmac_f32_e32 v74, v33, v46
	v_fmac_f32_e32 v73, v33, v43
	v_fmac_f32_e32 v72, v33, v65
	v_fmac_f32_e32 v71, v33, v62
	v_fmac_f32_e32 v70, v33, v59
	v_fmac_f32_e32 v69, v33, v56
	v_fmac_f32_e32 v68, v33, v53
	v_fmac_f32_e32 v67, v33, v50
	v_fmac_f32_e32 v66, v33, v47
	v_fmac_f32_e32 v32, v33, v44
	v_fmac_f32_e32 v91, v31, v41
	v_fmac_f32_e32 v89, v31, v63
	v_fmac_f32_e32 v88, v31, v60
	v_fmac_f32_e32 v87, v31, v57
	v_fmac_f32_e32 v86, v31, v54
	v_fmac_f32_e32 v85, v31, v51
	v_fmac_f32_e32 v84, v31, v48
	v_fmac_f32_e32 v83, v31, v45
	v_fmac_f32_e32 v82, v31, v42
	v_fmac_f32_e32 v81, v31, v64
	v_fmac_f32_e32 v80, v31, v61
	v_fmac_f32_e32 v79, v31, v58
	v_fmac_f32_e32 v78, v31, v55
	v_fmac_f32_e32 v77, v31, v52
	v_fmac_f32_e32 v76, v31, v49
	v_fmac_f32_e32 v75, v31, v46
	v_fmac_f32_e32 v74, v31, v43
	v_fmac_f32_e32 v73, v31, v65
	v_fmac_f32_e32 v72, v31, v62
	v_fmac_f32_e32 v71, v31, v59
	v_fmac_f32_e32 v70, v31, v56
	v_fmac_f32_e32 v69, v31, v53
	v_fmac_f32_e32 v68, v31, v50
	v_fmac_f32_e32 v67, v31, v47
	v_fmac_f32_e32 v66, v31, v44
	v_fmac_f32_e32 v32, v31, v40
	v_fmac_f32_e32 v90, v30, v41
	v_fmac_f32_e32 v91, v30, v63
	v_fmac_f32_e32 v89, v30, v60
	v_fmac_f32_e32 v88, v30, v57
	v_fmac_f32_e32 v87, v30, v54
	v_fmac_f32_e32 v86, v30, v51
	v_fmac_f32_e32 v85, v30, v48
	v_fmac_f32_e32 v84, v30, v45
	v_fmac_f32_e32 v83, v30, v42
	v_fmac_f32_e32 v82, v30, v64
	v_fmac_f32_e32 v81, v30, v61
	v_fmac_f32_e32 v80, v30, v58
	v_fmac_f32_e32 v79, v30, v55
	v_fmac_f32_e32 v78, v30, v52
	v_fmac_f32_e32 v77, v30, v49
	v_fmac_f32_e32 v76, v30, v46
	v_fmac_f32_e32 v75, v30, v43
	v_fmac_f32_e32 v74, v30, v65
	v_fmac_f32_e32 v73, v30, v62
	v_fmac_f32_e32 v72, v30, v59
	v_fmac_f32_e32 v71, v30, v56
	v_fmac_f32_e32 v70, v30, v53
	v_fmac_f32_e32 v69, v30, v50
	v_fmac_f32_e32 v68, v30, v47
	v_fmac_f32_e32 v67, v30, v44
	v_fmac_f32_e32 v66, v30, v40
	v_fmac_f32_e32 v32, v30, v39
	v_fmac_f32_e32 v90, v27, v63
	v_fmac_f32_e32 v91, v27, v60
	v_fmac_f32_e32 v89, v27, v57
	v_fmac_f32_e32 v88, v27, v54
	v_fmac_f32_e32 v87, v27, v51
	v_fmac_f32_e32 v86, v27, v48
	v_fmac_f32_e32 v85, v27, v45
	v_fmac_f32_e32 v84, v27, v42
	v_fmac_f32_e32 v83, v27, v64
	v_fmac_f32_e32 v82, v27, v61
	v_fmac_f32_e32 v81, v27, v58
	v_fmac_f32_e32 v80, v27, v55
	v_fmac_f32_e32 v79, v27, v52
	v_fmac_f32_e32 v78, v27, v49
	v_fmac_f32_e32 v77, v27, v46
	v_fmac_f32_e32 v76, v27, v43
	v_fmac_f32_e32 v75, v27, v65
	v_fmac_f32_e32 v74, v27, v62
	v_fmac_f32_e32 v73, v27, v59
	v_fmac_f32_e32 v72, v27, v56
	v_fmac_f32_e32 v71, v27, v53
	v_fmac_f32_e32 v70, v27, v50
	v_fmac_f32_e32 v69, v27, v47
	v_fmac_f32_e32 v68, v27, v44
	v_fmac_f32_e32 v67, v27, v40
	v_fmac_f32_e32 v66, v27, v39
	v_fmac_f32_e32 v32, v27, v38
	v_fmac_f32_e32 v90, v26, v60
	v_fmac_f32_e32 v91, v26, v57
	v_fmac_f32_e32 v89, v26, v54
	v_fmac_f32_e32 v88, v26, v51
	v_fmac_f32_e32 v87, v26, v48
	v_fmac_f32_e32 v86, v26, v45
	v_fmac_f32_e32 v85, v26, v42
	v_fmac_f32_e32 v84, v26, v64
	v_fmac_f32_e32 v83, v26, v61
	v_fmac_f32_e32 v82, v26, v58
	v_fmac_f32_e32 v81, v26, v55
	v_fmac_f32_e32 v80, v26, v52
	v_fmac_f32_e32 v79, v26, v49
	v_fmac_f32_e32 v78, v26, v46
	v_fmac_f32_e32 v77, v26, v43
	v_fmac_f32_e32 v76, v26, v65
	v_fmac_f32_e32 v75, v26, v62
; __device__ __forceinline__ void conv_item(const Params& p, int l, int item) {
;     ...
;         for (int t = 0; t < 32; ++t) {
;             float a = bias;
; #pragma unroll
;             for (int j = 0; j < 31; ++j) a = fmaf(wj[j], win[t + j], a);
;             CV[t * 512 + c] = a;
;         }
;     }
;     __syncthreads();
;     {
;         const int wv = tid >> 6, lane = tid & 63;
;         const float4 g0 = *reinterpret_cast<const float4*>(p.ln_g + l * 512 + lane * 8);
;         const float4 g1 = *reinterpret_cast<const float4*>(p.ln_g + l * 512 + lane * 8 + 4);
;         const float4 b0 = *reinterpret_cast<const float4*>(p.ln_b + l * 512 + lane * 8);
;         const float4 b1 = *reinterpret_cast<const float4*>(p.ln_b + l * 512 + lane * 8 + 4);
;         const float gg[8] = {g0.x, g0.y, g0.z, g0.w, g1.x, g1.y, g1.z, g1.w};
;         const float bb[8] = {b0.x, b0.y, b0.z, b0.w, b1.x, b1.y, b1.z, b1.w};
; #pragma unroll
;         for (int tt = 0; tt < 4; ++tt) {
;             const int t = wv * 4 + tt;
;             float4 v0 = *reinterpret_cast<const float4*>(CV + t * 512 + lane * 8);
;             float4 v1 = *reinterpret_cast<const float4*>(CV + t * 512 + lane * 8 + 4);
;             float v[8] = {v0.x, v0.y, v0.z, v0.w, v1.x, v1.y, v1.z, v1.w};
;             float s = 0.f, ss = 0.f;
; #pragma unroll
;             for (int i = 0; i < 8; ++i) { s += v[i]; ss += v[i] * v[i]; }
;             s = wave_sum(s); ss = wave_sum(ss);
	v_fmac_f32_e32 v74, v26, v59
	v_fmac_f32_e32 v73, v26, v56
	v_fmac_f32_e32 v72, v26, v53
	v_fmac_f32_e32 v71, v26, v50
	v_fmac_f32_e32 v70, v26, v47
	v_fmac_f32_e32 v69, v26, v44
	v_fmac_f32_e32 v68, v26, v40
	v_fmac_f32_e32 v67, v26, v39
	v_fmac_f32_e32 v66, v26, v38
	v_fmac_f32_e32 v32, v26, v37
	v_ashrrev_i32_e32 v26, 4, v29
	v_and_b32_e32 v4, -4, v26
	v_add_u32_e32 v16, s3, v4
	v_ashrrev_i32_e32 v17, 31, v16
	v_lshlrev_b64 v[0:1], 13, v[16:17]
	v_lshl_add_u64 v[0:1], s[78:79], 0, v[0:1]
	v_lshl_add_u64 v[0:1], v[0:1], 0, v[128:129]
	v_fmac_f32_e32 v90, v25, v57
	v_fmac_f32_e32 v91, v25, v54
	v_fmac_f32_e32 v89, v25, v51
	v_fmac_f32_e32 v88, v25, v48
	v_fmac_f32_e32 v87, v25, v45
	v_fmac_f32_e32 v86, v25, v42
	v_fmac_f32_e32 v85, v25, v64
	v_fmac_f32_e32 v84, v25, v61
	v_fmac_f32_e32 v83, v25, v58
	v_fmac_f32_e32 v82, v25, v55
	v_fmac_f32_e32 v81, v25, v52
	v_fmac_f32_e32 v80, v25, v49
	v_fmac_f32_e32 v79, v25, v46
	v_fmac_f32_e32 v78, v25, v43
	v_fmac_f32_e32 v77, v25, v65
	v_fmac_f32_e32 v76, v25, v62
	v_fmac_f32_e32 v75, v25, v59
	v_fmac_f32_e32 v74, v25, v56
	v_fmac_f32_e32 v73, v25, v53
	v_fmac_f32_e32 v72, v25, v50
	v_fmac_f32_e32 v71, v25, v47
	v_fmac_f32_e32 v70, v25, v44
	v_fmac_f32_e32 v69, v25, v40
	v_fmac_f32_e32 v68, v25, v39
	v_fmac_f32_e32 v67, v25, v38
	v_fmac_f32_e32 v66, v25, v37
	v_fmac_f32_e32 v32, v25, v35
	v_add_co_u32_e32 v2, vcc, s0, v0
	v_fmac_f32_e32 v90, v24, v54
	v_fmac_f32_e32 v91, v24, v51
	v_fmac_f32_e32 v89, v24, v48
	v_fmac_f32_e32 v88, v24, v45
	v_fmac_f32_e32 v87, v24, v42
	v_fmac_f32_e32 v86, v24, v64
	v_fmac_f32_e32 v85, v24, v61
	v_fmac_f32_e32 v84, v24, v58
	v_fmac_f32_e32 v83, v24, v55
	v_fmac_f32_e32 v82, v24, v52
	v_fmac_f32_e32 v81, v24, v49
	v_fmac_f32_e32 v80, v24, v46
	v_fmac_f32_e32 v79, v24, v43
	v_fmac_f32_e32 v78, v24, v65
	v_fmac_f32_e32 v77, v24, v62
	v_fmac_f32_e32 v76, v24, v59
	v_fmac_f32_e32 v75, v24, v56
	v_fmac_f32_e32 v74, v24, v53
	v_fmac_f32_e32 v73, v24, v50
	v_fmac_f32_e32 v72, v24, v47
	v_fmac_f32_e32 v71, v24, v44
	v_fmac_f32_e32 v70, v24, v40
	v_fmac_f32_e32 v69, v24, v39
	v_fmac_f32_e32 v68, v24, v38
	v_fmac_f32_e32 v67, v24, v37
	v_fmac_f32_e32 v66, v24, v35
	v_fmac_f32_e32 v32, v24, v34
	v_addc_co_u32_e32 v3, vcc, 0, v1, vcc
	ds_write2st64_b32 v36, v90, v91 offset0:40 offset1:48
	ds_write2st64_b32 v36, v89, v88 offset0:56 offset1:64
	ds_write2st64_b32 v36, v87, v86 offset0:72 offset1:80
	ds_write2st64_b32 v36, v85, v84 offset0:88 offset1:96
	ds_write2st64_b32 v36, v83, v82 offset0:104 offset1:112
	ds_write2st64_b32 v36, v81, v80 offset0:120 offset1:128
	ds_write2st64_b32 v36, v79, v78 offset0:136 offset1:144
	ds_write2st64_b32 v36, v77, v76 offset0:152 offset1:160
	ds_write2st64_b32 v36, v75, v74 offset0:168 offset1:176
	ds_write2st64_b32 v36, v73, v72 offset0:184 offset1:192
	ds_write2st64_b32 v36, v71, v70 offset0:200 offset1:208
	ds_write2st64_b32 v36, v69, v68 offset0:216 offset1:224
	ds_write2st64_b32 v36, v67, v66 offset0:232 offset1:240
	ds_write_b32 v36, v32 offset:63488
	s_waitcnt lgkmcnt(0)
	s_barrier
	s_waitcnt vmcnt(0)
	v_mov_b32_e32 v30, v140
	v_mov_b32_e32 v31, v141
	v_mov_b32_e32 v32, v142
	v_mov_b32_e32 v33, v143
	v_and_b32_e32 v2, 64, v213
	v_add_u32_e32 v2, 64, v2
	v_xor_b32_e32 v3, 32, v213
	v_cmp_lt_i32_e32 vcc, v3, v2
	v_lshlrev_b32_e32 v12, 2, v28
	v_add_u32_e32 v27, 0, v12
	v_cndmask_b32_e32 v3, v213, v3, vcc
	v_lshlrev_b32_e32 v25, 2, v3
	v_xor_b32_e32 v3, 16, v213
	v_cmp_lt_i32_e32 vcc, v3, v2
	v_lshl_add_u32 v17, v4, 11, v27
	v_lshl_add_u64 v[18:19], v[0:1], 0, s[10:11]
	v_cndmask_b32_e32 v3, v213, v3, vcc
	v_lshlrev_b32_e32 v24, 2, v3
	v_xor_b32_e32 v3, 8, v213
	v_cmp_lt_i32_e32 vcc, v3, v2
	ds_read_b128 v[34:37], v17 offset:63488
	ds_read_b128 v[38:41], v17 offset:63504
	v_cndmask_b32_e32 v3, v213, v3, vcc
	v_lshlrev_b32_e32 v23, 2, v3
	v_xor_b32_e32 v3, 4, v213
	v_cmp_lt_i32_e32 vcc, v3, v2
	v_mov_b32_e32 v50, v129
	s_waitcnt lgkmcnt(1)
	v_mov_b32_e32 v51, v35
	v_cndmask_b32_e32 v3, v213, v3, vcc
	v_lshlrev_b32_e32 v22, 2, v3
	v_xor_b32_e32 v3, 2, v213
	v_cmp_lt_i32_e32 vcc, v3, v2
	v_pk_mul_f32 v[48:49], v[34:35], v[34:35]
	v_pk_add_f32 v[50:51], v[34:35], v[50:51]
	v_cndmask_b32_e32 v3, v213, v3, vcc
	v_lshlrev_b32_e32 v21, 2, v3
	v_xor_b32_e32 v3, 1, v213
	v_cmp_lt_i32_e32 vcc, v3, v2
	v_pk_mov_b32 v[50:51], v[48:49], v[50:51] op_sel:[1,0]
	v_mov_b32_e32 v49, v35
	v_cndmask_b32_e32 v2, v213, v3, vcc
	v_lshlrev_b32_e32 v20, 2, v2
	global_load_dwordx4 v[0:3], v12, s[4:5] offset:16
	global_load_dwordx4 v[8:11], v12, s[4:5]
	global_load_dwordx4 v[4:7], v12, s[6:7] offset:16
	s_nop 0
	global_load_dwordx4 v[12:15], v12, s[6:7]
	v_pk_add_f32 v[48:49], v[50:51], v[48:49]
	v_mov_b32_e32 v51, v36
	s_waitcnt lgkmcnt(0)
	v_pk_mul_f32 v[44:45], v[38:39], v[38:39]
	v_pk_mul_f32 v[28:29], v[40:41], v[40:41]
	v_or_b32_e32 v26, 3, v26
	s_waitcnt vmcnt(4)
	v_lshlrev_b32_e32 v46, 16, v32
	v_and_b32_e32 v47, 0xffff0000, v32
	v_mul_f32_e32 v32, 0xbfb8aa3b, v46
	v_lshlrev_b32_e32 v42, 16, v33
	v_and_b32_e32 v43, 0xffff0000, v33
	v_exp_f32_e32 v52, v32
	v_pk_mul_f32 v[32:33], v[36:37], v[36:37]
	s_nop 0
	v_mov_b32_e32 v50, v32
	v_pk_add_f32 v[48:49], v[48:49], v[50:51]
	v_mov_b32_e32 v32, v33
	v_mov_b32_e32 v33, v37
	v_pk_add_f32 v[32:33], v[48:49], v[32:33]
	v_mov_b32_e32 v48, v44
	v_mov_b32_e32 v49, v38
	v_pk_add_f32 v[32:33], v[32:33], v[48:49]
	v_mov_b32_e32 v44, v45
	v_mov_b32_e32 v45, v39
	v_pk_add_f32 v[32:33], v[32:33], v[44:45]
	v_mov_b32_e32 v44, v28
	v_mov_b32_e32 v45, v40
	v_pk_add_f32 v[32:33], v[32:33], v[44:45]
	v_mov_b32_e32 v28, v29
	v_mov_b32_e32 v29, v41
	v_pk_add_f32 v[28:29], v[32:33], v[28:29]
	ds_bpermute_b32 v33, v25, v29
	ds_bpermute_b32 v32, v25, v28
	v_lshlrev_b32_e32 v48, 16, v31
	v_and_b32_e32 v49, 0xffff0000, v31
	v_mul_f32_e32 v31, 0xbfb8aa3b, v48
	v_mul_f32_e32 v45, 0xbfb8aa3b, v47
	s_waitcnt lgkmcnt(0)
; __device__ __forceinline__ float sigmoidf_(float x) { return __builtin_amdgcn_rcpf(1.0f + __expf(-x)); }
; __device__ __forceinline__ float siluf_(float x) { return x * sigmoidf_(x); }
; __device__ __forceinline__ float wave_sum(float v) {
; #pragma unroll
;     for (int o = 32; o >= 1; o >>= 1) v += __shfl_xor(v, o);
;     return v;
; }
; __device__ __forceinline__ void conv_item(const Params& p, int l, int item) {
;     ...
; #pragma unroll
;             for (int i = 0; i < 8; ++i) { s += v[i]; ss += v[i] * v[i]; }
;             s = wave_sum(s); ss = wave_sum(ss);
;             const float mean = s * (1.0f / 512.f);
;             const float var = fmaxf(ss * (1.0f / 512.f) - mean * mean, 0.f);
;             const float rstd = rsqrtf(var + 1e-5f);
;             bf16_t* gp = P1 + (long)(R0 + t) * P1W + 2048 + lane * 8;
;             uint4 gv = ld_nt_u4(gp);
;             const float gt[8] = {bflo(gv.x), bfhi(gv.x), bflo(gv.y), bfhi(gv.y), bflo(gv.z), bfhi(gv.z), bflo(gv.w), bfhi(gv.w)};
;             float y[8];
; #pragma unroll
;             for (int i = 0; i < 8; ++i) {
;                 float u = (v[i] - mean) * rstd * gg[i] + bb[i];
;                 y[i] = u * sigmoidf_(u) * siluf_(gt[i]);
;             }
;             uint4 o; o.x = pk2(y[0], y[1]); o.y = pk2(y[2], y[3]); o.z = pk2(y[4], y[5]); o.w = pk2(y[6], y[7]);
;             st16_wt(gp, o);
	v_pk_add_f32 v[28:29], v[28:29], v[32:33]
	ds_bpermute_b32 v33, v24, v29
	ds_bpermute_b32 v32, v24, v28
	v_exp_f32_e32 v31, v31
	v_mul_f32_e32 v50, 0xbfb8aa3b, v49
	v_exp_f32_e32 v45, v45
	v_exp_f32_e32 v51, v50
	s_waitcnt lgkmcnt(0)
	v_pk_add_f32 v[28:29], v[28:29], v[32:33]
	s_nop 1
	v_mov_b32_dpp v33, v29 row_ror:8 row_mask:0xf bank_mask:0xf
	v_mov_b32_dpp v32, v28 row_ror:8 row_mask:0xf bank_mask:0xf
	v_add_f32_e32 v31, 1.0, v31
	v_add_f32_e32 v44, 1.0, v52
	v_add_f32_e32 v45, 1.0, v45
	v_rcp_f32_e32 v50, v31
	s_waitcnt lgkmcnt(0)
	v_pk_add_f32 v[28:29], v[28:29], v[32:33]
	s_nop 1
	v_mov_b32_dpp v33, v29 row_ror:4 row_mask:0xf bank_mask:0xf
	v_mov_b32_dpp v32, v28 row_ror:4 row_mask:0xf bank_mask:0xf
	v_add_f32_e32 v31, 1.0, v51
	v_rcp_f32_e32 v44, v44
	v_rcp_f32_e32 v45, v45
	v_rcp_f32_e32 v51, v31
	s_waitcnt lgkmcnt(0)
	v_pk_add_f32 v[28:29], v[28:29], v[32:33]
	s_nop 1
	v_mov_b32_dpp v33, v29 row_ror:2 row_mask:0xf bank_mask:0xf
	v_mov_b32_dpp v32, v28 row_ror:2 row_mask:0xf bank_mask:0xf
	v_pk_mul_f32 v[44:45], v[44:45], v[46:47]
	v_pk_mul_f32 v[46:47], v[50:51], v[48:49]
	v_lshlrev_b32_e32 v48, 16, v30
	v_and_b32_e32 v49, 0xffff0000, v30
	s_waitcnt lgkmcnt(0)
	v_pk_add_f32 v[28:29], v[28:29], v[32:33]
	s_nop 1
	v_mov_b32_dpp v31, v29 row_ror:1 row_mask:0xf bank_mask:0xf
	v_mov_b32_dpp v30, v28 row_ror:1 row_mask:0xf bank_mask:0xf
	v_mul_f32_e32 v32, 0xbfb8aa3b, v48
	v_exp_f32_e32 v32, v32
	v_mul_f32_e32 v33, 0xbfb8aa3b, v49
	v_exp_f32_e32 v33, v33
	s_waitcnt lgkmcnt(0)
	v_pk_add_f32 v[28:29], v[28:29], v[30:31]
	v_add_f32_e32 v33, 1.0, v33
	v_pk_mul_f32 v[28:29], v[28:29], s[12:13] op_sel_hi:[1,0]
	s_nop 0
	v_fma_f32 v30, -v29, v29, v28
	v_max_f32_e32 v30, 0, v30
	v_add_f32_e32 v30, 0x3727c5ac, v30
	v_mul_f32_e32 v31, 0x4b800000, v30
	v_cmp_gt_f32_e32 vcc, s94, v30
	v_pk_add_f32 v[34:35], v[34:35], v[28:29] op_sel:[0,1] neg_lo:[0,1] neg_hi:[0,1]
	v_pk_add_f32 v[36:37], v[36:37], v[28:29] op_sel:[0,1] neg_lo:[0,1] neg_hi:[0,1]
	v_cndmask_b32_e32 v30, v30, v31, vcc
	v_rsq_f32_e32 v31, v30
	v_add_f32_e32 v30, 1.0, v32
	v_rcp_f32_e32 v30, v30
	v_mul_f32_e32 v32, 0x45800000, v31
	v_cndmask_b32_e32 v32, v31, v32, vcc
	v_pk_mul_f32 v[34:35], v[34:35], v[32:33] op_sel_hi:[1,0]
	s_waitcnt vmcnt(0)
	v_pk_fma_f32 v[34:35], v[8:9], v[34:35], v[12:13]
	s_nop 0
	v_mul_f32_e32 v31, 0xbfb8aa3b, v34
	v_exp_f32_e32 v50, v31
	v_mul_f32_e32 v31, 0xbfb8aa3b, v35
	v_exp_f32_e32 v51, v31
	v_rcp_f32_e32 v31, v33
	v_add_f32_e32 v33, 1.0, v50
	v_rcp_f32_e32 v50, v33
	v_add_f32_e32 v33, 1.0, v51
	v_pk_mul_f32 v[36:37], v[36:37], v[32:33] op_sel_hi:[1,0]
	v_pk_mul_f32 v[30:31], v[30:31], v[48:49]
	v_pk_fma_f32 v[36:37], v[10:11], v[36:37], v[14:15]
	s_nop 0
	v_mul_f32_e32 v51, 0xbfb8aa3b, v36
	v_exp_f32_e32 v52, v51
	v_mul_f32_e32 v51, 0xbfb8aa3b, v37
	v_exp_f32_e32 v53, v51
	v_rcp_f32_e32 v51, v33
	v_add_f32_e32 v33, 1.0, v52
	v_rcp_f32_e32 v52, v33
	v_add_f32_e32 v33, 1.0, v53
	v_rcp_f32_e32 v53, v33
	v_pk_mul_f32 v[34:35], v[34:35], v[50:51]
	v_mov_b32_e32 v50, v129
	v_pk_mul_f32 v[30:31], v[30:31], v[34:35]
	v_pk_mul_f32 v[34:35], v[36:37], v[52:53]
	v_pk_add_f32 v[36:37], v[38:39], v[28:29] op_sel:[0,1] neg_lo:[0,1] neg_hi:[0,1]
	v_pk_add_f32 v[28:29], v[40:41], v[28:29] op_sel:[0,1] neg_lo:[0,1] neg_hi:[0,1]
	v_pk_mul_f32 v[36:37], v[36:37], v[32:33] op_sel_hi:[1,0]
	v_pk_mul_f32 v[34:35], v[46:47], v[34:35]
	v_pk_fma_f32 v[36:37], v[0:1], v[36:37], v[4:5]
	s_nop 0
	v_mul_f32_e32 v33, 0xbfb8aa3b, v36
	v_exp_f32_e32 v33, v33
	v_mul_f32_e32 v38, 0xbfb8aa3b, v37
	v_exp_f32_e32 v39, v38
	v_add_f32_e32 v33, 1.0, v33
	v_rcp_f32_e32 v38, v33
	v_add_f32_e32 v33, 1.0, v39
	v_mul_f32_e32 v39, 0xbfb8aa3b, v42
	v_exp_f32_e32 v40, v39
	v_pk_mul_f32 v[28:29], v[28:29], v[32:33] op_sel_hi:[1,0]
	v_rcp_f32_e32 v39, v33
	v_pk_fma_f32 v[28:29], v[2:3], v[28:29], v[6:7]
	v_add_f32_e32 v33, 1.0, v40
	v_mul_f32_e32 v40, 0xbfb8aa3b, v29
	v_mul_f32_e32 v32, 0xbfb8aa3b, v28
	v_exp_f32_e32 v41, v40
	v_mul_f32_e32 v40, 0xbfb8aa3b, v43
	v_exp_f32_e32 v32, v32
	v_exp_f32_e32 v46, v40
	v_rcp_f32_e32 v40, v33
	v_add_f32_e32 v33, 1.0, v41
	v_add_f32_e32 v32, 1.0, v32
	v_add_f32_e32 v41, 1.0, v46
	v_rcp_f32_e32 v32, v32
	v_rcp_f32_e32 v33, v33
	v_rcp_f32_e32 v41, v41
	v_pk_mul_f32 v[36:37], v[36:37], v[38:39]
	v_pk_mul_f32 v[28:29], v[28:29], v[32:33]
	v_pk_mul_f32 v[32:33], v[40:41], v[42:43]
	v_pk_mul_f32 v[36:37], v[44:45], v[36:37]
	v_pk_mul_f32 v[32:33], v[32:33], v[28:29]
	v_cvt_pk_bf16_f32 v28, v30, v31
	v_cvt_pk_bf16_f32 v29, v34, v35
	v_cvt_pk_bf16_f32 v30, v36, v37
	v_cvt_pk_bf16_f32 v31, v32, v33
	global_store_dwordx4 v[18:19], v[28:31], off sc1
	s_nop 1
	v_add_u32_e32 v18, 1, v16
	v_ashrrev_i32_e32 v19, 31, v18
	v_lshlrev_b64 v[18:19], 13, v[18:19]
	v_lshl_add_u64 v[18:19], s[78:79], 0, v[18:19]
	v_lshl_add_u64 v[18:19], v[18:19], 0, v[128:129]
	v_add_co_u32_e32 v28, vcc, s0, v18
	v_add_u32_e32 v36, 0x800, v17
	s_nop 0
	v_addc_co_u32_e32 v29, vcc, 0, v19, vcc
	v_mov_b32_e32 v28, v144
	v_mov_b32_e32 v29, v145
	v_mov_b32_e32 v30, v146
	v_mov_b32_e32 v31, v147
	ds_read_b128 v[32:35], v36 offset:63504
	ds_read_b128 v[36:39], v36 offset:63488
	v_lshl_add_u64 v[18:19], v[18:19], 0, s[10:11]
	s_waitcnt lgkmcnt(1)
	v_pk_mul_f32 v[44:45], v[32:33], v[32:33]
	s_waitcnt lgkmcnt(0)
; __device__ __forceinline__ float sigmoidf_(float x) { return __builtin_amdgcn_rcpf(1.0f + __expf(-x)); }
; __device__ __forceinline__ float siluf_(float x) { return x * sigmoidf_(x); }
; __device__ __forceinline__ void conv_item(const Params& p, int l, int item) {
;     ...
;         for (int tt = 0; tt < 4; ++tt) {
;             const int t = wv * 4 + tt;
;             float4 v0 = *reinterpret_cast<const float4*>(CV + t * 512 + lane * 8);
;             float4 v1 = *reinterpret_cast<const float4*>(CV + t * 512 + lane * 8 + 4);
;             float v[8] = {v0.x, v0.y, v0.z, v0.w, v1.x, v1.y, v1.z, v1.w};
;             float s = 0.f, ss = 0.f;
; #pragma unroll
;             for (int i = 0; i < 8; ++i) { s += v[i]; ss += v[i] * v[i]; }
;             s = wave_sum(s); ss = wave_sum(ss);
;             const float mean = s * (1.0f / 512.f);
;             const float var = fmaxf(ss * (1.0f / 512.f) - mean * mean, 0.f);
;             const float rstd = rsqrtf(var + 1e-5f);
;             bf16_t* gp = P1 + (long)(R0 + t) * P1W + 2048 + lane * 8;
;             uint4 gv = ld_nt_u4(gp);
;             const float gt[8] = {bflo(gv.x), bfhi(gv.x), bflo(gv.y), bfhi(gv.y), bflo(gv.z), bfhi(gv.z), bflo(gv.w), bfhi(gv.w)};
;             float y[8];
; #pragma unroll
;             for (int i = 0; i < 8; ++i) {
;                 float u = (v[i] - mean) * rstd * gg[i] + bb[i];
;                 y[i] = u * sigmoidf_(u) * siluf_(gt[i]);
;             }
;             uint4 o; o.x = pk2(y[0], y[1]); o.y = pk2(y[2], y[3]); o.z = pk2(y[4], y[5]); o.w = pk2(y[6], y[7]);
;             st16_wt(gp, o);
;         }
	v_mov_b32_e32 v51, v37
	v_pk_mul_f32 v[48:49], v[36:37], v[36:37]
	v_pk_add_f32 v[50:51], v[36:37], v[50:51]
	v_pk_mul_f32 v[40:41], v[34:35], v[34:35]
	v_pk_mov_b32 v[50:51], v[48:49], v[50:51] op_sel:[1,0]
	v_mov_b32_e32 v49, v37
	v_pk_add_f32 v[48:49], v[50:51], v[48:49]
	v_mov_b32_e32 v51, v38
	v_lshlrev_b32_e32 v46, 16, v30
	v_and_b32_e32 v47, 0xffff0000, v30
	v_mul_f32_e32 v30, 0xbfb8aa3b, v46
	v_lshlrev_b32_e32 v42, 16, v31
	v_and_b32_e32 v43, 0xffff0000, v31
	v_exp_f32_e32 v52, v30
	v_pk_mul_f32 v[30:31], v[38:39], v[38:39]
	s_nop 0
	v_mov_b32_e32 v50, v30
	v_pk_add_f32 v[48:49], v[48:49], v[50:51]
	v_mov_b32_e32 v30, v31
	v_mov_b32_e32 v31, v39
	v_pk_add_f32 v[30:31], v[48:49], v[30:31]
	v_mov_b32_e32 v48, v44
	v_mov_b32_e32 v49, v32
	v_pk_add_f32 v[30:31], v[30:31], v[48:49]
	v_mov_b32_e32 v44, v45
	v_mov_b32_e32 v45, v33
	v_pk_add_f32 v[30:31], v[30:31], v[44:45]
	v_mov_b32_e32 v44, v40
	v_mov_b32_e32 v45, v34
	v_pk_add_f32 v[30:31], v[30:31], v[44:45]
	v_mov_b32_e32 v40, v41
	v_mov_b32_e32 v41, v35
	v_pk_add_f32 v[30:31], v[30:31], v[40:41]
	ds_bpermute_b32 v41, v25, v31
	ds_bpermute_b32 v40, v25, v30
	v_lshlrev_b32_e32 v48, 16, v29
	v_and_b32_e32 v49, 0xffff0000, v29
	v_mul_f32_e32 v29, 0xbfb8aa3b, v48
	v_mul_f32_e32 v45, 0xbfb8aa3b, v47
	s_waitcnt lgkmcnt(0)
	v_pk_add_f32 v[30:31], v[30:31], v[40:41]
	ds_bpermute_b32 v41, v24, v31
	ds_bpermute_b32 v40, v24, v30
	v_exp_f32_e32 v29, v29
	v_mul_f32_e32 v50, 0xbfb8aa3b, v49
	v_exp_f32_e32 v45, v45
	v_exp_f32_e32 v51, v50
	s_waitcnt lgkmcnt(0)
	v_pk_add_f32 v[30:31], v[30:31], v[40:41]
	s_nop 1
	v_mov_b32_dpp v41, v31 row_ror:8 row_mask:0xf bank_mask:0xf
	v_mov_b32_dpp v40, v30 row_ror:8 row_mask:0xf bank_mask:0xf
	v_add_f32_e32 v29, 1.0, v29
	v_add_f32_e32 v44, 1.0, v52
	v_add_f32_e32 v45, 1.0, v45
	v_rcp_f32_e32 v50, v29
	s_waitcnt lgkmcnt(0)
	v_pk_add_f32 v[30:31], v[30:31], v[40:41]
	s_nop 1
	v_mov_b32_dpp v41, v31 row_ror:4 row_mask:0xf bank_mask:0xf
	v_mov_b32_dpp v40, v30 row_ror:4 row_mask:0xf bank_mask:0xf
	v_add_f32_e32 v29, 1.0, v51
	v_rcp_f32_e32 v44, v44
	v_rcp_f32_e32 v45, v45
	v_rcp_f32_e32 v51, v29
	s_waitcnt lgkmcnt(0)
	v_pk_add_f32 v[30:31], v[30:31], v[40:41]
	s_nop 1
	v_mov_b32_dpp v41, v31 row_ror:2 row_mask:0xf bank_mask:0xf
	v_mov_b32_dpp v40, v30 row_ror:2 row_mask:0xf bank_mask:0xf
	v_pk_mul_f32 v[44:45], v[44:45], v[46:47]
	v_pk_mul_f32 v[46:47], v[50:51], v[48:49]
	v_lshlrev_b32_e32 v48, 16, v28
	v_and_b32_e32 v49, 0xffff0000, v28
	s_waitcnt lgkmcnt(0)
	v_pk_add_f32 v[28:29], v[30:31], v[40:41]
	s_nop 1
	v_mov_b32_dpp v31, v29 row_ror:1 row_mask:0xf bank_mask:0xf
	v_mov_b32_dpp v30, v28 row_ror:1 row_mask:0xf bank_mask:0xf
	v_mul_f32_e32 v40, 0xbfb8aa3b, v48
	v_exp_f32_e32 v40, v40
	v_mul_f32_e32 v41, 0xbfb8aa3b, v49
	v_exp_f32_e32 v41, v41
	s_waitcnt lgkmcnt(0)
	v_pk_add_f32 v[28:29], v[28:29], v[30:31]
	v_add_f32_e32 v41, 1.0, v41
	v_pk_mul_f32 v[28:29], v[28:29], s[12:13] op_sel_hi:[1,0]
	s_nop 0
	v_fma_f32 v30, -v29, v29, v28
	v_max_f32_e32 v30, 0, v30
	v_add_f32_e32 v30, 0x3727c5ac, v30
	v_mul_f32_e32 v31, 0x4b800000, v30
	v_cmp_gt_f32_e32 vcc, s94, v30
	v_pk_add_f32 v[36:37], v[36:37], v[28:29] op_sel:[0,1] neg_lo:[0,1] neg_hi:[0,1]
	v_pk_add_f32 v[38:39], v[38:39], v[28:29] op_sel:[0,1] neg_lo:[0,1] neg_hi:[0,1]
	v_cndmask_b32_e32 v30, v30, v31, vcc
	v_rsq_f32_e32 v31, v30
	v_add_f32_e32 v30, 1.0, v40
	v_rcp_f32_e32 v30, v30
	v_pk_add_f32 v[32:33], v[32:33], v[28:29] op_sel:[0,1] neg_lo:[0,1] neg_hi:[0,1]
	v_mul_f32_e32 v40, 0x45800000, v31
	v_cndmask_b32_e32 v40, v31, v40, vcc
	v_pk_mul_f32 v[36:37], v[36:37], v[40:41] op_sel_hi:[1,0]
	v_pk_add_f32 v[28:29], v[34:35], v[28:29] op_sel:[0,1] neg_lo:[0,1] neg_hi:[0,1]
	v_pk_fma_f32 v[36:37], v[8:9], v[36:37], v[12:13]
	v_mul_f32_e32 v35, 0xbfb8aa3b, v42
	v_mul_f32_e32 v31, 0xbfb8aa3b, v36
	v_exp_f32_e32 v50, v31
	v_mul_f32_e32 v31, 0xbfb8aa3b, v37
	v_exp_f32_e32 v51, v31
	v_rcp_f32_e32 v31, v41
	v_add_f32_e32 v41, 1.0, v50
	v_rcp_f32_e32 v50, v41
	v_add_f32_e32 v41, 1.0, v51
	v_pk_mul_f32 v[38:39], v[38:39], v[40:41] op_sel_hi:[1,0]
	v_pk_mul_f32 v[30:31], v[30:31], v[48:49]
	v_pk_fma_f32 v[38:39], v[10:11], v[38:39], v[14:15]
	v_exp_f32_e32 v35, v35
	v_mul_f32_e32 v51, 0xbfb8aa3b, v38
	v_exp_f32_e32 v52, v51
	v_mul_f32_e32 v51, 0xbfb8aa3b, v39
	v_exp_f32_e32 v53, v51
	v_rcp_f32_e32 v51, v41
	v_add_f32_e32 v41, 1.0, v52
	v_rcp_f32_e32 v52, v41
	v_add_f32_e32 v41, 1.0, v53
	v_rcp_f32_e32 v53, v41
	v_pk_mul_f32 v[28:29], v[28:29], v[40:41] op_sel_hi:[1,0]
	v_pk_mul_f32 v[32:33], v[32:33], v[40:41] op_sel_hi:[1,0]
	v_pk_fma_f32 v[28:29], v[2:3], v[28:29], v[6:7]
	v_pk_mul_f32 v[36:37], v[36:37], v[50:51]
	v_pk_fma_f32 v[32:33], v[0:1], v[32:33], v[4:5]
	v_mul_f32_e32 v40, 0xbfb8aa3b, v29
	v_pk_mul_f32 v[30:31], v[30:31], v[36:37]
	v_pk_mul_f32 v[36:37], v[38:39], v[52:53]
	v_mul_f32_e32 v38, 0xbfb8aa3b, v32
	v_mul_f32_e32 v39, 0xbfb8aa3b, v33
	v_mul_f32_e32 v34, 0xbfb8aa3b, v28
	v_exp_f32_e32 v41, v40
	v_mul_f32_e32 v40, 0xbfb8aa3b, v43
	v_exp_f32_e32 v38, v38
	v_exp_f32_e32 v39, v39
	v_pk_mul_f32 v[36:37], v[46:47], v[36:37]
	v_exp_f32_e32 v34, v34
	v_exp_f32_e32 v46, v40
	v_add_f32_e32 v35, 1.0, v35
	v_add_f32_e32 v38, 1.0, v38
	v_add_f32_e32 v39, 1.0, v39
	v_add_f32_e32 v34, 1.0, v34
	v_rcp_f32_e32 v40, v35
	v_add_f32_e32 v35, 1.0, v41
	v_add_f32_e32 v41, 1.0, v46
	v_rcp_f32_e32 v38, v38
	v_rcp_f32_e32 v39, v39
	v_rcp_f32_e32 v34, v34
	v_rcp_f32_e32 v35, v35
	v_rcp_f32_e32 v41, v41
	v_pk_mul_f32 v[32:33], v[32:33], v[38:39]
	v_mov_b32_e32 v48, v129
	v_pk_mul_f32 v[28:29], v[28:29], v[34:35]
	v_pk_mul_f32 v[34:35], v[40:41], v[42:43]
	v_pk_mul_f32 v[32:33], v[44:45], v[32:33]
	v_pk_mul_f32 v[34:35], v[34:35], v[28:29]
	v_cvt_pk_bf16_f32 v28, v30, v31
	v_cvt_pk_bf16_f32 v29, v36, v37
	v_cvt_pk_bf16_f32 v30, v32, v33
	v_cvt_pk_bf16_f32 v31, v34, v35
	global_store_dwordx4 v[18:19], v[28:31], off sc1
	s_nop 1
	v_add_u32_e32 v18, 2, v16
	v_ashrrev_i32_e32 v19, 31, v18
	v_lshlrev_b64 v[18:19], 13, v[18:19]
	v_lshl_add_u64 v[18:19], s[78:79], 0, v[18:19]
	v_lshl_add_u64 v[18:19], v[18:19], 0, v[128:129]
	v_add_co_u32_e32 v28, vcc, s0, v18
	v_add_u32_e32 v16, 0x1000, v17
	s_nop 0
	v_addc_co_u32_e32 v29, vcc, 0, v19, vcc
	v_mov_b32_e32 v28, v148
	v_mov_b32_e32 v29, v149
	v_mov_b32_e32 v30, v150
	v_mov_b32_e32 v31, v151
	ds_read_b128 v[32:35], v16 offset:63504
	ds_read_b128 v[36:39], v16 offset:63488
	v_lshl_add_u64 v[16:17], v[18:19], 0, s[10:11]
	s_waitcnt lgkmcnt(1)
; __device__ __forceinline__ float sigmoidf_(float x) { return __builtin_amdgcn_rcpf(1.0f + __expf(-x)); }
; __device__ __forceinline__ float siluf_(float x) { return x * sigmoidf_(x); }
; __device__ __forceinline__ void conv_item(const Params& p, int l, int item) {
;     ...
;         for (int tt = 0; tt < 4; ++tt) {
;             const int t = wv * 4 + tt;
;             float4 v0 = *reinterpret_cast<const float4*>(CV + t * 512 + lane * 8);
;             float4 v1 = *reinterpret_cast<const float4*>(CV + t * 512 + lane * 8 + 4);
;             float v[8] = {v0.x, v0.y, v0.z, v0.w, v1.x, v1.y, v1.z, v1.w};
;             float s = 0.f, ss = 0.f;
; #pragma unroll
;             for (int i = 0; i < 8; ++i) { s += v[i]; ss += v[i] * v[i]; }
;             s = wave_sum(s); ss = wave_sum(ss);
;             const float mean = s * (1.0f / 512.f);
;             const float var = fmaxf(ss * (1.0f / 512.f) - mean * mean, 0.f);
;             const float rstd = rsqrtf(var + 1e-5f);
;             bf16_t* gp = P1 + (long)(R0 + t) * P1W + 2048 + lane * 8;
;             uint4 gv = ld_nt_u4(gp);
;             const float gt[8] = {bflo(gv.x), bfhi(gv.x), bflo(gv.y), bfhi(gv.y), bflo(gv.z), bfhi(gv.z), bflo(gv.w), bfhi(gv.w)};
;             float y[8];
; #pragma unroll
;             for (int i = 0; i < 8; ++i) {
;                 float u = (v[i] - mean) * rstd * gg[i] + bb[i];
;                 y[i] = u * sigmoidf_(u) * siluf_(gt[i]);
;             }
;             uint4 o; o.x = pk2(y[0], y[1]); o.y = pk2(y[2], y[3]); o.z = pk2(y[4], y[5]); o.w = pk2(y[6], y[7]);
;             st16_wt(gp, o);
;         }
	v_pk_mul_f32 v[42:43], v[32:33], v[32:33]
	s_waitcnt lgkmcnt(0)
	v_mov_b32_e32 v49, v37
	v_pk_mul_f32 v[46:47], v[36:37], v[36:37]
	v_pk_add_f32 v[48:49], v[36:37], v[48:49]
	v_pk_mul_f32 v[18:19], v[34:35], v[34:35]
	v_pk_mov_b32 v[48:49], v[46:47], v[48:49] op_sel:[1,0]
	v_mov_b32_e32 v47, v37
	v_pk_add_f32 v[46:47], v[48:49], v[46:47]
	v_mov_b32_e32 v49, v38
	v_lshlrev_b32_e32 v44, 16, v30
	v_and_b32_e32 v45, 0xffff0000, v30
	v_mul_f32_e32 v30, 0xbfb8aa3b, v44
	v_lshlrev_b32_e32 v40, 16, v31
	v_and_b32_e32 v41, 0xffff0000, v31
	v_exp_f32_e32 v50, v30
	v_pk_mul_f32 v[30:31], v[38:39], v[38:39]
	s_nop 0
	v_mov_b32_e32 v48, v30
	v_pk_add_f32 v[46:47], v[46:47], v[48:49]
	v_mov_b32_e32 v30, v31
	v_mov_b32_e32 v31, v39
	v_pk_add_f32 v[30:31], v[46:47], v[30:31]
	v_mov_b32_e32 v46, v42
	v_mov_b32_e32 v47, v32
	v_pk_add_f32 v[30:31], v[30:31], v[46:47]
	v_mov_b32_e32 v42, v43
	v_mov_b32_e32 v43, v33
	v_pk_add_f32 v[30:31], v[30:31], v[42:43]
	v_mov_b32_e32 v42, v18
	v_mov_b32_e32 v43, v34
	v_pk_add_f32 v[30:31], v[30:31], v[42:43]
	v_mov_b32_e32 v18, v19
	v_mov_b32_e32 v19, v35
	v_pk_add_f32 v[18:19], v[30:31], v[18:19]
	ds_bpermute_b32 v31, v25, v19
	ds_bpermute_b32 v30, v25, v18
	v_lshlrev_b32_e32 v46, 16, v29
	v_and_b32_e32 v47, 0xffff0000, v29
	v_mul_f32_e32 v29, 0xbfb8aa3b, v46
	v_mul_f32_e32 v43, 0xbfb8aa3b, v45
	s_waitcnt lgkmcnt(0)
	v_pk_add_f32 v[18:19], v[18:19], v[30:31]
	ds_bpermute_b32 v31, v24, v19
	ds_bpermute_b32 v30, v24, v18
	v_exp_f32_e32 v29, v29
	v_mul_f32_e32 v48, 0xbfb8aa3b, v47
	v_exp_f32_e32 v43, v43
	v_exp_f32_e32 v49, v48
	s_waitcnt lgkmcnt(0)
	v_pk_add_f32 v[18:19], v[18:19], v[30:31]
	s_nop 1
	v_mov_b32_dpp v31, v19 row_ror:8 row_mask:0xf bank_mask:0xf
	v_mov_b32_dpp v30, v18 row_ror:8 row_mask:0xf bank_mask:0xf
	v_add_f32_e32 v29, 1.0, v29
	v_add_f32_e32 v42, 1.0, v50
	v_add_f32_e32 v43, 1.0, v43
	v_rcp_f32_e32 v48, v29
	s_waitcnt lgkmcnt(0)
	v_pk_add_f32 v[18:19], v[18:19], v[30:31]
	s_nop 1
	v_mov_b32_dpp v31, v19 row_ror:4 row_mask:0xf bank_mask:0xf
	v_mov_b32_dpp v30, v18 row_ror:4 row_mask:0xf bank_mask:0xf
	v_add_f32_e32 v29, 1.0, v49
	v_rcp_f32_e32 v42, v42
	v_rcp_f32_e32 v43, v43
	v_rcp_f32_e32 v49, v29
	s_waitcnt lgkmcnt(0)
	v_pk_add_f32 v[18:19], v[18:19], v[30:31]
	s_nop 1
	v_mov_b32_dpp v31, v19 row_ror:2 row_mask:0xf bank_mask:0xf
	v_mov_b32_dpp v30, v18 row_ror:2 row_mask:0xf bank_mask:0xf
	v_pk_mul_f32 v[42:43], v[42:43], v[44:45]
	v_pk_mul_f32 v[44:45], v[48:49], v[46:47]
	v_lshlrev_b32_e32 v46, 16, v28
	v_and_b32_e32 v47, 0xffff0000, v28
	s_waitcnt lgkmcnt(0)
	v_pk_add_f32 v[18:19], v[18:19], v[30:31]
	s_nop 1
	v_mov_b32_dpp v29, v19 row_ror:1 row_mask:0xf bank_mask:0xf
	v_mov_b32_dpp v28, v18 row_ror:1 row_mask:0xf bank_mask:0xf
	v_mul_f32_e32 v30, 0xbfb8aa3b, v46
	v_exp_f32_e32 v30, v30
	v_mul_f32_e32 v31, 0xbfb8aa3b, v47
	v_exp_f32_e32 v31, v31
	s_waitcnt lgkmcnt(0)
	v_pk_add_f32 v[18:19], v[18:19], v[28:29]
	v_add_f32_e32 v31, 1.0, v31
	v_pk_mul_f32 v[18:19], v[18:19], s[12:13] op_sel_hi:[1,0]
	s_nop 0
	v_fma_f32 v28, -v19, v19, v18
	v_max_f32_e32 v28, 0, v28
	v_add_f32_e32 v28, 0x3727c5ac, v28
	v_mul_f32_e32 v29, 0x4b800000, v28
	v_cmp_gt_f32_e32 vcc, s94, v28
	v_pk_add_f32 v[36:37], v[36:37], v[18:19] op_sel:[0,1] neg_lo:[0,1] neg_hi:[0,1]
	v_pk_add_f32 v[38:39], v[38:39], v[18:19] op_sel:[0,1] neg_lo:[0,1] neg_hi:[0,1]
	v_cndmask_b32_e32 v28, v28, v29, vcc
	v_rsq_f32_e32 v29, v28
	v_add_f32_e32 v28, 1.0, v30
	v_rcp_f32_e32 v28, v28
	v_pk_add_f32 v[32:33], v[32:33], v[18:19] op_sel:[0,1] neg_lo:[0,1] neg_hi:[0,1]
	v_mul_f32_e32 v30, 0x45800000, v29
	v_cndmask_b32_e32 v30, v29, v30, vcc
	v_pk_mul_f32 v[36:37], v[36:37], v[30:31] op_sel_hi:[1,0]
	v_pk_add_f32 v[18:19], v[34:35], v[18:19] op_sel:[0,1] neg_lo:[0,1] neg_hi:[0,1]
	v_pk_fma_f32 v[36:37], v[8:9], v[36:37], v[12:13]
	v_mul_f32_e32 v34, 0xbfb8aa3b, v40
	v_mul_f32_e32 v29, 0xbfb8aa3b, v36
	v_exp_f32_e32 v48, v29
	v_mul_f32_e32 v29, 0xbfb8aa3b, v37
	v_exp_f32_e32 v49, v29
	v_rcp_f32_e32 v29, v31
	v_add_f32_e32 v31, 1.0, v48
	v_rcp_f32_e32 v48, v31
	v_add_f32_e32 v31, 1.0, v49
	v_pk_mul_f32 v[38:39], v[38:39], v[30:31] op_sel_hi:[1,0]
	v_pk_mul_f32 v[28:29], v[28:29], v[46:47]
	v_pk_fma_f32 v[38:39], v[10:11], v[38:39], v[14:15]
	v_exp_f32_e32 v34, v34
	v_mul_f32_e32 v49, 0xbfb8aa3b, v38
	v_exp_f32_e32 v50, v49
	v_mul_f32_e32 v49, 0xbfb8aa3b, v39
	v_exp_f32_e32 v51, v49
	v_rcp_f32_e32 v49, v31
	v_add_f32_e32 v31, 1.0, v50
	v_rcp_f32_e32 v50, v31
	v_add_f32_e32 v31, 1.0, v51
	v_rcp_f32_e32 v51, v31
	v_pk_mul_f32 v[32:33], v[32:33], v[30:31] op_sel_hi:[1,0]
	v_pk_mul_f32 v[36:37], v[36:37], v[48:49]
	v_pk_fma_f32 v[32:33], v[0:1], v[32:33], v[4:5]
	v_pk_mul_f32 v[28:29], v[28:29], v[36:37]
	v_mul_f32_e32 v31, 0xbfb8aa3b, v32
	v_pk_mul_f32 v[36:37], v[38:39], v[50:51]
	v_exp_f32_e32 v31, v31
	v_mul_f32_e32 v38, 0xbfb8aa3b, v33
	v_exp_f32_e32 v39, v38
	v_pk_mul_f32 v[36:37], v[44:45], v[36:37]
	v_add_f32_e32 v31, 1.0, v31
	v_rcp_f32_e32 v38, v31
	v_add_f32_e32 v31, 1.0, v39
	v_pk_mul_f32 v[18:19], v[18:19], v[30:31] op_sel_hi:[1,0]
	v_rcp_f32_e32 v39, v31
	v_pk_fma_f32 v[18:19], v[2:3], v[18:19], v[6:7]
	v_add_f32_e32 v31, 1.0, v34
	v_mul_f32_e32 v34, 0xbfb8aa3b, v19
	v_mul_f32_e32 v30, 0xbfb8aa3b, v18
	v_exp_f32_e32 v35, v34
	v_mul_f32_e32 v34, 0xbfb8aa3b, v41
	v_exp_f32_e32 v30, v30
	v_exp_f32_e32 v44, v34
	v_rcp_f32_e32 v34, v31
	v_add_f32_e32 v31, 1.0, v35
	v_add_f32_e32 v30, 1.0, v30
	v_add_f32_e32 v35, 1.0, v44
	v_rcp_f32_e32 v30, v30
	v_rcp_f32_e32 v31, v31
	v_rcp_f32_e32 v35, v35
	v_pk_mul_f32 v[32:33], v[32:33], v[38:39]
	v_cvt_pk_bf16_f32 v28, v28, v29
	v_pk_mul_f32 v[18:19], v[18:19], v[30:31]
	v_pk_mul_f32 v[30:31], v[34:35], v[40:41]
	v_pk_mul_f32 v[32:33], v[42:43], v[32:33]
	v_pk_mul_f32 v[18:19], v[30:31], v[18:19]
	v_cvt_pk_bf16_f32 v29, v36, v37
	v_cvt_pk_bf16_f32 v30, v32, v33
	v_cvt_pk_bf16_f32 v31, v18, v19
	global_store_dwordx4 v[16:17], v[28:31], off sc1
	s_nop 1
	v_add_u32_e32 v16, s3, v26
	v_ashrrev_i32_e32 v17, 31, v16
	v_lshlrev_b64 v[16:17], 13, v[16:17]
	v_lshl_add_u64 v[16:17], s[78:79], 0, v[16:17]
	v_lshl_add_u64 v[16:17], v[16:17], 0, v[128:129]
	v_add_co_u32_e32 v18, vcc, s0, v16
	v_mov_b32_e32 v46, v129
	s_nop 0
	v_addc_co_u32_e32 v19, vcc, 0, v17, vcc
	v_mov_b32_e32 v28, v152
	v_mov_b32_e32 v29, v153
	v_mov_b32_e32 v30, v154
	v_mov_b32_e32 v31, v155
	v_lshl_add_u32 v18, v26, 11, v27
	ds_read_b128 v[32:35], v18 offset:63504
	ds_read_b128 v[36:39], v18 offset:63488
	v_readlane_b32 s0, v234, 41
	v_lshl_add_u64 v[16:17], v[16:17], 0, s[10:11]
	s_add_i32 s8, s8, s0
	s_waitcnt lgkmcnt(1)
; __device__ __forceinline__ float sigmoidf_(float x) { return __builtin_amdgcn_rcpf(1.0f + __expf(-x)); }
; __device__ __forceinline__ float siluf_(float x) { return x * sigmoidf_(x); }
; __device__ __forceinline__ void conv_item(const Params& p, int l, int item) {
;     ...
;         for (int tt = 0; tt < 4; ++tt) {
;             const int t = wv * 4 + tt;
;             float4 v0 = *reinterpret_cast<const float4*>(CV + t * 512 + lane * 8);
;             float4 v1 = *reinterpret_cast<const float4*>(CV + t * 512 + lane * 8 + 4);
;             float v[8] = {v0.x, v0.y, v0.z, v0.w, v1.x, v1.y, v1.z, v1.w};
;             float s = 0.f, ss = 0.f;
; #pragma unroll
;             for (int i = 0; i < 8; ++i) { s += v[i]; ss += v[i] * v[i]; }
;             s = wave_sum(s); ss = wave_sum(ss);
;             const float mean = s * (1.0f / 512.f);
;             const float var = fmaxf(ss * (1.0f / 512.f) - mean * mean, 0.f);
;             const float rstd = rsqrtf(var + 1e-5f);
;             bf16_t* gp = P1 + (long)(R0 + t) * P1W + 2048 + lane * 8;
;             uint4 gv = ld_nt_u4(gp);
;             const float gt[8] = {bflo(gv.x), bfhi(gv.x), bflo(gv.y), bfhi(gv.y), bflo(gv.z), bfhi(gv.z), bflo(gv.w), bfhi(gv.w)};
;             float y[8];
; #pragma unroll
;             for (int i = 0; i < 8; ++i) {
;                 float u = (v[i] - mean) * rstd * gg[i] + bb[i];
;                 y[i] = u * sigmoidf_(u) * siluf_(gt[i]);
;             }
;             uint4 o; o.x = pk2(y[0], y[1]); o.y = pk2(y[2], y[3]); o.z = pk2(y[4], y[5]); o.w = pk2(y[6], y[7]);
;             st16_wt(gp, o);
;         }
;     }
;     __syncthreads();
	v_pk_mul_f32 v[40:41], v[32:33], v[32:33]
	s_waitcnt lgkmcnt(0)
	v_mov_b32_e32 v47, v37
	v_pk_mul_f32 v[44:45], v[36:37], v[36:37]
	v_pk_add_f32 v[46:47], v[36:37], v[46:47]
	v_pk_mul_f32 v[18:19], v[34:35], v[34:35]
	v_pk_mov_b32 v[46:47], v[44:45], v[46:47] op_sel:[1,0]
	v_mov_b32_e32 v45, v37
	v_pk_add_f32 v[44:45], v[46:47], v[44:45]
	v_mov_b32_e32 v47, v38
	v_readlane_b32 s0, v234, 42
	s_add_i32 s3, s3, s0
	s_cmpk_gt_i32 s8, 0x1ff
	v_lshlrev_b32_e32 v42, 16, v30
	v_and_b32_e32 v43, 0xffff0000, v30
	v_mul_f32_e32 v30, 0xbfb8aa3b, v42
	v_lshlrev_b32_e32 v26, 16, v31
	v_and_b32_e32 v27, 0xffff0000, v31
	v_exp_f32_e32 v48, v30
	v_pk_mul_f32 v[30:31], v[38:39], v[38:39]
	s_nop 0
	v_mov_b32_e32 v46, v30
	v_pk_add_f32 v[44:45], v[44:45], v[46:47]
	v_mov_b32_e32 v30, v31
	v_mov_b32_e32 v31, v39
	v_pk_add_f32 v[30:31], v[44:45], v[30:31]
	v_mov_b32_e32 v44, v40
	v_mov_b32_e32 v45, v32
	v_pk_add_f32 v[30:31], v[30:31], v[44:45]
	v_mov_b32_e32 v40, v41
	v_mov_b32_e32 v41, v33
	v_pk_add_f32 v[30:31], v[30:31], v[40:41]
	v_mov_b32_e32 v40, v18
	v_mov_b32_e32 v41, v34
	v_pk_add_f32 v[30:31], v[30:31], v[40:41]
	v_mov_b32_e32 v18, v19
	v_mov_b32_e32 v19, v35
	v_pk_add_f32 v[18:19], v[30:31], v[18:19]
	ds_bpermute_b32 v31, v25, v19
	ds_bpermute_b32 v30, v25, v18
	v_add_f32_e32 v25, 1.0, v48
	v_rcp_f32_e32 v40, v25
	v_mul_f32_e32 v25, 0xbfb8aa3b, v43
	v_exp_f32_e32 v41, v25
	s_waitcnt lgkmcnt(0)
	v_pk_add_f32 v[18:19], v[18:19], v[30:31]
	ds_bpermute_b32 v25, v24, v19
	ds_bpermute_b32 v24, v24, v18
	v_add_f32_e32 v30, 1.0, v41
	v_rcp_f32_e32 v41, v30
	v_lshlrev_b32_e32 v30, 16, v29
	v_and_b32_e32 v31, 0xffff0000, v29
	s_waitcnt lgkmcnt(0)
	v_pk_add_f32 v[18:19], v[18:19], v[24:25]
	s_nop 1
	v_mov_b32_dpp v25, v19 row_ror:8 row_mask:0xf bank_mask:0xf
	v_mov_b32_dpp v24, v18 row_ror:8 row_mask:0xf bank_mask:0xf
	v_mul_f32_e32 v23, 0xbfb8aa3b, v30
	v_exp_f32_e32 v29, v23
	v_mul_f32_e32 v23, 0xbfb8aa3b, v31
	v_exp_f32_e32 v44, v23
	s_waitcnt lgkmcnt(0)
	v_pk_add_f32 v[18:19], v[18:19], v[24:25]
	s_nop 1
	v_mov_b32_dpp v23, v19 row_ror:4 row_mask:0xf bank_mask:0xf
	v_mov_b32_dpp v22, v18 row_ror:4 row_mask:0xf bank_mask:0xf
	v_add_f32_e32 v24, 1.0, v29
	v_add_f32_e32 v25, 1.0, v44
	v_rcp_f32_e32 v24, v24
	v_rcp_f32_e32 v25, v25
	s_waitcnt lgkmcnt(0)
	v_pk_add_f32 v[18:19], v[18:19], v[22:23]
	s_nop 1
	v_mov_b32_dpp v23, v19 row_ror:2 row_mask:0xf bank_mask:0xf
	v_mov_b32_dpp v22, v18 row_ror:2 row_mask:0xf bank_mask:0xf
	v_pk_mul_f32 v[24:25], v[24:25], v[30:31]
	v_lshlrev_b32_e32 v30, 16, v28
	v_and_b32_e32 v31, 0xffff0000, v28
	v_pk_mul_f32 v[40:41], v[40:41], v[42:43]
	s_waitcnt lgkmcnt(0)
	v_pk_add_f32 v[18:19], v[18:19], v[22:23]
	s_nop 1
	v_mov_b32_dpp v21, v19 row_ror:1 row_mask:0xf bank_mask:0xf
	v_mov_b32_dpp v20, v18 row_ror:1 row_mask:0xf bank_mask:0xf
	v_mul_f32_e32 v22, 0xbfb8aa3b, v30
	v_exp_f32_e32 v22, v22
	v_mul_f32_e32 v23, 0xbfb8aa3b, v31
	v_exp_f32_e32 v23, v23
	s_waitcnt lgkmcnt(0)
	v_pk_add_f32 v[18:19], v[18:19], v[20:21]
	v_add_f32_e32 v23, 1.0, v23
	v_pk_mul_f32 v[18:19], v[18:19], s[12:13] op_sel_hi:[1,0]
	s_nop 0
	v_fma_f32 v20, -v19, v19, v18
	v_max_f32_e32 v20, 0, v20
	v_add_f32_e32 v20, 0x3727c5ac, v20
	v_mul_f32_e32 v21, 0x4b800000, v20
	v_cmp_gt_f32_e32 vcc, s94, v20
	v_pk_add_f32 v[28:29], v[36:37], v[18:19] op_sel:[0,1] neg_lo:[0,1] neg_hi:[0,1]
	s_nop 0
	v_cndmask_b32_e32 v20, v20, v21, vcc
	v_rsq_f32_e32 v21, v20
	v_add_f32_e32 v20, 1.0, v22
	v_rcp_f32_e32 v20, v20
	v_mul_f32_e32 v22, 0x45800000, v21
	v_cndmask_b32_e32 v22, v21, v22, vcc
	v_pk_mul_f32 v[28:29], v[28:29], v[22:23] op_sel_hi:[1,0]
	v_rcp_f32_e32 v21, v23
	v_pk_fma_f32 v[8:9], v[8:9], v[28:29], v[12:13]
	v_pk_add_f32 v[28:29], v[38:39], v[18:19] op_sel:[0,1] neg_lo:[0,1] neg_hi:[0,1]
	v_mul_f32_e32 v12, 0xbfb8aa3b, v8
	v_mul_f32_e32 v13, 0xbfb8aa3b, v9
	v_exp_f32_e32 v12, v12
	v_exp_f32_e32 v13, v13
	v_pk_mul_f32 v[28:29], v[28:29], v[22:23] op_sel_hi:[1,0]
	v_pk_mul_f32 v[20:21], v[20:21], v[30:31]
	v_add_f32_e32 v12, 1.0, v12
	v_add_f32_e32 v13, 1.0, v13
	v_rcp_f32_e32 v12, v12
	v_rcp_f32_e32 v13, v13
	v_pk_fma_f32 v[10:11], v[10:11], v[28:29], v[14:15]
	v_pk_mul_f32 v[8:9], v[8:9], v[12:13]
	v_mul_f32_e32 v14, 0xbfb8aa3b, v10
	v_mul_f32_e32 v15, 0xbfb8aa3b, v11
	v_exp_f32_e32 v14, v14
	v_exp_f32_e32 v15, v15
	v_pk_add_f32 v[12:13], v[32:33], v[18:19] op_sel:[0,1] neg_lo:[0,1] neg_hi:[0,1]
	v_pk_mul_f32 v[8:9], v[20:21], v[8:9]
	v_pk_mul_f32 v[12:13], v[12:13], v[22:23] op_sel_hi:[1,0]
	v_add_f32_e32 v14, 1.0, v14
	v_pk_fma_f32 v[0:1], v[0:1], v[12:13], v[4:5]
	v_add_f32_e32 v15, 1.0, v15
	v_mul_f32_e32 v4, 0xbfb8aa3b, v0
	v_rcp_f32_e32 v14, v14
	v_rcp_f32_e32 v15, v15
	v_exp_f32_e32 v12, v4
	v_mul_f32_e32 v4, 0xbfb8aa3b, v1
	v_exp_f32_e32 v13, v4
	v_pk_mul_f32 v[10:11], v[10:11], v[14:15]
	s_nop 0
	v_pk_mul_f32 v[4:5], v[24:25], v[10:11]
	v_add_f32_e32 v10, 1.0, v12
	v_add_f32_e32 v11, 1.0, v13
	v_pk_add_f32 v[12:13], v[34:35], v[18:19] op_sel:[0,1] neg_lo:[0,1] neg_hi:[0,1]
	v_rcp_f32_e32 v10, v10
	v_pk_mul_f32 v[12:13], v[12:13], v[22:23] op_sel_hi:[1,0]
	v_rcp_f32_e32 v11, v11
	v_pk_fma_f32 v[2:3], v[2:3], v[12:13], v[6:7]
	v_mul_f32_e32 v7, 0xbfb8aa3b, v26
	v_mul_f32_e32 v12, 0xbfb8aa3b, v3
	v_mul_f32_e32 v6, 0xbfb8aa3b, v2
	v_exp_f32_e32 v7, v7
	v_exp_f32_e32 v13, v12
	v_mul_f32_e32 v12, 0xbfb8aa3b, v27
	v_exp_f32_e32 v6, v6
	v_exp_f32_e32 v14, v12
	v_add_f32_e32 v7, 1.0, v7
	v_rcp_f32_e32 v12, v7
	v_add_f32_e32 v6, 1.0, v6
	v_add_f32_e32 v7, 1.0, v13
	v_add_f32_e32 v13, 1.0, v14
	v_rcp_f32_e32 v6, v6
	v_rcp_f32_e32 v7, v7
	v_rcp_f32_e32 v13, v13
	v_pk_mul_f32 v[0:1], v[0:1], v[10:11]
	s_nop 0
	v_pk_mul_f32 v[10:11], v[40:41], v[0:1]
	v_pk_mul_f32 v[0:1], v[2:3], v[6:7]
	v_pk_mul_f32 v[2:3], v[12:13], v[26:27]
	s_nop 0
	v_pk_mul_f32 v[6:7], v[2:3], v[0:1]
	v_cvt_pk_bf16_f32 v0, v8, v9
	v_cvt_pk_bf16_f32 v1, v4, v5
	v_cvt_pk_bf16_f32 v2, v10, v11
	v_cvt_pk_bf16_f32 v3, v6, v7
	global_store_dwordx4 v[16:17], v[0:3], off sc1
	s_nop 1
	s_barrier
	s_cbranch_scc1 .LBB0_196

; __device__ __forceinline__ float siluf_(float x) { return x * sigmoidf_(x); }
; __device__ __forceinline__ void attn_block(const Params& p, int bh, int qblk) {
;     ...
;     bf16_t* orow = P1 + (long)(b * T_ + q0 + ql) * P1W + 3584 + h * 64 + 4 * hi;
; #pragma unroll
;     for (int dt = 0; dt < 2; ++dt)
; #pragma unroll
;         for (int c = 0; c < 4; ++c) {
;             bf16_t* gp = orow + dt * 32 + 8 * c;
;             uint2 gv = *reinterpret_cast<const uint2*>(gp);
;             float a0 = dt ? o1[4 * c] : o0[4 * c], a1 = dt ? o1[4 * c + 1] : o0[4 * c + 1];
;             float a2 = dt ? o1[4 * c + 2] : o0[4 * c + 2], a3 = dt ? o1[4 * c + 3] : o0[4 * c + 3];
;             uint2 o; o.x = pk2(a0 * siluf_(bflo(gv.x)), a1 * siluf_(bfhi(gv.x))); o.y = pk2(a2 * siluf_(bflo(gv.y)), a3 * siluf_(bfhi(gv.y)));
;             *reinterpret_cast<uint2*>(gp) = o;
;         }
.LBB0_188:
	s_or_b64 exec, exec, s[92:93]
	v_lshl_add_u64 v[32:33], v[92:93], 0, s[72:73]
	v_mov_b32_e32 v95, v129
	v_lshl_add_u64 v[34:35], v[32:33], 0, v[94:95]
	s_mov_b64 s[0:1], 0x1c00
	v_lshl_add_u64 v[32:33], v[34:35], 0, s[0:1]
	v_add_co_u32_e32 v34, vcc, 0x1000, v34
	v_readlane_b32 s0, v234, 11
	s_nop 0
	v_addc_co_u32_e32 v35, vcc, 0, v35, vcc
	global_load_dwordx2 v[140:141], v[32:33], off
	global_load_dwordx2 v[142:143], v[32:33], off offset:16
	global_load_dwordx2 v[144:145], v[32:33], off offset:32
	global_load_dwordx2 v[146:147], v[32:33], off offset:48
	global_load_dwordx2 v[148:149], v[32:33], off offset:64
	global_load_dwordx2 v[150:151], v[32:33], off offset:80
	global_load_dwordx2 v[152:153], v[32:33], off offset:96
	global_load_dwordx2 v[154:155], v[32:33], off offset:112
	s_waitcnt vmcnt(7)
	v_mov_b32_e32 v36, v140
	v_mov_b32_e32 v37, v141
	s_add_i32 s54, s54, s0
	s_add_i32 s71, s71, s0
	s_cmpk_lt_i32 s54, 0x200
	v_lshlrev_b32_e32 v38, 16, v36
	v_and_b32_e32 v39, 0xffff0000, v36
	v_mul_f32_e32 v36, 0xbfb8aa3b, v38
	v_exp_f32_e32 v36, v36
	s_nop 0
	v_add_f32_e32 v36, 1.0, v36
	v_rcp_f32_e32 v40, v36
	v_mul_f32_e32 v36, 0xbfb8aa3b, v39
	v_exp_f32_e32 v36, v36
	s_nop 0
	v_add_f32_e32 v36, 1.0, v36
	v_rcp_f32_e32 v41, v36
	v_lshlrev_b32_e32 v36, 16, v37
	v_and_b32_e32 v37, 0xffff0000, v37
	v_pk_mul_f32 v[38:39], v[40:41], v[38:39]
	s_nop 0
	v_pk_mul_f32 v[16:17], v[16:17], v[38:39]
	s_nop 0
	v_cvt_pk_bf16_f32 v16, v16, v17
	v_mul_f32_e32 v17, 0xbfb8aa3b, v36
	v_exp_f32_e32 v17, v17
	s_nop 0
	v_add_f32_e32 v17, 1.0, v17
	v_rcp_f32_e32 v38, v17
	v_mul_f32_e32 v17, 0xbfb8aa3b, v37
	v_exp_f32_e32 v17, v17
	s_nop 0
	v_add_f32_e32 v17, 1.0, v17
	v_rcp_f32_e32 v39, v17
	s_nop 0
	v_pk_mul_f32 v[36:37], v[38:39], v[36:37]
	s_nop 0
	v_pk_mul_f32 v[18:19], v[18:19], v[36:37]
	s_nop 0
	v_cvt_pk_bf16_f32 v17, v18, v19
	global_store_dwordx2 v[34:35], v[16:17], off offset:3072
	s_waitcnt vmcnt(7)
	v_mov_b32_e32 v16, v142
	v_mov_b32_e32 v17, v143
	v_lshlrev_b32_e32 v18, 16, v16
	v_and_b32_e32 v19, 0xffff0000, v16
	v_mul_f32_e32 v16, 0xbfb8aa3b, v18
	v_exp_f32_e32 v16, v16
	s_nop 0
	v_add_f32_e32 v16, 1.0, v16
	v_rcp_f32_e32 v34, v16
	v_mul_f32_e32 v16, 0xbfb8aa3b, v19
	v_exp_f32_e32 v16, v16
	s_nop 0
	v_add_f32_e32 v16, 1.0, v16
	v_rcp_f32_e32 v35, v16
	s_nop 0
	v_pk_mul_f32 v[18:19], v[34:35], v[18:19]
	s_nop 0
	v_pk_mul_f32 v[18:19], v[20:21], v[18:19]
	s_nop 0
	v_cvt_pk_bf16_f32 v16, v18, v19
	v_lshlrev_b32_e32 v18, 16, v17
	v_and_b32_e32 v19, 0xffff0000, v17
	v_mul_f32_e32 v17, 0xbfb8aa3b, v18
	v_exp_f32_e32 v17, v17
	s_nop 0
	v_add_f32_e32 v17, 1.0, v17
	v_rcp_f32_e32 v20, v17
	v_mul_f32_e32 v17, 0xbfb8aa3b, v19
	v_exp_f32_e32 v17, v17
	s_nop 0
	v_add_f32_e32 v17, 1.0, v17
	v_rcp_f32_e32 v21, v17
	s_nop 0
	v_pk_mul_f32 v[18:19], v[20:21], v[18:19]
	s_nop 0
	v_pk_mul_f32 v[18:19], v[22:23], v[18:19]
	s_nop 0
	v_cvt_pk_bf16_f32 v17, v18, v19
	global_store_dwordx2 v[32:33], v[16:17], off offset:16
	s_waitcnt vmcnt(7)
	v_mov_b32_e32 v16, v144
	v_mov_b32_e32 v17, v145
	v_lshlrev_b32_e32 v18, 16, v16
	v_and_b32_e32 v19, 0xffff0000, v16
	v_mul_f32_e32 v16, 0xbfb8aa3b, v18
	v_exp_f32_e32 v16, v16
	s_nop 0
	v_add_f32_e32 v16, 1.0, v16
	v_rcp_f32_e32 v20, v16
	v_mul_f32_e32 v16, 0xbfb8aa3b, v19
	v_exp_f32_e32 v16, v16
	s_nop 0
	v_add_f32_e32 v16, 1.0, v16
	v_rcp_f32_e32 v21, v16
	s_nop 0
	v_pk_mul_f32 v[18:19], v[20:21], v[18:19]
	s_nop 0
	v_pk_mul_f32 v[18:19], v[24:25], v[18:19]
	s_nop 0
	v_cvt_pk_bf16_f32 v16, v18, v19
	v_lshlrev_b32_e32 v18, 16, v17
	v_and_b32_e32 v19, 0xffff0000, v17
	v_mul_f32_e32 v17, 0xbfb8aa3b, v18
	v_exp_f32_e32 v17, v17
	s_nop 0
	v_add_f32_e32 v17, 1.0, v17
	v_rcp_f32_e32 v20, v17
	v_mul_f32_e32 v17, 0xbfb8aa3b, v19
	v_exp_f32_e32 v17, v17
	s_nop 0
	v_add_f32_e32 v17, 1.0, v17
	v_rcp_f32_e32 v21, v17
	s_nop 0
	v_pk_mul_f32 v[18:19], v[20:21], v[18:19]
	s_nop 0
	v_pk_mul_f32 v[18:19], v[26:27], v[18:19]
	s_nop 0
	v_cvt_pk_bf16_f32 v17, v18, v19
	global_store_dwordx2 v[32:33], v[16:17], off offset:32
	s_waitcnt vmcnt(7)
; __device__ __forceinline__ float siluf_(float x) { return x * sigmoidf_(x); }
; __device__ __forceinline__ void attn_block(const Params& p, int bh, int qblk) {
;     ...
;     bf16_t* orow = P1 + (long)(b * T_ + q0 + ql) * P1W + 3584 + h * 64 + 4 * hi;
; #pragma unroll
;     for (int dt = 0; dt < 2; ++dt)
; #pragma unroll
;         for (int c = 0; c < 4; ++c) {
;             bf16_t* gp = orow + dt * 32 + 8 * c;
;             uint2 gv = *reinterpret_cast<const uint2*>(gp);
;             float a0 = dt ? o1[4 * c] : o0[4 * c], a1 = dt ? o1[4 * c + 1] : o0[4 * c + 1];
;             float a2 = dt ? o1[4 * c + 2] : o0[4 * c + 2], a3 = dt ? o1[4 * c + 3] : o0[4 * c + 3];
;             uint2 o; o.x = pk2(a0 * siluf_(bflo(gv.x)), a1 * siluf_(bfhi(gv.x))); o.y = pk2(a2 * siluf_(bflo(gv.y)), a3 * siluf_(bfhi(gv.y)));
;             *reinterpret_cast<uint2*>(gp) = o;
;         }
;     __syncthreads();
	v_mov_b32_e32 v16, v146
	v_mov_b32_e32 v17, v147
	v_lshlrev_b32_e32 v18, 16, v16
	v_and_b32_e32 v19, 0xffff0000, v16
	v_mul_f32_e32 v16, 0xbfb8aa3b, v18
	v_exp_f32_e32 v16, v16
	s_nop 0
	v_add_f32_e32 v16, 1.0, v16
	v_rcp_f32_e32 v20, v16
	v_mul_f32_e32 v16, 0xbfb8aa3b, v19
	v_exp_f32_e32 v16, v16
	s_nop 0
	v_add_f32_e32 v16, 1.0, v16
	v_rcp_f32_e32 v21, v16
	s_nop 0
	v_pk_mul_f32 v[18:19], v[20:21], v[18:19]
	s_nop 0
	v_pk_mul_f32 v[18:19], v[28:29], v[18:19]
	s_nop 0
	v_cvt_pk_bf16_f32 v16, v18, v19
	v_lshlrev_b32_e32 v18, 16, v17
	v_and_b32_e32 v19, 0xffff0000, v17
	v_mul_f32_e32 v17, 0xbfb8aa3b, v18
	v_exp_f32_e32 v17, v17
	s_nop 0
	v_add_f32_e32 v17, 1.0, v17
	v_rcp_f32_e32 v20, v17
	v_mul_f32_e32 v17, 0xbfb8aa3b, v19
	v_exp_f32_e32 v17, v17
	s_nop 0
	v_add_f32_e32 v17, 1.0, v17
	v_rcp_f32_e32 v21, v17
	s_nop 0
	v_pk_mul_f32 v[18:19], v[20:21], v[18:19]
	s_nop 0
	v_pk_mul_f32 v[18:19], v[30:31], v[18:19]
	s_nop 0
	v_cvt_pk_bf16_f32 v17, v18, v19
	global_store_dwordx2 v[32:33], v[16:17], off offset:48
	s_waitcnt vmcnt(7)
	v_mov_b32_e32 v16, v148
	v_mov_b32_e32 v17, v149
	v_lshlrev_b32_e32 v18, 16, v16
	v_and_b32_e32 v19, 0xffff0000, v16
	v_mul_f32_e32 v16, 0xbfb8aa3b, v18
	v_exp_f32_e32 v16, v16
	s_nop 0
	v_add_f32_e32 v16, 1.0, v16
	v_rcp_f32_e32 v20, v16
	v_mul_f32_e32 v16, 0xbfb8aa3b, v19
	v_exp_f32_e32 v16, v16
	s_nop 0
	v_add_f32_e32 v16, 1.0, v16
	v_rcp_f32_e32 v21, v16
	v_lshlrev_b32_e32 v16, 16, v17
	v_and_b32_e32 v17, 0xffff0000, v17
	v_pk_mul_f32 v[18:19], v[20:21], v[18:19]
	s_nop 0
	v_pk_mul_f32 v[0:1], v[0:1], v[18:19]
	s_nop 0
	v_cvt_pk_bf16_f32 v0, v0, v1
	v_mul_f32_e32 v1, 0xbfb8aa3b, v16
	v_exp_f32_e32 v1, v1
	s_nop 0
	v_add_f32_e32 v1, 1.0, v1
	v_rcp_f32_e32 v18, v1
	v_mul_f32_e32 v1, 0xbfb8aa3b, v17
	v_exp_f32_e32 v1, v1
	s_nop 0
	v_add_f32_e32 v1, 1.0, v1
	v_rcp_f32_e32 v19, v1
	s_nop 0
	v_pk_mul_f32 v[16:17], v[18:19], v[16:17]
	s_nop 0
	v_pk_mul_f32 v[2:3], v[2:3], v[16:17]
	s_nop 0
	v_cvt_pk_bf16_f32 v1, v2, v3
	global_store_dwordx2 v[32:33], v[0:1], off offset:64
	s_waitcnt vmcnt(7)
	v_mov_b32_e32 v0, v150
	v_mov_b32_e32 v1, v151
	v_lshlrev_b32_e32 v2, 16, v0
	v_and_b32_e32 v3, 0xffff0000, v0
	v_mul_f32_e32 v0, 0xbfb8aa3b, v2
	v_exp_f32_e32 v0, v0
	s_nop 0
	v_add_f32_e32 v0, 1.0, v0
	v_rcp_f32_e32 v16, v0
	v_mul_f32_e32 v0, 0xbfb8aa3b, v3
	v_exp_f32_e32 v0, v0
	s_nop 0
	v_add_f32_e32 v0, 1.0, v0
	v_rcp_f32_e32 v17, v0
	s_nop 0
	v_pk_mul_f32 v[2:3], v[16:17], v[2:3]
	s_nop 0
	v_pk_mul_f32 v[2:3], v[4:5], v[2:3]
	s_nop 0
	v_cvt_pk_bf16_f32 v0, v2, v3
	v_lshlrev_b32_e32 v2, 16, v1
	v_and_b32_e32 v3, 0xffff0000, v1
	v_mul_f32_e32 v1, 0xbfb8aa3b, v2
	v_exp_f32_e32 v1, v1
	s_nop 0
	v_add_f32_e32 v1, 1.0, v1
	v_rcp_f32_e32 v4, v1
	v_mul_f32_e32 v1, 0xbfb8aa3b, v3
	v_exp_f32_e32 v1, v1
	s_nop 0
	v_add_f32_e32 v1, 1.0, v1
	v_rcp_f32_e32 v5, v1
	s_nop 0
	v_pk_mul_f32 v[2:3], v[4:5], v[2:3]
	s_nop 0
	v_pk_mul_f32 v[2:3], v[6:7], v[2:3]
	s_nop 0
	v_cvt_pk_bf16_f32 v1, v2, v3
	global_store_dwordx2 v[32:33], v[0:1], off offset:80
	s_waitcnt vmcnt(7)
	v_mov_b32_e32 v0, v152
	v_mov_b32_e32 v1, v153
	v_lshlrev_b32_e32 v2, 16, v0
	v_and_b32_e32 v3, 0xffff0000, v0
	v_mul_f32_e32 v0, 0xbfb8aa3b, v2
	v_exp_f32_e32 v0, v0
	s_nop 0
	v_add_f32_e32 v0, 1.0, v0
	v_rcp_f32_e32 v4, v0
	v_mul_f32_e32 v0, 0xbfb8aa3b, v3
	v_exp_f32_e32 v0, v0
	s_nop 0
	v_add_f32_e32 v0, 1.0, v0
	v_rcp_f32_e32 v5, v0
	s_nop 0
	v_pk_mul_f32 v[2:3], v[4:5], v[2:3]
	s_nop 0
	v_pk_mul_f32 v[2:3], v[8:9], v[2:3]
	s_nop 0
	v_cvt_pk_bf16_f32 v0, v2, v3
	v_lshlrev_b32_e32 v2, 16, v1
	v_and_b32_e32 v3, 0xffff0000, v1
	v_mul_f32_e32 v1, 0xbfb8aa3b, v2
	v_exp_f32_e32 v1, v1
	s_nop 0
	v_add_f32_e32 v1, 1.0, v1
	v_rcp_f32_e32 v4, v1
	v_mul_f32_e32 v1, 0xbfb8aa3b, v3
	v_exp_f32_e32 v1, v1
	s_nop 0
	v_add_f32_e32 v1, 1.0, v1
	v_rcp_f32_e32 v5, v1
	s_nop 0
	v_pk_mul_f32 v[2:3], v[4:5], v[2:3]
	s_nop 0
	v_pk_mul_f32 v[2:3], v[10:11], v[2:3]
	s_nop 0
	v_cvt_pk_bf16_f32 v1, v2, v3
	global_store_dwordx2 v[32:33], v[0:1], off offset:96
	s_waitcnt vmcnt(7)
	v_mov_b32_e32 v0, v154
	v_mov_b32_e32 v1, v155
	v_lshlrev_b32_e32 v2, 16, v0
	v_and_b32_e32 v3, 0xffff0000, v0
	v_mul_f32_e32 v0, 0xbfb8aa3b, v2
	v_exp_f32_e32 v0, v0
	s_nop 0
	v_add_f32_e32 v0, 1.0, v0
	v_rcp_f32_e32 v4, v0
	v_mul_f32_e32 v0, 0xbfb8aa3b, v3
	v_exp_f32_e32 v0, v0
	s_nop 0
	v_add_f32_e32 v0, 1.0, v0
	v_rcp_f32_e32 v5, v0
	s_nop 0
	v_pk_mul_f32 v[2:3], v[4:5], v[2:3]
	s_nop 0
	v_pk_mul_f32 v[2:3], v[12:13], v[2:3]
	s_nop 0
	v_cvt_pk_bf16_f32 v0, v2, v3
	v_lshlrev_b32_e32 v2, 16, v1
	v_and_b32_e32 v3, 0xffff0000, v1
	v_mul_f32_e32 v1, 0xbfb8aa3b, v2
	v_exp_f32_e32 v1, v1
	s_nop 0
	v_add_f32_e32 v1, 1.0, v1
	v_rcp_f32_e32 v4, v1
	v_mul_f32_e32 v1, 0xbfb8aa3b, v3
	v_exp_f32_e32 v1, v1
	s_nop 0
	v_add_f32_e32 v1, 1.0, v1
	v_rcp_f32_e32 v5, v1
	s_nop 0
	v_pk_mul_f32 v[2:3], v[4:5], v[2:3]
	s_nop 0
	v_pk_mul_f32 v[2:3], v[14:15], v[2:3]
	s_nop 0
	v_cvt_pk_bf16_f32 v1, v2, v3
	global_store_dwordx2 v[32:33], v[0:1], off offset:112
	s_barrier
	s_cbranch_scc0 .LBB0_166

; template <int W>
; __device__ __forceinline__ void pool_fill(const bf16_t* P1, char* lds, int tid, int r0, int t0, int g) {
;     ...
;         const uint4 cu = v[rr + W - 1];
;         const float inv = 1.0f / (float)min(t + 1, W);
;         uint4 o;
;         o.x = pk2(sum[0] * inv - bflo(cu.x), sum[1] * inv - bfhi(cu.x));
;         o.y = pk2(sum[2] * inv - bflo(cu.y), sum[3] * inv - bfhi(cu.y));
;         o.z = pk2(sum[4] * inv - bflo(cu.z), sum[5] * inv - bfhi(cu.z));
;         o.w = pk2(sum[6] * inv - bflo(cu.w), sum[7] * inv - bfhi(cu.w));
;         *reinterpret_cast<uint4*>(lds + row * 256 + ((c ^ (row & 15)) * 16)) = o;
;     }
; }
; __device__ __forceinline__ void pool_item(const Params& p, int l, int item) {
;     char* lds = (char*)shm;
;     const int tid = tid_opaque();
;     const int tt = item >> 2, g = item & 3;
;     const int r0 = tt * 256, t0 = r0 & 8191;
;     const int w = 2 << g;
;     bf16_t* P1 = (bf16_t*)(p.ws + WS_P1);
;     const bf16_t* wp = (const bf16_t*)(p.ws + WS_WPOOL) + (long)g * 16384;
;     for (int idx = tid; idx < 2048; idx += NT) {
;         int n = idx >> 4, c = idx & 15;
;         uint4 v = *reinterpret_cast<const uint4*>(wp + n * 128 + c * 8);
;         *reinterpret_cast<uint4*>(lds + 65536 + n * 256 + ((c ^ (n & 15)) * 16)) = v;
;     }
;     if (g == 0) pool_fill<2>(P1, lds, tid, r0, t0, g);
;     else if (g == 1) pool_fill<4>(P1, lds, tid, r0, t0, g);
;     else if (g == 2) pool_fill<8>(P1, lds, tid, r0, t0, g);
;     else pool_fill<16>(P1, lds, tid, r0, t0, g);
;     __syncthreads();
;     {
;         const int wv = tid >> 6, lane = tid & 63, fr = lane & 15, fq = lane >> 4;
;         f32x4 acc[2][8];
; #pragma unroll
;         for (int m = 0; m < 2; ++m)
; #pragma unroll
;             for (int n = 0; n < 8; ++n) acc[m][n] = f32x4{0.f, 0.f, 0.f, 0.f};
; #pragma unroll
;         for (int ks = 0; ks < 4; ++ks) {
;             bf16x8 a[2], bb[8];
; #pragma unroll
;             for (int m = 0; m < 2; ++m) {
;                 int row = wv * 32 + m * 16 + fr;
;                 a[m] = *reinterpret_cast<const bf16x8*>(lds + row * 256 + (((ks * 4 + fq) ^ (row & 15)) * 16));
;             }
; #pragma unroll
;             for (int n = 0; n < 8; ++n) {
;                 int nr = n * 16 + fr;
;                 bb[n] = *reinterpret_cast<const bf16x8*>(lds + 65536 + nr * 256 + (((ks * 4 + fq) ^ (nr & 15)) * 16));
;             }
.LBB0_201:
	v_add_u32_e32 v8, 1, v8
	v_cvt_f32_i32_e32 v8, v8
	v_and_b32_e32 v92, 15, v214
	v_bfe_u32 v93, v214, 4, 2
	v_bitop3_b32 v128, v93, v92, 4 bitop3:0x36
	v_div_scale_f32 v9, s[0:1], v8, v8, 1.0
	v_rcp_f32_e32 v10, v9
	v_lshlrev_b32_e32 v74, 4, v128
	v_bitop3_b32 v138, v93, v92, 8 bitop3:0x36
	v_bitop3_b32 v139, v93, v92, 12 bitop3:0x36
	v_fma_f32 v11, -v9, v10, 1.0
	v_fmac_f32_e32 v10, v11, v10
	v_div_scale_f32 v11, vcc, 1.0, v8, 1.0
	v_mul_f32_e32 v12, v11, v10
	v_fma_f32 v13, -v9, v12, v11
	v_fmac_f32_e32 v12, v13, v10
	v_fma_f32 v9, -v9, v12, v11
	v_div_fmas_f32 v9, v9, v10, v12
	v_div_fixup_f32 v10, v9, v8, 1.0
	v_pk_fma_f32 v[0:1], v[10:11], v[0:1], v[34:35] op_sel_hi:[0,1,1] neg_lo:[0,0,1] neg_hi:[0,0,1]
	v_cvt_pk_bf16_f32 v9, v0, v1
	v_xor_b32_e32 v1, v218, v214
	v_lshlrev_b32_e32 v1, 4, v1
	v_pk_fma_f32 v[6:7], v[6:7], v[10:11], v[28:29] op_sel_hi:[1,0,1] neg_lo:[0,0,1] neg_hi:[0,0,1]
	v_pk_fma_f32 v[4:5], v[10:11], v[4:5], v[30:31] op_sel_hi:[0,1,1] neg_lo:[0,0,1] neg_hi:[0,0,1]
	v_pk_fma_f32 v[2:3], v[10:11], v[2:3], v[32:33] op_sel_hi:[0,1,1] neg_lo:[0,0,1] neg_hi:[0,0,1]
	v_lshlrev_b32_e32 v0, 8, v218
	v_and_b32_e32 v1, 0xf0, v1
	v_cvt_pk_bf16_f32 v6, v6, v7
	v_cvt_pk_bf16_f32 v7, v4, v5
	v_cvt_pk_bf16_f32 v8, v2, v3
	v_add3_u32 v0, 0, v0, v1
	ds_write_b128 v0, v[6:9]
	v_lshrrev_b32_e32 v0, 4, v214
	v_bitop3_b32 v44, v0, v92, 3 bitop3:0x6c
	v_lshlrev_b32_e32 v0, 7, v214
	v_lshlrev_b32_e32 v1, 8, v92
	v_and_b32_e32 v0, 0xffffe000, v0
	v_add_u32_e32 v45, s90, v1
	v_lshlrev_b32_e32 v8, 4, v44
	v_add3_u32 v94, 0, v0, v1
	v_add_u32_e32 v4, v94, v8
	v_add_u32_e32 v36, v45, v8
	s_waitcnt lgkmcnt(0)
	s_barrier
	ds_read_b128 v[0:3], v4
	ds_read_b128 v[4:7], v4 offset:4096
	ds_read_b128 v[8:11], v36
	ds_read_b128 v[12:15], v36 offset:4096
	ds_read_b128 v[16:19], v36 offset:8192
	ds_read_b128 v[20:23], v36 offset:12288
	ds_read_b128 v[24:27], v36 offset:16384
	ds_read_b128 v[28:31], v36 offset:20480
	ds_read_b128 v[32:35], v36 offset:24576
	ds_read_b128 v[36:39], v36 offset:28672
	v_add_u32_e32 v70, v94, v74
	s_waitcnt lgkmcnt(0)
	v_mfma_f32_16x16x32_bf16 v[40:43], v[8:11], v[0:3], 0
	v_add_u32_e32 v90, v45, v74
	s_lshl_b32 s0, s12, 7
	s_or_b32 s72, s0, s4
	v_mfma_f32_16x16x32_bf16 v[46:49], v[12:15], v[0:3], 0
	s_lshl_b64 s[0:1], s[72:73], 2
	v_readlane_b32 s16, v234, 49
	v_readlane_b32 s17, v234, 50
	v_mfma_f32_16x16x32_bf16 v[50:53], v[16:19], v[0:3], 0
	s_add_u32 s0, s16, s0
	s_addc_u32 s1, s17, s1
	s_lshl_b32 s2, s12, 9
	v_mfma_f32_16x16x32_bf16 v[54:57], v[20:23], v[0:3], 0
	s_add_u32 s2, s5, s2
	v_lshlrev_b32_e32 v95, 4, v93
	s_addc_u32 s3, s10, 0
	global_load_dwordx4 v[140:143], v95, s[0:1]
	global_load_dwordx4 v[144:147], v95, s[2:3]
	global_load_dwordx4 v[148:151], v95, s[0:1] offset:64
	global_load_dwordx4 v[152:155], v95, s[2:3] offset:64
	global_load_dwordx4 v[156:159], v95, s[0:1] offset:128
	global_load_dwordx4 v[160:163], v95, s[2:3] offset:128
	global_load_dwordx4 v[164:167], v95, s[0:1] offset:192
	global_load_dwordx4 v[168:171], v95, s[2:3] offset:192
	global_load_dwordx4 v[172:175], v95, s[0:1] offset:256
	global_load_dwordx4 v[176:179], v95, s[2:3] offset:256
	global_load_dwordx4 v[180:183], v95, s[0:1] offset:320
	global_load_dwordx4 v[184:187], v95, s[2:3] offset:320
	global_load_dwordx4 v[188:191], v95, s[0:1] offset:384
	global_load_dwordx4 v[192:195], v95, s[2:3] offset:384
	global_load_dwordx4 v[196:199], v95, s[0:1] offset:448
	global_load_dwordx4 v[200:203], v95, s[2:3] offset:448
	v_mfma_f32_16x16x32_bf16 v[58:61], v[24:27], v[0:3], 0
	s_lshl_b32 s72, s12, 8
	v_readlane_b32 s18, v234, 51
	v_readlane_b32 s19, v234, 52
	v_mfma_f32_16x16x32_bf16 v[62:65], v[28:31], v[0:3], 0
	v_mfma_f32_16x16x32_bf16 v[66:69], v[32:35], v[0:3], 0
	v_mfma_f32_16x16x32_bf16 v[0:3], v[36:39], v[0:3], 0
	v_mfma_f32_16x16x32_bf16 v[8:11], v[8:11], v[4:7], 0
	v_mfma_f32_16x16x32_bf16 v[12:15], v[12:15], v[4:7], 0
	v_mfma_f32_16x16x32_bf16 v[16:19], v[16:19], v[4:7], 0
	v_mfma_f32_16x16x32_bf16 v[20:23], v[20:23], v[4:7], 0
	v_mfma_f32_16x16x32_bf16 v[24:27], v[24:27], v[4:7], 0
	v_mfma_f32_16x16x32_bf16 v[28:31], v[28:31], v[4:7], 0
	v_mfma_f32_16x16x32_bf16 v[32:35], v[32:35], v[4:7], 0
	v_mfma_f32_16x16x32_bf16 v[4:7], v[36:39], v[4:7], 0
	ds_read_b128 v[36:39], v70
	ds_read_b128 v[70:73], v70 offset:4096
	ds_read_b128 v[74:77], v90
	ds_read_b128 v[78:81], v90 offset:4096
	ds_read_b128 v[82:85], v90 offset:8192
	ds_read_b128 v[86:89], v90 offset:12288
	ds_read_b128 v[96:99], v90 offset:16384
	ds_read_b128 v[100:103], v90 offset:20480
	ds_read_b128 v[104:107], v90 offset:24576
	ds_read_b128 v[108:111], v90 offset:28672
	s_waitcnt lgkmcnt(0)
	v_mfma_f32_16x16x32_bf16 v[40:43], v[74:77], v[36:39], v[40:43]
	v_mfma_f32_16x16x32_bf16 v[8:11], v[74:77], v[70:73], v[8:11]
	v_lshlrev_b32_e32 v74, 4, v138
	v_add_u32_e32 v90, v45, v74
	v_mfma_f32_16x16x32_bf16 v[12:15], v[78:81], v[70:73], v[12:15]
	v_mfma_f32_16x16x32_bf16 v[16:19], v[82:85], v[70:73], v[16:19]
	v_mfma_f32_16x16x32_bf16 v[20:23], v[86:89], v[70:73], v[20:23]
	v_mfma_f32_16x16x32_bf16 v[24:27], v[96:99], v[70:73], v[24:27]
	v_mfma_f32_16x16x32_bf16 v[28:31], v[100:103], v[70:73], v[28:31]
	v_mfma_f32_16x16x32_bf16 v[32:35], v[104:107], v[70:73], v[32:35]
	v_mfma_f32_16x16x32_bf16 v[4:7], v[108:111], v[70:73], v[4:7]
	v_add_u32_e32 v70, v94, v74
	v_mfma_f32_16x16x32_bf16 v[46:49], v[78:81], v[36:39], v[46:49]
	v_mfma_f32_16x16x32_bf16 v[50:53], v[82:85], v[36:39], v[50:53]
	v_mfma_f32_16x16x32_bf16 v[54:57], v[86:89], v[36:39], v[54:57]
	v_mfma_f32_16x16x32_bf16 v[58:61], v[96:99], v[36:39], v[58:61]
	v_mfma_f32_16x16x32_bf16 v[62:65], v[100:103], v[36:39], v[62:65]
	v_mfma_f32_16x16x32_bf16 v[66:69], v[104:107], v[36:39], v[66:69]
	v_mfma_f32_16x16x32_bf16 v[0:3], v[108:111], v[36:39], v[0:3]
	ds_read_b128 v[36:39], v70
	ds_read_b128 v[70:73], v70 offset:4096
	ds_read_b128 v[74:77], v90
	ds_read_b128 v[78:81], v90 offset:4096
	ds_read_b128 v[82:85], v90 offset:8192
	ds_read_b128 v[86:89], v90 offset:12288
	ds_read_b128 v[96:99], v90 offset:16384
	ds_read_b128 v[100:103], v90 offset:20480
	ds_read_b128 v[104:107], v90 offset:24576
	ds_read_b128 v[108:111], v90 offset:28672
	s_waitcnt lgkmcnt(0)
; __device__ __forceinline__ f32x4 mfma16(bf16x8 a, bf16x8 b, f32x4 c) { return __builtin_amdgcn_mfma_f32_16x16x32_bf16(a, b, c, 0, 0, 0); }
; __device__ __forceinline__ void pool_item(const Params& p, int l, int item) {
;     ...
;         for (int ks = 0; ks < 4; ++ks) {
;             bf16x8 a[2], bb[8];
; #pragma unroll
;             for (int m = 0; m < 2; ++m) {
;                 int row = wv * 32 + m * 16 + fr;
;                 a[m] = *reinterpret_cast<const bf16x8*>(lds + row * 256 + (((ks * 4 + fq) ^ (row & 15)) * 16));
;             }
; #pragma unroll
;             for (int n = 0; n < 8; ++n) {
;                 int nr = n * 16 + fr;
;                 bb[n] = *reinterpret_cast<const bf16x8*>(lds + 65536 + nr * 256 + (((ks * 4 + fq) ^ (nr & 15)) * 16));
;             }
; #pragma unroll
;             for (int m = 0; m < 2; ++m)
; #pragma unroll
;                 for (int n = 0; n < 8; ++n) acc[m][n] = mfma16(bb[n], a[m], acc[m][n]);
;         }
;         const float* pb = p.pool_b + (l * 4 + g) * 128;
;         const float* ps = p.pool_scale + l * 512 + g * 128;
;         __syncthreads();
; #pragma unroll
;         for (int m = 0; m < 2; ++m)
; #pragma unroll
;             for (int n = 0; n < 8; ++n) {
;                 const int rl = wv * 32 + m * 16 + fr;
;                 const int col = n * 16 + fq * 4;
;                 float4 b4 = *reinterpret_cast<const float4*>(pb + col);
;                 float4 s4 = *reinterpret_cast<const float4*>(ps + col);
;                 f32x4 a = acc[m][n];
;                 uint2 o;
;                 o.x = pk2((a[0] + b4.x) * s4.x, (a[1] + b4.y) * s4.y);
;                 o.y = pk2((a[2] + b4.z) * s4.z, (a[3] + b4.w) * s4.w);
;                 *reinterpret_cast<uint2*>(lds + rl * 256 + ((((col >> 2)) ^ fr) << 3)) = o;
;             }
	v_mfma_f32_16x16x32_bf16 v[40:43], v[74:77], v[36:39], v[40:43]
	v_mfma_f32_16x16x32_bf16 v[8:11], v[74:77], v[70:73], v[8:11]
	v_mfma_f32_16x16x32_bf16 v[74:77], v[86:89], v[70:73], v[20:23]
	s_nop 2
	v_lshlrev_b32_e32 v20, 4, v139
	v_add_u32_e32 v21, v94, v20
	v_mfma_f32_16x16x32_bf16 v[46:49], v[78:81], v[36:39], v[46:49]
	v_mfma_f32_16x16x32_bf16 v[50:53], v[82:85], v[36:39], v[50:53]
	v_mfma_f32_16x16x32_bf16 v[54:57], v[86:89], v[36:39], v[54:57]
	v_mfma_f32_16x16x32_bf16 v[58:61], v[96:99], v[36:39], v[58:61]
	v_mfma_f32_16x16x32_bf16 v[62:65], v[100:103], v[36:39], v[62:65]
	v_mfma_f32_16x16x32_bf16 v[12:15], v[78:81], v[70:73], v[12:15]
	v_mfma_f32_16x16x32_bf16 v[16:19], v[82:85], v[70:73], v[16:19]
	v_mfma_f32_16x16x32_bf16 v[78:81], v[96:99], v[70:73], v[24:27]
	v_mfma_f32_16x16x32_bf16 v[86:89], v[100:103], v[70:73], v[28:31]
	v_mfma_f32_16x16x32_bf16 v[96:99], v[104:107], v[70:73], v[32:35]
	s_nop 1
	v_add_u32_e32 v28, v45, v20
	v_mfma_f32_16x16x32_bf16 v[70:73], v[108:111], v[70:73], v[4:7]
	s_nop 2
	ds_read_b128 v[4:7], v21
	ds_read_b128 v[100:103], v21 offset:4096
	v_mfma_f32_16x16x32_bf16 v[66:69], v[104:107], v[36:39], v[66:69]
	v_mfma_f32_16x16x32_bf16 v[0:3], v[108:111], v[36:39], v[0:3]
	ds_read_b128 v[20:23], v28
	ds_read_b128 v[24:27], v28 offset:4096
	ds_read_b128 v[104:107], v28 offset:8192
	ds_read_b128 v[108:111], v28 offset:12288
	ds_read_b128 v[112:115], v28 offset:16384
	ds_read_b128 v[116:119], v28 offset:20480
	ds_read_b128 v[120:123], v28 offset:24576
	ds_read_b128 v[124:127], v28 offset:28672
	s_waitcnt lgkmcnt(0)
	s_barrier
	v_mfma_f32_16x16x32_bf16 v[130:133], v[20:23], v[4:7], v[40:43]
	v_mfma_f32_16x16x32_bf16 v[40:43], v[104:107], v[4:7], v[50:53]
	s_nop 2
	s_waitcnt vmcnt(0)
	v_mov_b32_e32 v50, v140
	v_mov_b32_e32 v51, v141
	v_mov_b32_e32 v52, v144
	v_mov_b32_e32 v53, v145
	s_nop 0
	s_nop 0
	v_pk_add_f32 v[50:51], v[130:131], v[50:51]
	v_mfma_f32_16x16x32_bf16 v[134:137], v[24:27], v[4:7], v[46:49]
	v_mul_f32_e64 v50, v50, v52
	v_mul_f32_e64 v51, v51, v53
	v_cvt_pk_bf16_f32 v90, v50, v51
	v_mfma_f32_16x16x32_bf16 v[32:35], v[124:127], v[4:7], v[0:3]
	v_mfma_f32_16x16x32_bf16 v[28:31], v[20:23], v[100:103], v[8:11]
	v_mfma_f32_16x16x32_bf16 v[24:27], v[24:27], v[100:103], v[12:15]
	v_mfma_f32_16x16x32_bf16 v[20:23], v[104:107], v[100:103], v[16:19]
	v_mfma_f32_16x16x32_bf16 v[16:19], v[108:111], v[100:103], v[74:77]
	v_mfma_f32_16x16x32_bf16 v[12:15], v[112:115], v[100:103], v[78:81]
	v_mfma_f32_16x16x32_bf16 v[0:3], v[124:127], v[100:103], v[70:73]
	s_nop 2
	v_mov_b32_e32 v72, v140
	v_mov_b32_e32 v73, v141
	v_mov_b32_e32 v74, v142
	v_mov_b32_e32 v75, v143
	v_mov_b32_e32 v78, v144
	v_mov_b32_e32 v79, v145
	v_mov_b32_e32 v80, v146
	v_mov_b32_e32 v81, v147
	s_nop 0
	v_pk_add_f32 v[50:51], v[132:133], v[74:75]
	s_nop 0
	v_pk_mul_f32 v[50:51], v[50:51], v[80:81]
	v_mfma_f32_16x16x32_bf16 v[46:49], v[108:111], v[4:7], v[54:57]
	v_cvt_pk_bf16_f32 v91, v50, v51
	v_pk_add_f32 v[28:29], v[28:29], v[72:73]
	v_mfma_f32_16x16x32_bf16 v[82:85], v[112:115], v[4:7], v[58:61]
	v_mul_f32_e64 v28, v28, v78
	v_mul_f32_e64 v29, v29, v79
	v_cvt_pk_bf16_f32 v28, v28, v29
	v_mfma_f32_16x16x32_bf16 v[54:57], v[116:119], v[4:7], v[62:65]
	v_mfma_f32_16x16x32_bf16 v[36:39], v[120:123], v[4:7], v[66:69]
	v_mfma_f32_16x16x32_bf16 v[4:7], v[120:123], v[100:103], v[96:99]
	s_nop 2
	v_lshl_add_u32 v99, v44, 3, v94
	v_mov_b32_e32 v44, v148
	v_mov_b32_e32 v45, v149
	v_mov_b32_e32 v50, v152
	v_mov_b32_e32 v51, v153
	v_mov_b32_e32 v62, v148
	v_mov_b32_e32 v63, v149
	v_mov_b32_e32 v64, v150
	v_mov_b32_e32 v65, v151
	v_mov_b32_e32 v68, v152
	v_mov_b32_e32 v69, v153
	v_mov_b32_e32 v70, v154
	v_mov_b32_e32 v71, v155
	v_mfma_f32_16x16x32_bf16 v[8:11], v[116:119], v[100:103], v[86:89]
	v_lshl_add_u32 v100, v128, 3, v94
	v_lshl_add_u32 v97, v138, 3, v94
	v_lshl_add_u32 v98, v139, 3, v94
	v_lshlrev_b32_e32 v128, 4, v92
	s_nop 0
	v_pk_add_f32 v[44:45], v[134:135], v[44:45]
	s_nop 0
	v_pk_mul_f32 v[44:45], v[44:45], v[50:51]
	s_nop 0
	v_pk_add_f32 v[24:25], v[24:25], v[62:63]
	v_cvt_pk_bf16_f32 v88, v44, v45
	v_pk_add_f32 v[44:45], v[136:137], v[64:65]
	s_nop 0
	v_pk_mul_f32 v[24:25], v[24:25], v[68:69]
	v_pk_mul_f32 v[44:45], v[44:45], v[70:71]
	v_cvt_pk_bf16_f32 v24, v24, v25
	v_cvt_pk_bf16_f32 v89, v44, v45
	v_mov_b32_e32 v44, v156
	v_mov_b32_e32 v45, v157
	v_mov_b32_e32 v50, v160
	v_mov_b32_e32 v51, v161
	v_mov_b32_e32 v58, v156
	v_mov_b32_e32 v59, v157
	v_mov_b32_e32 v60, v158
	v_mov_b32_e32 v61, v159
	v_mov_b32_e32 v64, v160
	v_mov_b32_e32 v65, v161
	v_mov_b32_e32 v66, v162
	v_mov_b32_e32 v67, v163
	s_nop 0
	v_pk_add_f32 v[40:41], v[40:41], v[44:45]
	s_nop 0
	v_pk_mul_f32 v[40:41], v[40:41], v[50:51]
	s_nop 0
	v_pk_add_f32 v[20:21], v[20:21], v[58:59]
	v_cvt_pk_bf16_f32 v70, v40, v41
	v_pk_add_f32 v[40:41], v[42:43], v[60:61]
	s_nop 0
	v_pk_mul_f32 v[20:21], v[20:21], v[64:65]
	v_pk_mul_f32 v[40:41], v[40:41], v[66:67]
	v_cvt_pk_bf16_f32 v20, v20, v21
	v_cvt_pk_bf16_f32 v71, v40, v41
	v_mov_b32_e32 v40, v164
	v_mov_b32_e32 v41, v165
	v_mov_b32_e32 v42, v168
	v_mov_b32_e32 v43, v169
	s_nop 0
	v_pk_add_f32 v[40:41], v[46:47], v[40:41]
	s_nop 0
	v_pk_mul_f32 v[40:41], v[40:41], v[42:43]
	s_nop 0
	v_cvt_pk_bf16_f32 v60, v40, v41
	v_mov_b32_e32 v40, v164
	v_mov_b32_e32 v41, v165
	v_mov_b32_e32 v42, v166
	v_mov_b32_e32 v43, v167
	v_mov_b32_e32 v44, v168
	v_mov_b32_e32 v45, v169
	v_mov_b32_e32 v46, v170
	v_mov_b32_e32 v47, v171
	s_nop 0
	v_pk_add_f32 v[42:43], v[48:49], v[42:43]
	s_nop 0
	v_pk_mul_f32 v[42:43], v[42:43], v[46:47]
	v_pk_add_f32 v[16:17], v[16:17], v[40:41]
	v_cvt_pk_bf16_f32 v61, v42, v43
	v_mov_b32_e32 v42, v172
; __device__ __forceinline__ void pool_item(const Params& p, int l, int item) {
;     ...
;         const float* pb = p.pool_b + (l * 4 + g) * 128;
;         const float* ps = p.pool_scale + l * 512 + g * 128;
;         __syncthreads();
; #pragma unroll
;         for (int m = 0; m < 2; ++m)
; #pragma unroll
;             for (int n = 0; n < 8; ++n) {
;                 const int rl = wv * 32 + m * 16 + fr;
;                 const int col = n * 16 + fq * 4;
;                 float4 b4 = *reinterpret_cast<const float4*>(pb + col);
;                 float4 s4 = *reinterpret_cast<const float4*>(ps + col);
;                 f32x4 a = acc[m][n];
;                 uint2 o;
;                 o.x = pk2((a[0] + b4.x) * s4.x, (a[1] + b4.y) * s4.y);
;                 o.y = pk2((a[2] + b4.z) * s4.z, (a[3] + b4.w) * s4.w);
;                 *reinterpret_cast<uint2*>(lds + rl * 256 + ((((col >> 2)) ^ fr) << 3)) = o;
;             }
;     }
;     __syncthreads();
;     {
;         const int cg = tid & 15, rg = tid >> 4;
	v_mov_b32_e32 v43, v173
	v_mov_b32_e32 v46, v176
	v_mov_b32_e32 v47, v177
	v_pk_mul_f32 v[16:17], v[16:17], v[44:45]
	s_nop 0
	v_pk_add_f32 v[42:43], v[82:83], v[42:43]
	s_nop 0
	v_pk_mul_f32 v[42:43], v[42:43], v[46:47]
	v_mov_b32_e32 v46, v172
	v_mov_b32_e32 v47, v173
	v_mov_b32_e32 v48, v174
	v_mov_b32_e32 v49, v175
	v_mov_b32_e32 v50, v176
	v_mov_b32_e32 v51, v177
	v_mov_b32_e32 v52, v178
	v_mov_b32_e32 v53, v179
	v_cvt_pk_bf16_f32 v42, v42, v43
	v_cvt_pk_bf16_f32 v16, v16, v17
	s_nop 0
	v_pk_add_f32 v[48:49], v[84:85], v[48:49]
	s_nop 0
	v_pk_mul_f32 v[48:49], v[48:49], v[52:53]
	v_pk_add_f32 v[12:13], v[12:13], v[46:47]
	v_cvt_pk_bf16_f32 v43, v48, v49
	v_bitop3_b32 v48, v93, v92, 16 bitop3:0x36
	v_lshl_add_u32 v96, v48, 3, v94
	v_mov_b32_e32 v48, v180
	v_mov_b32_e32 v49, v181
	v_mov_b32_e32 v52, v184
	v_mov_b32_e32 v53, v185
	v_pk_mul_f32 v[12:13], v[12:13], v[50:51]
	s_nop 0
	v_pk_add_f32 v[48:49], v[54:55], v[48:49]
	s_nop 0
	v_pk_mul_f32 v[48:49], v[48:49], v[52:53]
	v_mov_b32_e32 v52, v180
	v_mov_b32_e32 v53, v181
	v_mov_b32_e32 v54, v182
	v_mov_b32_e32 v55, v183
	v_mov_b32_e32 v74, v184
	v_mov_b32_e32 v75, v185
	v_mov_b32_e32 v76, v186
	v_mov_b32_e32 v77, v187
	v_cvt_pk_bf16_f32 v48, v48, v49
	v_cvt_pk_bf16_f32 v12, v12, v13
	s_nop 0
	v_pk_add_f32 v[54:55], v[56:57], v[54:55]
	s_nop 0
	v_pk_mul_f32 v[54:55], v[54:55], v[76:77]
	v_pk_add_f32 v[8:9], v[8:9], v[52:53]
	v_cvt_pk_bf16_f32 v49, v54, v55
	v_bitop3_b32 v54, v93, v92, 20 bitop3:0x36
	v_lshl_add_u32 v76, v54, 3, v94
	v_mov_b32_e32 v54, v188
	v_mov_b32_e32 v55, v189
	v_mov_b32_e32 v56, v192
	v_mov_b32_e32 v57, v193
	v_pk_mul_f32 v[8:9], v[8:9], v[74:75]
	s_nop 0
	v_pk_add_f32 v[36:37], v[36:37], v[54:55]
	s_nop 0
	v_pk_mul_f32 v[36:37], v[36:37], v[56:57]
	v_mov_b32_e32 v54, v188
	v_mov_b32_e32 v55, v189
	v_mov_b32_e32 v56, v190
	v_mov_b32_e32 v57, v191
	v_mov_b32_e32 v84, v192
	v_mov_b32_e32 v85, v193
	v_mov_b32_e32 v86, v194
	v_mov_b32_e32 v87, v195
	v_cvt_pk_bf16_f32 v66, v36, v37
	v_cvt_pk_bf16_f32 v8, v8, v9
	s_nop 0
	v_pk_add_f32 v[36:37], v[38:39], v[56:57]
	s_nop 0
	v_pk_mul_f32 v[36:37], v[36:37], v[86:87]
	v_pk_add_f32 v[4:5], v[4:5], v[54:55]
	v_cvt_pk_bf16_f32 v67, v36, v37
	v_bitop3_b32 v36, v93, v92, 24 bitop3:0x36
	v_lshl_add_u32 v77, v36, 3, v94
	v_mov_b32_e32 v36, v196
	v_mov_b32_e32 v37, v197
	v_mov_b32_e32 v38, v200
	v_mov_b32_e32 v39, v201
	v_pk_mul_f32 v[4:5], v[4:5], v[84:85]
	s_nop 0
	v_pk_add_f32 v[32:33], v[32:33], v[36:37]
	s_nop 0
	v_pk_mul_f32 v[32:33], v[32:33], v[38:39]
	v_mov_b32_e32 v36, v196
	v_mov_b32_e32 v37, v197
	v_mov_b32_e32 v38, v198
	v_mov_b32_e32 v39, v199
	v_mov_b32_e32 v80, v200
	v_mov_b32_e32 v81, v201
	v_mov_b32_e32 v82, v202
	v_mov_b32_e32 v83, v203
	v_cvt_pk_bf16_f32 v4, v4, v5
	v_cvt_pk_bf16_f32 v32, v32, v33
	s_nop 0
	v_pk_add_f32 v[34:35], v[34:35], v[38:39]
	v_mov_b32_e32 v38, v142
	v_mov_b32_e32 v39, v143
	v_mov_b32_e32 v56, v146
	v_mov_b32_e32 v57, v147
	s_nop 0
	v_pk_mul_f32 v[34:35], v[34:35], v[82:83]
	v_pk_add_f32 v[0:1], v[0:1], v[36:37]
	v_cvt_pk_bf16_f32 v33, v34, v35
	v_bitop3_b32 v34, v93, v92, 28 bitop3:0x36
	v_pk_mul_f32 v[0:1], v[0:1], v[80:81]
	v_lshl_add_u32 v34, v34, 3, v94
	v_cvt_pk_bf16_f32 v0, v0, v1
	v_and_b32_e32 v36, 16, v214
	s_nop 0
	v_pk_add_f32 v[30:31], v[30:31], v[38:39]
	s_nop 0
	v_pk_mul_f32 v[30:31], v[30:31], v[56:57]
	s_nop 0
	v_cvt_pk_bf16_f32 v29, v30, v31
	ds_write2st64_b64 v99, v[90:91], v[28:29] offset1:8
	v_mov_b32_e32 v28, v150
	v_mov_b32_e32 v29, v151
	v_mov_b32_e32 v30, v154
	v_mov_b32_e32 v31, v155
	s_nop 0
	v_pk_add_f32 v[26:27], v[26:27], v[28:29]
	s_nop 0
	v_pk_mul_f32 v[26:27], v[26:27], v[30:31]
	s_nop 0
	v_cvt_pk_bf16_f32 v25, v26, v27
	ds_write2st64_b64 v100, v[88:89], v[24:25] offset1:8
	v_mov_b32_e32 v24, v158
	v_mov_b32_e32 v25, v159
	v_mov_b32_e32 v26, v162
	v_mov_b32_e32 v27, v163
	s_nop 0
	v_pk_add_f32 v[22:23], v[22:23], v[24:25]
	s_nop 0
	v_pk_mul_f32 v[22:23], v[22:23], v[26:27]
	s_nop 0
	v_cvt_pk_bf16_f32 v21, v22, v23
	ds_write2st64_b64 v97, v[70:71], v[20:21] offset1:8
	v_mov_b32_e32 v20, v166
	v_mov_b32_e32 v21, v167
	v_mov_b32_e32 v22, v170
	v_mov_b32_e32 v23, v171
	s_nop 0
	v_pk_add_f32 v[18:19], v[18:19], v[20:21]
	s_nop 0
	v_pk_mul_f32 v[18:19], v[18:19], v[22:23]
	s_nop 0
	v_cvt_pk_bf16_f32 v17, v18, v19
	ds_write2st64_b64 v98, v[60:61], v[16:17] offset1:8
	v_mov_b32_e32 v16, v174
	v_mov_b32_e32 v17, v175
	v_mov_b32_e32 v18, v178
	v_mov_b32_e32 v19, v179
	s_nop 0
	v_pk_add_f32 v[14:15], v[14:15], v[16:17]
	s_nop 0
	v_pk_mul_f32 v[14:15], v[14:15], v[18:19]
	s_nop 0
	v_cvt_pk_bf16_f32 v13, v14, v15
	ds_write2st64_b64 v96, v[42:43], v[12:13] offset1:8
	v_mov_b32_e32 v12, v182
	v_mov_b32_e32 v13, v183
	v_mov_b32_e32 v14, v186
	v_mov_b32_e32 v15, v187
	s_nop 0
	v_pk_add_f32 v[10:11], v[10:11], v[12:13]
	s_nop 0
	v_pk_mul_f32 v[10:11], v[10:11], v[14:15]
	s_nop 0
	v_cvt_pk_bf16_f32 v9, v10, v11
	ds_write2st64_b64 v76, v[48:49], v[8:9] offset1:8
	v_mov_b32_e32 v8, v190
	v_mov_b32_e32 v9, v191
	v_mov_b32_e32 v10, v194
	v_mov_b32_e32 v11, v195
	s_nop 0
	v_pk_add_f32 v[6:7], v[6:7], v[8:9]
	s_nop 0
	v_pk_mul_f32 v[6:7], v[6:7], v[10:11]
	s_nop 0
	v_cvt_pk_bf16_f32 v5, v6, v7
	ds_write2st64_b64 v77, v[66:67], v[4:5] offset1:8
	v_mov_b32_e32 v4, v198
	v_mov_b32_e32 v5, v199
	v_mov_b32_e32 v6, v202
	v_mov_b32_e32 v7, v203
	s_mov_b32 s0, 0x40000
	s_nop 0
	v_pk_add_f32 v[2:3], v[2:3], v[4:5]
	s_nop 0
	v_pk_mul_f32 v[2:3], v[2:3], v[6:7]
	s_nop 0
	v_cvt_pk_bf16_f32 v1, v2, v3
	ds_write2st64_b64 v34, v[32:33], v[0:1] offset1:8
	v_ashrrev_i32_e32 v34, 4, v214
	v_add_u32_e32 v0, s6, v34
	v_ashrrev_i32_e32 v1, 31, v0
	v_lshlrev_b64 v[0:1], 13, v[0:1]
	v_lshl_add_u64 v[0:1], s[78:79], 0, v[0:1]
	v_lshl_add_u64 v[0:1], v[0:1], 0, s[72:73]
	v_lshl_add_u64 v[0:1], v[0:1], 0, v[128:129]
	s_waitcnt lgkmcnt(0)
	s_barrier
; __device__ __forceinline__ float siluf_(float x) { return x * sigmoidf_(x); }
; __device__ __forceinline__ void pool_item(const Params& p, int l, int item) {
;     ...
;     {
;         const int cg = tid & 15, rg = tid >> 4;
;         uint4 gv[8];
; #pragma unroll
;         for (int k = 0; k < 8; ++k) gv[k] = ld_nt_u4(P1 + (long)(r0 + rg + 32 * k) * P1W + 512 + g * 128 + cg * 8);
; #pragma unroll
;         for (int k = 0; k < 8; ++k) {
;             const int rl = rg + 32 * k, ksw = rl & 15;
;             uint4 v = *reinterpret_cast<const uint4*>(lds + rl * 256 + ((cg ^ (ksw >> 1)) << 4));
;             if (ksw & 1) v = make_uint4(v.z, v.w, v.x, v.y);
;             uint4 o;
;             o.x = pk2(bflo(v.x) * siluf_(bflo(gv[k].x)), bfhi(v.x) * siluf_(bfhi(gv[k].x)));
;             o.y = pk2(bflo(v.y) * siluf_(bflo(gv[k].y)), bfhi(v.y) * siluf_(bfhi(gv[k].y)));
;             o.z = pk2(bflo(v.z) * siluf_(bflo(gv[k].z)), bfhi(v.z) * siluf_(bfhi(gv[k].z)));
;             o.w = pk2(bflo(v.w) * siluf_(bflo(gv[k].w)), bfhi(v.w) * siluf_(bfhi(gv[k].w)));
;             st16_wt(P1 + (long)(r0 + rl) * P1W + 512 + g * 128 + cg * 8, o);
;         }
	global_load_dwordx4 v[28:31], v[0:1], off offset:1024 nt
	v_add_co_u32_e32 v2, vcc, s0, v0
	s_mov_b32 s0, 0xc0000
	s_nop 0
	v_addc_co_u32_e32 v3, vcc, 0, v1, vcc
	global_load_dwordx4 v[24:27], v[2:3], off offset:1024 nt
	v_add_co_u32_e32 v2, vcc, s69, v0
	v_lshrrev_b32_e32 v35, 1, v34
	s_nop 0
	v_addc_co_u32_e32 v3, vcc, 0, v1, vcc
	global_load_dwordx4 v[20:23], v[2:3], off offset:1024 nt
	v_add_co_u32_e32 v2, vcc, s0, v0
	s_mov_b32 s0, 0x100000
	s_nop 0
	v_addc_co_u32_e32 v3, vcc, 0, v1, vcc
	global_load_dwordx4 v[16:19], v[2:3], off offset:1024 nt
	v_add_co_u32_e32 v2, vcc, s0, v0
	s_mov_b32 s0, 0x140000
	s_nop 0
	v_addc_co_u32_e32 v3, vcc, 0, v1, vcc
	global_load_dwordx4 v[12:15], v[2:3], off offset:1024 nt
	v_add_co_u32_e32 v2, vcc, s0, v0
	s_mov_b32 s0, 0x180000
	s_nop 0
	v_addc_co_u32_e32 v3, vcc, 0, v1, vcc
	global_load_dwordx4 v[8:11], v[2:3], off offset:1024 nt
	v_add_co_u32_e32 v2, vcc, s0, v0
	s_mov_b32 s0, 0x1c0000
	s_nop 0
	v_addc_co_u32_e32 v3, vcc, 0, v1, vcc
	v_lshl_add_u64 v[32:33], v[0:1], 0, s[48:49]
	v_add_co_u32_e32 v0, vcc, s0, v0
	v_bitop3_b32 v35, v35, v92, 7 bitop3:0x6c
	s_nop 0
	v_addc_co_u32_e32 v1, vcc, 0, v1, vcc
	v_lshl_add_u32 v35, v35, 4, 0
	v_cmp_eq_u32_e32 vcc, 0, v36
	v_lshl_add_u32 v36, v34, 8, v35
	ds_read_b128 v[36:39], v36
	global_load_dwordx4 v[4:7], v[2:3], off offset:1024 nt
	v_readlane_b32 s0, v234, 38
	global_load_dwordx4 v[0:3], v[0:1], off offset:1024 nt
	s_add_i32 s11, s11, s0
	s_waitcnt lgkmcnt(0)
	v_cndmask_b32_e32 v40, v38, v36, vcc
	v_cndmask_b32_e32 v44, v36, v38, vcc
	v_cndmask_b32_e32 v42, v39, v37, vcc
	v_cndmask_b32_e32 v43, v37, v39, vcc
	v_lshlrev_b32_e32 v36, 16, v40
	v_and_b32_e32 v37, 0xffff0000, v40
	s_cmpk_gt_i32 s11, 0xff
	s_waitcnt vmcnt(7)
	v_lshlrev_b32_e32 v38, 16, v28
	v_and_b32_e32 v39, 0xffff0000, v28
	v_mul_f32_e32 v28, 0xbfb8aa3b, v38
	v_exp_f32_e32 v28, v28
	s_nop 0
	v_add_f32_e32 v28, 1.0, v28
	v_rcp_f32_e32 v40, v28
	v_mul_f32_e32 v28, 0xbfb8aa3b, v39
	v_exp_f32_e32 v28, v28
	s_nop 0
	v_add_f32_e32 v28, 1.0, v28
	v_rcp_f32_e32 v41, v28
	s_nop 0
	v_pk_mul_f32 v[38:39], v[40:41], v[38:39]
	s_nop 0
	v_pk_mul_f32 v[36:37], v[38:39], v[36:37]
	v_lshlrev_b32_e32 v38, 16, v29
	v_and_b32_e32 v39, 0xffff0000, v29
	v_mul_f32_e32 v29, 0xbfb8aa3b, v38
	v_exp_f32_e32 v29, v29
	v_cvt_pk_bf16_f32 v28, v36, v37
	v_lshlrev_b32_e32 v36, 16, v42
	v_and_b32_e32 v37, 0xffff0000, v42
	v_add_f32_e32 v29, 1.0, v29
	v_rcp_f32_e32 v40, v29
	v_mul_f32_e32 v29, 0xbfb8aa3b, v39
	v_exp_f32_e32 v29, v29
	s_nop 0
	v_add_f32_e32 v29, 1.0, v29
	v_rcp_f32_e32 v41, v29
	s_nop 0
	v_pk_mul_f32 v[38:39], v[40:41], v[38:39]
	s_nop 0
	v_pk_mul_f32 v[36:37], v[38:39], v[36:37]
	v_lshlrev_b32_e32 v40, 16, v44
	v_cvt_pk_bf16_f32 v29, v36, v37
	v_lshlrev_b32_e32 v36, 16, v30
	v_and_b32_e32 v37, 0xffff0000, v30
	v_mul_f32_e32 v30, 0xbfb8aa3b, v36
	v_exp_f32_e32 v30, v30
	v_and_b32_e32 v41, 0xffff0000, v44
	v_add_f32_e32 v30, 1.0, v30
	v_rcp_f32_e32 v38, v30
	v_mul_f32_e32 v30, 0xbfb8aa3b, v37
	v_exp_f32_e32 v30, v30
	s_nop 0
	v_add_f32_e32 v30, 1.0, v30
	v_rcp_f32_e32 v39, v30
	s_nop 0
	v_pk_mul_f32 v[36:37], v[38:39], v[36:37]
	s_nop 0
	v_pk_mul_f32 v[36:37], v[36:37], v[40:41]
	v_lshlrev_b32_e32 v40, 16, v43
	v_cvt_pk_bf16_f32 v30, v36, v37
	v_lshlrev_b32_e32 v36, 16, v31
	v_and_b32_e32 v37, 0xffff0000, v31
	v_mul_f32_e32 v31, 0xbfb8aa3b, v36
	v_exp_f32_e32 v31, v31
	v_and_b32_e32 v41, 0xffff0000, v43
	v_add_f32_e32 v31, 1.0, v31
	v_rcp_f32_e32 v38, v31
	v_mul_f32_e32 v31, 0xbfb8aa3b, v37
	v_exp_f32_e32 v31, v31
	s_nop 0
	v_add_f32_e32 v31, 1.0, v31
	v_rcp_f32_e32 v39, v31
	s_nop 0
	v_pk_mul_f32 v[36:37], v[38:39], v[36:37]
	s_nop 0
	v_pk_mul_f32 v[36:37], v[36:37], v[40:41]
	s_nop 0
	v_cvt_pk_bf16_f32 v31, v36, v37
	v_add_u32_e32 v36, 32, v34
	global_store_dwordx4 v[32:33], v[28:31], off sc1
	s_nop 1
	v_lshl_add_u32 v28, v36, 8, v35
	ds_read_b128 v[28:31], v28
	s_waitcnt lgkmcnt(0)
	v_cndmask_b32_e32 v32, v30, v28, vcc
	v_cndmask_b32_e32 v39, v28, v30, vcc
	s_waitcnt vmcnt(6)
	v_lshlrev_b32_e32 v30, 16, v24
	v_cndmask_b32_e32 v37, v31, v29, vcc
	v_cndmask_b32_e32 v38, v29, v31, vcc
	v_and_b32_e32 v31, 0xffff0000, v24
	v_mul_f32_e32 v24, 0xbfb8aa3b, v30
	v_exp_f32_e32 v24, v24
	v_lshlrev_b32_e32 v28, 16, v32
	v_and_b32_e32 v29, 0xffff0000, v32
	v_add_f32_e32 v24, 1.0, v24
	v_rcp_f32_e32 v32, v24
	v_mul_f32_e32 v24, 0xbfb8aa3b, v31
	v_exp_f32_e32 v24, v24
	s_nop 0
	v_add_f32_e32 v24, 1.0, v24
	v_rcp_f32_e32 v33, v24
	s_nop 0
	v_pk_mul_f32 v[30:31], v[32:33], v[30:31]
	s_nop 0
	v_pk_mul_f32 v[28:29], v[30:31], v[28:29]
	v_lshlrev_b32_e32 v30, 16, v25
	v_and_b32_e32 v31, 0xffff0000, v25
	v_mul_f32_e32 v25, 0xbfb8aa3b, v30
	v_exp_f32_e32 v25, v25
	v_cvt_pk_bf16_f32 v24, v28, v29
	v_lshlrev_b32_e32 v28, 16, v37
	v_and_b32_e32 v29, 0xffff0000, v37
	v_add_f32_e32 v25, 1.0, v25
	v_rcp_f32_e32 v32, v25
	v_mul_f32_e32 v25, 0xbfb8aa3b, v31
	v_exp_f32_e32 v25, v25
	s_nop 0
	v_add_f32_e32 v25, 1.0, v25
	v_rcp_f32_e32 v33, v25
	s_nop 0
	v_pk_mul_f32 v[30:31], v[32:33], v[30:31]
	s_nop 0
	v_pk_mul_f32 v[28:29], v[30:31], v[28:29]
	v_lshlrev_b32_e32 v32, 16, v39
	v_cvt_pk_bf16_f32 v25, v28, v29
	v_lshlrev_b32_e32 v28, 16, v26
	v_and_b32_e32 v29, 0xffff0000, v26
	v_mul_f32_e32 v26, 0xbfb8aa3b, v28
	v_exp_f32_e32 v26, v26
	v_and_b32_e32 v33, 0xffff0000, v39
	v_add_f32_e32 v26, 1.0, v26
	v_rcp_f32_e32 v30, v26
	v_mul_f32_e32 v26, 0xbfb8aa3b, v29
	v_exp_f32_e32 v26, v26
	s_nop 0
	v_add_f32_e32 v26, 1.0, v26
	v_rcp_f32_e32 v31, v26
	s_nop 0
	v_pk_mul_f32 v[28:29], v[30:31], v[28:29]
	s_nop 0
	v_pk_mul_f32 v[28:29], v[28:29], v[32:33]
	v_lshlrev_b32_e32 v32, 16, v38
	v_cvt_pk_bf16_f32 v26, v28, v29
	v_lshlrev_b32_e32 v28, 16, v27
	v_and_b32_e32 v29, 0xffff0000, v27
	v_mul_f32_e32 v27, 0xbfb8aa3b, v28
	v_exp_f32_e32 v27, v27
	v_and_b32_e32 v33, 0xffff0000, v38
	v_add_f32_e32 v27, 1.0, v27
	v_rcp_f32_e32 v30, v27
	v_mul_f32_e32 v27, 0xbfb8aa3b, v29
	v_exp_f32_e32 v27, v27
	s_nop 0
	v_add_f32_e32 v27, 1.0, v27
	v_rcp_f32_e32 v31, v27
	s_nop 0
	v_pk_mul_f32 v[28:29], v[30:31], v[28:29]
	s_nop 0
	v_pk_mul_f32 v[28:29], v[28:29], v[32:33]
	v_add_u32_e32 v30, 64, v34
	v_cvt_pk_bf16_f32 v27, v28, v29
	v_add_u32_e32 v28, s6, v36
	v_ashrrev_i32_e32 v29, 31, v28
	v_lshlrev_b64 v[28:29], 13, v[28:29]
	v_lshl_add_u64 v[28:29], s[78:79], 0, v[28:29]
	v_lshl_add_u64 v[28:29], v[28:29], 0, s[72:73]
	v_lshl_add_u64 v[28:29], v[28:29], 0, v[128:129]
	v_lshl_add_u64 v[28:29], v[28:29], 0, s[48:49]
	global_store_dwordx4 v[28:29], v[24:27], off sc1
	s_nop 1
	v_lshl_add_u32 v24, v30, 8, v35
	ds_read_b128 v[24:27], v24
	s_waitcnt lgkmcnt(0)
; __device__ __forceinline__ float siluf_(float x) { return x * sigmoidf_(x); }
; __device__ __forceinline__ void pool_item(const Params& p, int l, int item) {
;     ...
; #pragma unroll
;         for (int k = 0; k < 8; ++k) {
;             const int rl = rg + 32 * k, ksw = rl & 15;
;             uint4 v = *reinterpret_cast<const uint4*>(lds + rl * 256 + ((cg ^ (ksw >> 1)) << 4));
;             if (ksw & 1) v = make_uint4(v.z, v.w, v.x, v.y);
;             uint4 o;
;             o.x = pk2(bflo(v.x) * siluf_(bflo(gv[k].x)), bfhi(v.x) * siluf_(bfhi(gv[k].x)));
;             o.y = pk2(bflo(v.y) * siluf_(bflo(gv[k].y)), bfhi(v.y) * siluf_(bfhi(gv[k].y)));
;             o.z = pk2(bflo(v.z) * siluf_(bflo(gv[k].z)), bfhi(v.z) * siluf_(bfhi(gv[k].z)));
;             o.w = pk2(bflo(v.w) * siluf_(bflo(gv[k].w)), bfhi(v.w) * siluf_(bfhi(gv[k].w)));
;             st16_wt(P1 + (long)(r0 + rl) * P1W + 512 + g * 128 + cg * 8, o);
;         }
	v_cndmask_b32_e32 v28, v26, v24, vcc
	v_cndmask_b32_e32 v33, v24, v26, vcc
	s_waitcnt vmcnt(5)
	v_lshlrev_b32_e32 v26, 16, v20
	v_cndmask_b32_e32 v31, v27, v25, vcc
	v_cndmask_b32_e32 v32, v25, v27, vcc
	v_and_b32_e32 v27, 0xffff0000, v20
	v_mul_f32_e32 v20, 0xbfb8aa3b, v26
	v_exp_f32_e32 v20, v20
	v_lshlrev_b32_e32 v24, 16, v28
	v_and_b32_e32 v25, 0xffff0000, v28
	v_add_f32_e32 v20, 1.0, v20
	v_rcp_f32_e32 v28, v20
	v_mul_f32_e32 v20, 0xbfb8aa3b, v27
	v_exp_f32_e32 v20, v20
	s_nop 0
	v_add_f32_e32 v20, 1.0, v20
	v_rcp_f32_e32 v29, v20
	s_nop 0
	v_pk_mul_f32 v[26:27], v[28:29], v[26:27]
	s_nop 0
	v_pk_mul_f32 v[24:25], v[26:27], v[24:25]
	v_lshlrev_b32_e32 v26, 16, v21
	v_and_b32_e32 v27, 0xffff0000, v21
	v_mul_f32_e32 v21, 0xbfb8aa3b, v26
	v_exp_f32_e32 v21, v21
	v_cvt_pk_bf16_f32 v20, v24, v25
	v_lshlrev_b32_e32 v24, 16, v31
	v_and_b32_e32 v25, 0xffff0000, v31
	v_add_f32_e32 v21, 1.0, v21
	v_rcp_f32_e32 v28, v21
	v_mul_f32_e32 v21, 0xbfb8aa3b, v27
	v_exp_f32_e32 v21, v21
	s_nop 0
	v_add_f32_e32 v21, 1.0, v21
	v_rcp_f32_e32 v29, v21
	s_nop 0
	v_pk_mul_f32 v[26:27], v[28:29], v[26:27]
	s_nop 0
	v_pk_mul_f32 v[24:25], v[26:27], v[24:25]
	v_lshlrev_b32_e32 v28, 16, v33
	v_cvt_pk_bf16_f32 v21, v24, v25
	v_lshlrev_b32_e32 v24, 16, v22
	v_and_b32_e32 v25, 0xffff0000, v22
	v_mul_f32_e32 v22, 0xbfb8aa3b, v24
	v_exp_f32_e32 v22, v22
	v_and_b32_e32 v29, 0xffff0000, v33
	v_add_f32_e32 v22, 1.0, v22
	v_rcp_f32_e32 v26, v22
	v_mul_f32_e32 v22, 0xbfb8aa3b, v25
	v_exp_f32_e32 v22, v22
	s_nop 0
	v_add_f32_e32 v22, 1.0, v22
	v_rcp_f32_e32 v27, v22
	s_nop 0
	v_pk_mul_f32 v[24:25], v[26:27], v[24:25]
	s_nop 0
	v_pk_mul_f32 v[24:25], v[24:25], v[28:29]
	v_lshlrev_b32_e32 v28, 16, v32
	v_cvt_pk_bf16_f32 v22, v24, v25
	v_lshlrev_b32_e32 v24, 16, v23
	v_and_b32_e32 v25, 0xffff0000, v23
	v_mul_f32_e32 v23, 0xbfb8aa3b, v24
	v_exp_f32_e32 v23, v23
	v_and_b32_e32 v29, 0xffff0000, v32
	v_add_f32_e32 v23, 1.0, v23
	v_rcp_f32_e32 v26, v23
	v_mul_f32_e32 v23, 0xbfb8aa3b, v25
	v_exp_f32_e32 v23, v23
	s_nop 0
	v_add_f32_e32 v23, 1.0, v23
	v_rcp_f32_e32 v27, v23
	s_nop 0
	v_pk_mul_f32 v[24:25], v[26:27], v[24:25]
	s_nop 0
	v_pk_mul_f32 v[24:25], v[24:25], v[28:29]
	v_add_u32_e32 v26, 0x60, v34
	v_cvt_pk_bf16_f32 v23, v24, v25
	v_add_u32_e32 v24, s6, v30
	v_ashrrev_i32_e32 v25, 31, v24
	v_lshlrev_b64 v[24:25], 13, v[24:25]
	v_lshl_add_u64 v[24:25], s[78:79], 0, v[24:25]
	v_lshl_add_u64 v[24:25], v[24:25], 0, s[72:73]
	v_lshl_add_u64 v[24:25], v[24:25], 0, v[128:129]
	v_lshl_add_u64 v[24:25], v[24:25], 0, s[48:49]
	global_store_dwordx4 v[24:25], v[20:23], off sc1
	s_nop 1
	v_lshl_add_u32 v20, v26, 8, v35
	ds_read_b128 v[20:23], v20
	s_waitcnt lgkmcnt(0)
	v_cndmask_b32_e32 v24, v22, v20, vcc
	v_cndmask_b32_e32 v29, v20, v22, vcc
	s_waitcnt vmcnt(4)
	v_lshlrev_b32_e32 v22, 16, v16
	v_cndmask_b32_e32 v27, v23, v21, vcc
	v_cndmask_b32_e32 v28, v21, v23, vcc
	v_and_b32_e32 v23, 0xffff0000, v16
	v_mul_f32_e32 v16, 0xbfb8aa3b, v22
	v_exp_f32_e32 v16, v16
	v_lshlrev_b32_e32 v20, 16, v24
	v_and_b32_e32 v21, 0xffff0000, v24
	v_add_f32_e32 v16, 1.0, v16
	v_rcp_f32_e32 v24, v16
	v_mul_f32_e32 v16, 0xbfb8aa3b, v23
	v_exp_f32_e32 v16, v16
	s_nop 0
	v_add_f32_e32 v16, 1.0, v16
	v_rcp_f32_e32 v25, v16
	s_nop 0
	v_pk_mul_f32 v[22:23], v[24:25], v[22:23]
	s_nop 0
	v_pk_mul_f32 v[20:21], v[22:23], v[20:21]
	v_lshlrev_b32_e32 v22, 16, v17
	v_and_b32_e32 v23, 0xffff0000, v17
	v_mul_f32_e32 v17, 0xbfb8aa3b, v22
	v_exp_f32_e32 v17, v17
	v_cvt_pk_bf16_f32 v16, v20, v21
	v_lshlrev_b32_e32 v20, 16, v27
	v_and_b32_e32 v21, 0xffff0000, v27
	v_add_f32_e32 v17, 1.0, v17
	v_rcp_f32_e32 v24, v17
	v_mul_f32_e32 v17, 0xbfb8aa3b, v23
	v_exp_f32_e32 v17, v17
	s_nop 0
	v_add_f32_e32 v17, 1.0, v17
	v_rcp_f32_e32 v25, v17
	s_nop 0
	v_pk_mul_f32 v[22:23], v[24:25], v[22:23]
	s_nop 0
	v_pk_mul_f32 v[20:21], v[22:23], v[20:21]
	v_lshlrev_b32_e32 v24, 16, v29
	v_cvt_pk_bf16_f32 v17, v20, v21
	v_lshlrev_b32_e32 v20, 16, v18
	v_and_b32_e32 v21, 0xffff0000, v18
	v_mul_f32_e32 v18, 0xbfb8aa3b, v20
	v_exp_f32_e32 v18, v18
	v_and_b32_e32 v25, 0xffff0000, v29
	v_add_f32_e32 v18, 1.0, v18
	v_rcp_f32_e32 v22, v18
	v_mul_f32_e32 v18, 0xbfb8aa3b, v21
	v_exp_f32_e32 v18, v18
	s_nop 0
	v_add_f32_e32 v18, 1.0, v18
	v_rcp_f32_e32 v23, v18
	s_nop 0
	v_pk_mul_f32 v[20:21], v[22:23], v[20:21]
	s_nop 0
	v_pk_mul_f32 v[20:21], v[20:21], v[24:25]
	v_lshlrev_b32_e32 v24, 16, v28
	v_cvt_pk_bf16_f32 v18, v20, v21
	v_lshlrev_b32_e32 v20, 16, v19
	v_and_b32_e32 v21, 0xffff0000, v19
	v_mul_f32_e32 v19, 0xbfb8aa3b, v20
	v_exp_f32_e32 v19, v19
	v_and_b32_e32 v25, 0xffff0000, v28
	v_add_f32_e32 v19, 1.0, v19
	v_rcp_f32_e32 v22, v19
	v_mul_f32_e32 v19, 0xbfb8aa3b, v21
	v_exp_f32_e32 v19, v19
	s_nop 0
	v_add_f32_e32 v19, 1.0, v19
	v_rcp_f32_e32 v23, v19
	s_nop 0
	v_pk_mul_f32 v[20:21], v[22:23], v[20:21]
	s_nop 0
	v_pk_mul_f32 v[20:21], v[20:21], v[24:25]
	v_add_u32_e32 v22, 0x80, v34
	v_cvt_pk_bf16_f32 v19, v20, v21
	v_add_u32_e32 v20, s6, v26
	v_ashrrev_i32_e32 v21, 31, v20
	v_lshlrev_b64 v[20:21], 13, v[20:21]
	v_lshl_add_u64 v[20:21], s[78:79], 0, v[20:21]
	v_lshl_add_u64 v[20:21], v[20:21], 0, s[72:73]
	v_lshl_add_u64 v[20:21], v[20:21], 0, v[128:129]
	v_lshl_add_u64 v[20:21], v[20:21], 0, s[48:49]
	global_store_dwordx4 v[20:21], v[16:19], off sc1
	s_nop 1
	v_lshl_add_u32 v16, v22, 8, v35
	ds_read_b128 v[16:19], v16
	s_waitcnt lgkmcnt(0)
	v_cndmask_b32_e32 v20, v18, v16, vcc
	v_cndmask_b32_e32 v25, v16, v18, vcc
	s_waitcnt vmcnt(3)
; __device__ __forceinline__ float siluf_(float x) { return x * sigmoidf_(x); }
; __device__ __forceinline__ void pool_item(const Params& p, int l, int item) {
;     ...
; #pragma unroll
;         for (int k = 0; k < 8; ++k) {
;             const int rl = rg + 32 * k, ksw = rl & 15;
;             uint4 v = *reinterpret_cast<const uint4*>(lds + rl * 256 + ((cg ^ (ksw >> 1)) << 4));
;             if (ksw & 1) v = make_uint4(v.z, v.w, v.x, v.y);
;             uint4 o;
;             o.x = pk2(bflo(v.x) * siluf_(bflo(gv[k].x)), bfhi(v.x) * siluf_(bfhi(gv[k].x)));
;             o.y = pk2(bflo(v.y) * siluf_(bflo(gv[k].y)), bfhi(v.y) * siluf_(bfhi(gv[k].y)));
;             o.z = pk2(bflo(v.z) * siluf_(bflo(gv[k].z)), bfhi(v.z) * siluf_(bfhi(gv[k].z)));
;             o.w = pk2(bflo(v.w) * siluf_(bflo(gv[k].w)), bfhi(v.w) * siluf_(bfhi(gv[k].w)));
;             st16_wt(P1 + (long)(r0 + rl) * P1W + 512 + g * 128 + cg * 8, o);
;         }
	v_lshlrev_b32_e32 v18, 16, v12
	v_cndmask_b32_e32 v23, v19, v17, vcc
	v_cndmask_b32_e32 v24, v17, v19, vcc
	v_and_b32_e32 v19, 0xffff0000, v12
	v_mul_f32_e32 v12, 0xbfb8aa3b, v18
	v_exp_f32_e32 v12, v12
	v_lshlrev_b32_e32 v16, 16, v20
	v_and_b32_e32 v17, 0xffff0000, v20
	v_add_f32_e32 v12, 1.0, v12
	v_rcp_f32_e32 v20, v12
	v_mul_f32_e32 v12, 0xbfb8aa3b, v19
	v_exp_f32_e32 v12, v12
	s_nop 0
	v_add_f32_e32 v12, 1.0, v12
	v_rcp_f32_e32 v21, v12
	s_nop 0
	v_pk_mul_f32 v[18:19], v[20:21], v[18:19]
	s_nop 0
	v_pk_mul_f32 v[16:17], v[18:19], v[16:17]
	v_lshlrev_b32_e32 v18, 16, v13
	v_and_b32_e32 v19, 0xffff0000, v13
	v_mul_f32_e32 v13, 0xbfb8aa3b, v18
	v_exp_f32_e32 v13, v13
	v_cvt_pk_bf16_f32 v12, v16, v17
	v_lshlrev_b32_e32 v16, 16, v23
	v_and_b32_e32 v17, 0xffff0000, v23
	v_add_f32_e32 v13, 1.0, v13
	v_rcp_f32_e32 v20, v13
	v_mul_f32_e32 v13, 0xbfb8aa3b, v19
	v_exp_f32_e32 v13, v13
	s_nop 0
	v_add_f32_e32 v13, 1.0, v13
	v_rcp_f32_e32 v21, v13
	s_nop 0
	v_pk_mul_f32 v[18:19], v[20:21], v[18:19]
	s_nop 0
	v_pk_mul_f32 v[16:17], v[18:19], v[16:17]
	v_lshlrev_b32_e32 v20, 16, v25
	v_cvt_pk_bf16_f32 v13, v16, v17
	v_lshlrev_b32_e32 v16, 16, v14
	v_and_b32_e32 v17, 0xffff0000, v14
	v_mul_f32_e32 v14, 0xbfb8aa3b, v16
	v_exp_f32_e32 v14, v14
	v_and_b32_e32 v21, 0xffff0000, v25
	v_add_f32_e32 v14, 1.0, v14
	v_rcp_f32_e32 v18, v14
	v_mul_f32_e32 v14, 0xbfb8aa3b, v17
	v_exp_f32_e32 v14, v14
	s_nop 0
	v_add_f32_e32 v14, 1.0, v14
	v_rcp_f32_e32 v19, v14
	s_nop 0
	v_pk_mul_f32 v[16:17], v[18:19], v[16:17]
	s_nop 0
	v_pk_mul_f32 v[16:17], v[16:17], v[20:21]
	v_lshlrev_b32_e32 v20, 16, v24
	v_cvt_pk_bf16_f32 v14, v16, v17
	v_lshlrev_b32_e32 v16, 16, v15
	v_and_b32_e32 v17, 0xffff0000, v15
	v_mul_f32_e32 v15, 0xbfb8aa3b, v16
	v_exp_f32_e32 v15, v15
	v_and_b32_e32 v21, 0xffff0000, v24
	v_add_f32_e32 v15, 1.0, v15
	v_rcp_f32_e32 v18, v15
	v_mul_f32_e32 v15, 0xbfb8aa3b, v17
	v_exp_f32_e32 v15, v15
	s_nop 0
	v_add_f32_e32 v15, 1.0, v15
	v_rcp_f32_e32 v19, v15
	s_nop 0
	v_pk_mul_f32 v[16:17], v[18:19], v[16:17]
	s_nop 0
	v_pk_mul_f32 v[16:17], v[16:17], v[20:21]
	v_add_u32_e32 v18, 0xa0, v34
	v_cvt_pk_bf16_f32 v15, v16, v17
	v_add_u32_e32 v16, s6, v22
	v_ashrrev_i32_e32 v17, 31, v16
	v_lshlrev_b64 v[16:17], 13, v[16:17]
	v_lshl_add_u64 v[16:17], s[78:79], 0, v[16:17]
	v_lshl_add_u64 v[16:17], v[16:17], 0, s[72:73]
	v_lshl_add_u64 v[16:17], v[16:17], 0, v[128:129]
	v_lshl_add_u64 v[16:17], v[16:17], 0, s[48:49]
	global_store_dwordx4 v[16:17], v[12:15], off sc1
	s_nop 1
	v_lshl_add_u32 v12, v18, 8, v35
	ds_read_b128 v[12:15], v12
	s_waitcnt lgkmcnt(0)
	v_cndmask_b32_e32 v16, v14, v12, vcc
	v_cndmask_b32_e32 v21, v12, v14, vcc
	s_waitcnt vmcnt(2)
	v_lshlrev_b32_e32 v14, 16, v8
	v_cndmask_b32_e32 v19, v15, v13, vcc
	v_cndmask_b32_e32 v20, v13, v15, vcc
	v_and_b32_e32 v15, 0xffff0000, v8
	v_mul_f32_e32 v8, 0xbfb8aa3b, v14
	v_exp_f32_e32 v8, v8
	v_lshlrev_b32_e32 v12, 16, v16
	v_and_b32_e32 v13, 0xffff0000, v16
	v_add_f32_e32 v8, 1.0, v8
	v_rcp_f32_e32 v16, v8
	v_mul_f32_e32 v8, 0xbfb8aa3b, v15
	v_exp_f32_e32 v8, v8
	s_nop 0
	v_add_f32_e32 v8, 1.0, v8
	v_rcp_f32_e32 v17, v8
	s_nop 0
	v_pk_mul_f32 v[14:15], v[16:17], v[14:15]
	s_nop 0
	v_pk_mul_f32 v[12:13], v[14:15], v[12:13]
	v_lshlrev_b32_e32 v14, 16, v9
	v_and_b32_e32 v15, 0xffff0000, v9
	v_mul_f32_e32 v9, 0xbfb8aa3b, v14
	v_exp_f32_e32 v9, v9
	v_cvt_pk_bf16_f32 v8, v12, v13
	v_lshlrev_b32_e32 v12, 16, v19
	v_and_b32_e32 v13, 0xffff0000, v19
	v_add_f32_e32 v9, 1.0, v9
	v_rcp_f32_e32 v16, v9
	v_mul_f32_e32 v9, 0xbfb8aa3b, v15
	v_exp_f32_e32 v9, v9
	s_nop 0
	v_add_f32_e32 v9, 1.0, v9
	v_rcp_f32_e32 v17, v9
	s_nop 0
	v_pk_mul_f32 v[14:15], v[16:17], v[14:15]
	s_nop 0
	v_pk_mul_f32 v[12:13], v[14:15], v[12:13]
	v_lshlrev_b32_e32 v16, 16, v21
	v_cvt_pk_bf16_f32 v9, v12, v13
	v_lshlrev_b32_e32 v12, 16, v10
	v_and_b32_e32 v13, 0xffff0000, v10
	v_mul_f32_e32 v10, 0xbfb8aa3b, v12
	v_exp_f32_e32 v10, v10
	v_and_b32_e32 v17, 0xffff0000, v21
	v_add_f32_e32 v10, 1.0, v10
	v_rcp_f32_e32 v14, v10
	v_mul_f32_e32 v10, 0xbfb8aa3b, v13
	v_exp_f32_e32 v10, v10
	s_nop 0
	v_add_f32_e32 v10, 1.0, v10
	v_rcp_f32_e32 v15, v10
	s_nop 0
	v_pk_mul_f32 v[12:13], v[14:15], v[12:13]
	s_nop 0
	v_pk_mul_f32 v[12:13], v[12:13], v[16:17]
	v_lshlrev_b32_e32 v16, 16, v20
	v_cvt_pk_bf16_f32 v10, v12, v13
	v_lshlrev_b32_e32 v12, 16, v11
	v_and_b32_e32 v13, 0xffff0000, v11
	v_mul_f32_e32 v11, 0xbfb8aa3b, v12
	v_exp_f32_e32 v11, v11
	v_and_b32_e32 v17, 0xffff0000, v20
	v_add_f32_e32 v11, 1.0, v11
	v_rcp_f32_e32 v14, v11
	v_mul_f32_e32 v11, 0xbfb8aa3b, v13
	v_exp_f32_e32 v11, v11
	s_nop 0
	v_add_f32_e32 v11, 1.0, v11
	v_rcp_f32_e32 v15, v11
	s_nop 0
	v_pk_mul_f32 v[12:13], v[14:15], v[12:13]
	s_nop 0
	v_pk_mul_f32 v[12:13], v[12:13], v[16:17]
	v_add_u32_e32 v14, 0xc0, v34
	v_cvt_pk_bf16_f32 v11, v12, v13
	v_add_u32_e32 v12, s6, v18
	v_ashrrev_i32_e32 v13, 31, v12
	v_lshlrev_b64 v[12:13], 13, v[12:13]
	v_lshl_add_u64 v[12:13], s[78:79], 0, v[12:13]
	v_lshl_add_u64 v[12:13], v[12:13], 0, s[72:73]
	v_lshl_add_u64 v[12:13], v[12:13], 0, v[128:129]
	v_lshl_add_u64 v[12:13], v[12:13], 0, s[48:49]
	global_store_dwordx4 v[12:13], v[8:11], off sc1
	s_nop 1
	v_lshl_add_u32 v8, v14, 8, v35
	ds_read_b128 v[8:11], v8
	s_waitcnt lgkmcnt(0)
; __device__ __forceinline__ float siluf_(float x) { return x * sigmoidf_(x); }
; __device__ __forceinline__ void pool_item(const Params& p, int l, int item) {
;     ...
; #pragma unroll
;         for (int k = 0; k < 8; ++k) {
;             const int rl = rg + 32 * k, ksw = rl & 15;
;             uint4 v = *reinterpret_cast<const uint4*>(lds + rl * 256 + ((cg ^ (ksw >> 1)) << 4));
;             if (ksw & 1) v = make_uint4(v.z, v.w, v.x, v.y);
;             uint4 o;
;             o.x = pk2(bflo(v.x) * siluf_(bflo(gv[k].x)), bfhi(v.x) * siluf_(bfhi(gv[k].x)));
;             o.y = pk2(bflo(v.y) * siluf_(bflo(gv[k].y)), bfhi(v.y) * siluf_(bfhi(gv[k].y)));
;             o.z = pk2(bflo(v.z) * siluf_(bflo(gv[k].z)), bfhi(v.z) * siluf_(bfhi(gv[k].z)));
;             o.w = pk2(bflo(v.w) * siluf_(bflo(gv[k].w)), bfhi(v.w) * siluf_(bfhi(gv[k].w)));
;             st16_wt(P1 + (long)(r0 + rl) * P1W + 512 + g * 128 + cg * 8, o);
;         }
;     }
;     __syncthreads();
	v_cndmask_b32_e32 v12, v10, v8, vcc
	v_cndmask_b32_e32 v17, v8, v10, vcc
	s_waitcnt vmcnt(1)
	v_lshlrev_b32_e32 v10, 16, v4
	v_cndmask_b32_e32 v15, v11, v9, vcc
	v_cndmask_b32_e32 v16, v9, v11, vcc
	v_and_b32_e32 v11, 0xffff0000, v4
	v_mul_f32_e32 v4, 0xbfb8aa3b, v10
	v_exp_f32_e32 v4, v4
	v_lshlrev_b32_e32 v8, 16, v12
	v_and_b32_e32 v9, 0xffff0000, v12
	v_add_f32_e32 v4, 1.0, v4
	v_rcp_f32_e32 v12, v4
	v_mul_f32_e32 v4, 0xbfb8aa3b, v11
	v_exp_f32_e32 v4, v4
	s_nop 0
	v_add_f32_e32 v4, 1.0, v4
	v_rcp_f32_e32 v13, v4
	s_nop 0
	v_pk_mul_f32 v[10:11], v[12:13], v[10:11]
	s_nop 0
	v_pk_mul_f32 v[8:9], v[10:11], v[8:9]
	v_lshlrev_b32_e32 v10, 16, v5
	v_and_b32_e32 v11, 0xffff0000, v5
	v_mul_f32_e32 v5, 0xbfb8aa3b, v10
	v_exp_f32_e32 v5, v5
	v_cvt_pk_bf16_f32 v4, v8, v9
	v_lshlrev_b32_e32 v8, 16, v15
	v_and_b32_e32 v9, 0xffff0000, v15
	v_add_f32_e32 v5, 1.0, v5
	v_rcp_f32_e32 v12, v5
	v_mul_f32_e32 v5, 0xbfb8aa3b, v11
	v_exp_f32_e32 v5, v5
	s_nop 0
	v_add_f32_e32 v5, 1.0, v5
	v_rcp_f32_e32 v13, v5
	s_nop 0
	v_pk_mul_f32 v[10:11], v[12:13], v[10:11]
	s_nop 0
	v_pk_mul_f32 v[8:9], v[10:11], v[8:9]
	v_lshlrev_b32_e32 v12, 16, v17
	v_cvt_pk_bf16_f32 v5, v8, v9
	v_lshlrev_b32_e32 v8, 16, v6
	v_and_b32_e32 v9, 0xffff0000, v6
	v_mul_f32_e32 v6, 0xbfb8aa3b, v8
	v_exp_f32_e32 v6, v6
	v_and_b32_e32 v13, 0xffff0000, v17
	v_add_f32_e32 v6, 1.0, v6
	v_rcp_f32_e32 v10, v6
	v_mul_f32_e32 v6, 0xbfb8aa3b, v9
	v_exp_f32_e32 v6, v6
	s_nop 0
	v_add_f32_e32 v6, 1.0, v6
	v_rcp_f32_e32 v11, v6
	s_nop 0
	v_pk_mul_f32 v[8:9], v[10:11], v[8:9]
	s_nop 0
	v_pk_mul_f32 v[8:9], v[8:9], v[12:13]
	v_lshlrev_b32_e32 v12, 16, v16
	v_cvt_pk_bf16_f32 v6, v8, v9
	v_lshlrev_b32_e32 v8, 16, v7
	v_and_b32_e32 v9, 0xffff0000, v7
	v_mul_f32_e32 v7, 0xbfb8aa3b, v8
	v_exp_f32_e32 v7, v7
	v_and_b32_e32 v13, 0xffff0000, v16
	v_add_f32_e32 v7, 1.0, v7
	v_rcp_f32_e32 v10, v7
	v_mul_f32_e32 v7, 0xbfb8aa3b, v9
	v_exp_f32_e32 v7, v7
	s_nop 0
	v_add_f32_e32 v7, 1.0, v7
	v_rcp_f32_e32 v11, v7
	s_nop 0
	v_pk_mul_f32 v[8:9], v[10:11], v[8:9]
	s_nop 0
	v_pk_mul_f32 v[8:9], v[8:9], v[12:13]
	v_add_u32_e32 v10, 0xe0, v34
	v_cvt_pk_bf16_f32 v7, v8, v9
	v_add_u32_e32 v8, s6, v14
	v_ashrrev_i32_e32 v9, 31, v8
	v_lshlrev_b64 v[8:9], 13, v[8:9]
	v_lshl_add_u64 v[8:9], s[78:79], 0, v[8:9]
	v_lshl_add_u64 v[8:9], v[8:9], 0, s[72:73]
	v_lshl_add_u64 v[8:9], v[8:9], 0, v[128:129]
	v_lshl_add_u64 v[8:9], v[8:9], 0, s[48:49]
	global_store_dwordx4 v[8:9], v[4:7], off sc1
	s_nop 1
	v_lshl_add_u32 v4, v10, 8, v35
	ds_read_b128 v[4:7], v4
	s_waitcnt lgkmcnt(0)
	v_cndmask_b32_e32 v8, v6, v4, vcc
	v_cndmask_b32_e32 v13, v4, v6, vcc
	s_waitcnt vmcnt(0)
	v_lshlrev_b32_e32 v6, 16, v0
	v_cndmask_b32_e32 v11, v7, v5, vcc
	v_cndmask_b32_e32 v12, v5, v7, vcc
	v_and_b32_e32 v7, 0xffff0000, v0
	v_mul_f32_e32 v0, 0xbfb8aa3b, v6
	v_exp_f32_e32 v0, v0
	v_lshlrev_b32_e32 v4, 16, v8
	v_and_b32_e32 v5, 0xffff0000, v8
	v_add_f32_e32 v0, 1.0, v0
	v_rcp_f32_e32 v8, v0
	v_mul_f32_e32 v0, 0xbfb8aa3b, v7
	v_exp_f32_e32 v0, v0
	s_nop 0
	v_add_f32_e32 v0, 1.0, v0
	v_rcp_f32_e32 v9, v0
	s_nop 0
	v_pk_mul_f32 v[6:7], v[8:9], v[6:7]
	s_nop 0
	v_pk_mul_f32 v[4:5], v[6:7], v[4:5]
	v_lshlrev_b32_e32 v6, 16, v1
	v_and_b32_e32 v7, 0xffff0000, v1
	v_mul_f32_e32 v1, 0xbfb8aa3b, v6
	v_exp_f32_e32 v1, v1
	v_cvt_pk_bf16_f32 v0, v4, v5
	v_lshlrev_b32_e32 v4, 16, v11
	v_and_b32_e32 v5, 0xffff0000, v11
	v_add_f32_e32 v1, 1.0, v1
	v_rcp_f32_e32 v8, v1
	v_mul_f32_e32 v1, 0xbfb8aa3b, v7
	v_exp_f32_e32 v1, v1
	s_nop 0
	v_add_f32_e32 v1, 1.0, v1
	v_rcp_f32_e32 v9, v1
	s_nop 0
	v_pk_mul_f32 v[6:7], v[8:9], v[6:7]
	s_nop 0
	v_pk_mul_f32 v[4:5], v[6:7], v[4:5]
	v_lshlrev_b32_e32 v8, 16, v13
	v_cvt_pk_bf16_f32 v1, v4, v5
	v_lshlrev_b32_e32 v4, 16, v2
	v_and_b32_e32 v5, 0xffff0000, v2
	v_mul_f32_e32 v2, 0xbfb8aa3b, v4
	v_exp_f32_e32 v2, v2
	v_and_b32_e32 v9, 0xffff0000, v13
	v_add_f32_e32 v2, 1.0, v2
	v_rcp_f32_e32 v6, v2
	v_mul_f32_e32 v2, 0xbfb8aa3b, v5
	v_exp_f32_e32 v2, v2
	s_nop 0
	v_add_f32_e32 v2, 1.0, v2
	v_rcp_f32_e32 v7, v2
	s_nop 0
	v_pk_mul_f32 v[4:5], v[6:7], v[4:5]
	s_nop 0
	v_pk_mul_f32 v[4:5], v[4:5], v[8:9]
	v_lshlrev_b32_e32 v8, 16, v12
	v_cvt_pk_bf16_f32 v2, v4, v5
	v_lshlrev_b32_e32 v4, 16, v3
	v_and_b32_e32 v5, 0xffff0000, v3
	v_mul_f32_e32 v3, 0xbfb8aa3b, v4
	v_exp_f32_e32 v3, v3
	v_and_b32_e32 v9, 0xffff0000, v12
	v_add_f32_e32 v3, 1.0, v3
	v_rcp_f32_e32 v6, v3
	v_mul_f32_e32 v3, 0xbfb8aa3b, v5
	v_exp_f32_e32 v3, v3
	s_nop 0
	v_add_f32_e32 v3, 1.0, v3
	v_rcp_f32_e32 v7, v3
	s_nop 0
	v_pk_mul_f32 v[4:5], v[6:7], v[4:5]
	s_nop 0
	v_pk_mul_f32 v[4:5], v[4:5], v[8:9]
	s_nop 0
	v_cvt_pk_bf16_f32 v3, v4, v5
	v_add_u32_e32 v4, s6, v10
	v_ashrrev_i32_e32 v5, 31, v4
	v_lshlrev_b64 v[4:5], 13, v[4:5]
	v_lshl_add_u64 v[4:5], s[78:79], 0, v[4:5]
	v_lshl_add_u64 v[4:5], v[4:5], 0, s[72:73]
	v_lshl_add_u64 v[4:5], v[4:5], 0, v[128:129]
	v_lshl_add_u64 v[4:5], v[4:5], 0, s[48:49]
	global_store_dwordx4 v[4:5], v[0:3], off sc1
	s_nop 1
	s_barrier
	s_cbranch_scc1 .LBB0_334

; __device__ __forceinline__ uint4 epi_read(int row, int c16) {
;     const int k = row & 15;
;     uint4 v = *reinterpret_cast<const uint4*>((const char*)shm + row * 512 + ((c16 ^ (k >> 1)) << 4));
;     if (k & 1) v = make_uint4(v.z, v.w, v.x, v.y);
;     return v;
; }
.LBB0_402:
	ds_read_b128 v[28:31], v33 offset:8192
	s_waitcnt vmcnt(7)
	v_bfe_u32 v60, v58, 16, 8
	v_bfe_u32 v53, v58, 8, 8
	v_lshl_add_u32 v66, v60, 2, s6
	v_bfe_u32 v60, v59, 16, 8
	s_waitcnt lgkmcnt(0)
	v_cndmask_b32_e64 v37, v28, v30, s[4:5]
	v_cndmask_b32_e64 v41, v29, v31, s[4:5]
	v_cndmask_b32_e64 v45, v31, v29, s[4:5]
	v_cndmask_b32_e64 v49, v30, v28, s[4:5]
	v_lshlrev_b32_e32 v28, 16, v37
	v_and_b32_e32 v29, 0xffff0000, v37
	v_and_b32_e32 v37, 0xff, v58
	v_lshrrev_b32_e32 v58, 24, v58
	v_lshlrev_b32_e32 v30, 16, v41
	v_and_b32_e32 v31, 0xffff0000, v41
	v_lshl_add_u32 v37, v37, 2, s6
	v_and_b32_e32 v41, 0xff, v59
	v_bfe_u32 v57, v59, 8, 8
	v_lshl_add_u32 v67, v60, 2, s6
	v_lshl_add_u32 v69, v58, 2, s6
	v_lshrrev_b32_e32 v58, 24, v59
	v_lshl_add_u32 v41, v41, 2, s6
	v_lshl_add_u32 v53, v53, 2, s6
	v_lshl_add_u32 v57, v57, 2, s6
	v_lshl_add_u32 v70, v58, 2, s6
	ds_read_b32 v58, v37
	ds_read_b32 v60, v41
	ds_read_b32 v59, v53
	ds_read_b32 v61, v57
	ds_read_b32 v66, v66
	ds_read_b32 v68, v67
	ds_read_b32 v67, v69
	ds_read_b32 v69, v70
	v_lshlrev_b32_e32 v70, 16, v24
	v_and_b32_e32 v71, 0xffff0000, v24
	v_lshlrev_b32_e32 v72, 16, v49
	v_and_b32_e32 v73, 0xffff0000, v49
	s_waitcnt lgkmcnt(5)
	v_pk_fma_f32 v[58:59], v[58:59], v[72:73], v[70:71]
	v_lshlrev_b32_e32 v24, 16, v25
	v_and_b32_e32 v25, 0xffff0000, v25
	v_lshlrev_b32_e32 v70, 16, v45
	v_and_b32_e32 v71, 0xffff0000, v45
	s_waitcnt lgkmcnt(1)
	v_pk_fma_f32 v[66:67], v[66:67], v[70:71], v[24:25]
	v_lshlrev_b32_e32 v24, 16, v26
	v_and_b32_e32 v25, 0xffff0000, v26
	v_pk_fma_f32 v[28:29], v[60:61], v[28:29], v[24:25]
	v_lshlrev_b32_e32 v24, 16, v27
	v_and_b32_e32 v25, 0xffff0000, v27
	s_waitcnt lgkmcnt(0)
	v_pk_fma_f32 v[30:31], v[68:69], v[30:31], v[24:25]
	v_cvt_pk_bf16_f32 v24, v58, v59
	v_cvt_pk_bf16_f32 v25, v66, v67
	v_cvt_pk_bf16_f32 v26, v28, v29
	v_cvt_pk_bf16_f32 v27, v30, v31
	s_mov_b64 s[0:1], -1
	s_and_b64 vcc, exec, s[16:17]
	s_cbranch_vccz .LBB0_404
	global_store_dwordx4 v56, v[24:27], s[12:13]
	s_mov_b64 s[0:1], 0

; __device__ __forceinline__ uint4 epi_read(int row, int c16) {
;     const int k = row & 15;
;     uint4 v = *reinterpret_cast<const uint4*>((const char*)shm + row * 512 + ((c16 ^ (k >> 1)) << 4));
;     if (k & 1) v = make_uint4(v.z, v.w, v.x, v.y);
;     return v;
; }
.LBB0_406:
	ds_read_b128 v[24:27], v33 offset:16384
	s_waitcnt vmcnt(7)
	v_bfe_u32 v30, v54, 8, 8
	v_lshl_add_u32 v31, v30, 2, s6
	v_bfe_u32 v30, v55, 8, 8
	v_lshl_add_u32 v45, v30, 2, s6
	v_bfe_u32 v30, v54, 16, 8
	s_waitcnt lgkmcnt(0)
	v_cndmask_b32_e64 v28, v24, v26, s[4:5]
	v_cndmask_b32_e64 v29, v25, v27, s[4:5]
	v_lshl_add_u32 v49, v30, 2, s6
	v_bfe_u32 v30, v55, 16, 8
	v_cndmask_b32_e64 v37, v27, v25, s[4:5]
	v_cndmask_b32_e64 v41, v26, v24, s[4:5]
	v_lshlrev_b32_e32 v24, 16, v28
	v_and_b32_e32 v25, 0xffff0000, v28
	v_lshlrev_b32_e32 v26, 16, v29
	v_and_b32_e32 v27, 0xffff0000, v29
	v_and_b32_e32 v28, 0xff, v54
	v_and_b32_e32 v29, 0xff, v55
	v_lshl_add_u32 v53, v30, 2, s6
	v_lshrrev_b32_e32 v30, 24, v54
	v_lshl_add_u32 v28, v28, 2, s6
	v_lshl_add_u32 v29, v29, 2, s6
	v_lshl_add_u32 v57, v30, 2, s6
	v_lshrrev_b32_e32 v30, 24, v55
	v_lshl_add_u32 v58, v30, 2, s6
	ds_read_b32 v28, v28
	ds_read_b32 v30, v29
	ds_read_b32 v29, v31
	ds_read_b32 v31, v45
	ds_read_b32 v54, v49
	ds_read_b32 v56, v53
	ds_read_b32 v55, v57
	ds_read_b32 v57, v58
	v_lshlrev_b32_e32 v58, 16, v20
	v_and_b32_e32 v59, 0xffff0000, v20
	v_lshlrev_b32_e32 v60, 16, v41
	v_and_b32_e32 v61, 0xffff0000, v41
	s_waitcnt lgkmcnt(5)
	v_pk_fma_f32 v[28:29], v[28:29], v[60:61], v[58:59]
	v_lshlrev_b32_e32 v20, 16, v21
	v_and_b32_e32 v21, 0xffff0000, v21
	v_lshlrev_b32_e32 v58, 16, v37
	v_and_b32_e32 v59, 0xffff0000, v37
	s_waitcnt lgkmcnt(1)
	v_pk_fma_f32 v[54:55], v[54:55], v[58:59], v[20:21]
	v_lshlrev_b32_e32 v20, 16, v22
	v_and_b32_e32 v21, 0xffff0000, v22
	v_pk_fma_f32 v[24:25], v[30:31], v[24:25], v[20:21]
	v_lshlrev_b32_e32 v20, 16, v23
	v_and_b32_e32 v21, 0xffff0000, v23
	s_waitcnt lgkmcnt(0)
	v_pk_fma_f32 v[26:27], v[56:57], v[26:27], v[20:21]
	v_cvt_pk_bf16_f32 v20, v28, v29
	v_cvt_pk_bf16_f32 v21, v54, v55
	v_cvt_pk_bf16_f32 v22, v24, v25
	v_cvt_pk_bf16_f32 v23, v26, v27
	s_mov_b64 s[0:1], -1
	s_and_b64 vcc, exec, s[16:17]
	s_cbranch_vccz .LBB0_408
	global_store_dwordx4 v52, v[20:23], s[12:13]
	s_mov_b64 s[0:1], 0

; __device__ __forceinline__ uint4 epi_read(int row, int c16) {
;     const int k = row & 15;
;     uint4 v = *reinterpret_cast<const uint4*>((const char*)shm + row * 512 + ((c16 ^ (k >> 1)) << 4));
;     if (k & 1) v = make_uint4(v.z, v.w, v.x, v.y);
;     return v;
; }
.LBB0_410:
	ds_read_b128 v[20:23], v33 offset:24576
	s_waitcnt vmcnt(7)
	v_bfe_u32 v26, v50, 8, 8
	v_lshl_add_u32 v27, v26, 2, s6
	v_bfe_u32 v26, v51, 8, 8
	v_lshl_add_u32 v28, v26, 2, s6
	v_bfe_u32 v26, v50, 16, 8
	s_waitcnt lgkmcnt(0)
	v_cndmask_b32_e64 v24, v20, v22, s[4:5]
	v_cndmask_b32_e64 v25, v21, v23, s[4:5]
	v_lshl_add_u32 v29, v26, 2, s6
	v_bfe_u32 v26, v51, 16, 8
	v_cndmask_b32_e64 v37, v23, v21, s[4:5]
	v_cndmask_b32_e64 v41, v22, v20, s[4:5]
	v_lshlrev_b32_e32 v20, 16, v24
	v_and_b32_e32 v21, 0xffff0000, v24
	v_lshlrev_b32_e32 v22, 16, v25
	v_and_b32_e32 v23, 0xffff0000, v25
	v_and_b32_e32 v24, 0xff, v50
	v_and_b32_e32 v25, 0xff, v51
	v_lshl_add_u32 v30, v26, 2, s6
	v_lshrrev_b32_e32 v26, 24, v50
	v_lshl_add_u32 v24, v24, 2, s6
	v_lshl_add_u32 v25, v25, 2, s6
	v_lshl_add_u32 v31, v26, 2, s6
	v_lshrrev_b32_e32 v26, 24, v51
	v_lshl_add_u32 v45, v26, 2, s6
	ds_read_b32 v24, v24
	ds_read_b32 v26, v25
	ds_read_b32 v25, v27
	ds_read_b32 v27, v28
	ds_read_b32 v28, v29
	ds_read_b32 v30, v30
	ds_read_b32 v29, v31
	ds_read_b32 v31, v45
	v_lshlrev_b32_e32 v50, 16, v16
	v_and_b32_e32 v51, 0xffff0000, v16
	v_lshlrev_b32_e32 v52, 16, v41
	v_and_b32_e32 v53, 0xffff0000, v41
	s_waitcnt lgkmcnt(5)
	v_pk_fma_f32 v[24:25], v[24:25], v[52:53], v[50:51]
	v_lshlrev_b32_e32 v16, 16, v17
	v_and_b32_e32 v17, 0xffff0000, v17
	v_lshlrev_b32_e32 v50, 16, v37
	v_and_b32_e32 v51, 0xffff0000, v37
	s_waitcnt lgkmcnt(1)
	v_pk_fma_f32 v[28:29], v[28:29], v[50:51], v[16:17]
	v_lshlrev_b32_e32 v16, 16, v18
	v_and_b32_e32 v17, 0xffff0000, v18
	v_pk_fma_f32 v[20:21], v[26:27], v[20:21], v[16:17]
	v_lshlrev_b32_e32 v16, 16, v19
	v_and_b32_e32 v17, 0xffff0000, v19
	s_waitcnt lgkmcnt(0)
	v_pk_fma_f32 v[22:23], v[30:31], v[22:23], v[16:17]
	v_cvt_pk_bf16_f32 v16, v24, v25
	v_cvt_pk_bf16_f32 v17, v28, v29
	v_cvt_pk_bf16_f32 v18, v20, v21
	v_cvt_pk_bf16_f32 v19, v22, v23
	s_mov_b64 s[0:1], -1
	s_and_b64 vcc, exec, s[16:17]
	s_cbranch_vccz .LBB0_412
	global_store_dwordx4 v48, v[16:19], s[12:13]
	s_mov_b64 s[0:1], 0

; __device__ __forceinline__ uint4 epi_read(int row, int c16) {
;     const int k = row & 15;
;     uint4 v = *reinterpret_cast<const uint4*>((const char*)shm + row * 512 + ((c16 ^ (k >> 1)) << 4));
;     if (k & 1) v = make_uint4(v.z, v.w, v.x, v.y);
;     return v;
; }
.LBB0_414:
	ds_read_b128 v[16:19], v33 offset:32768
	s_waitcnt vmcnt(7)
	v_bfe_u32 v22, v46, 8, 8
	v_lshl_add_u32 v23, v22, 2, s6
	v_bfe_u32 v22, v47, 8, 8
	v_lshl_add_u32 v24, v22, 2, s6
	v_bfe_u32 v22, v46, 16, 8
	s_waitcnt lgkmcnt(0)
	v_cndmask_b32_e64 v20, v16, v18, s[4:5]
	v_cndmask_b32_e64 v21, v17, v19, s[4:5]
	v_lshl_add_u32 v25, v22, 2, s6
	v_bfe_u32 v22, v47, 16, 8
	v_cndmask_b32_e64 v37, v19, v17, s[4:5]
	v_cndmask_b32_e64 v31, v18, v16, s[4:5]
	v_lshlrev_b32_e32 v16, 16, v20
	v_and_b32_e32 v17, 0xffff0000, v20
	v_lshlrev_b32_e32 v18, 16, v21
	v_and_b32_e32 v19, 0xffff0000, v21
	v_and_b32_e32 v20, 0xff, v46
	v_and_b32_e32 v21, 0xff, v47
	v_lshl_add_u32 v26, v22, 2, s6
	v_lshrrev_b32_e32 v22, 24, v46
	v_lshl_add_u32 v20, v20, 2, s6
	v_lshl_add_u32 v21, v21, 2, s6
	v_lshl_add_u32 v27, v22, 2, s6
	v_lshrrev_b32_e32 v22, 24, v47
	v_lshl_add_u32 v28, v22, 2, s6
	ds_read_b32 v20, v20
	ds_read_b32 v22, v21
	ds_read_b32 v21, v23
	ds_read_b32 v23, v24
	ds_read_b32 v24, v25
	ds_read_b32 v26, v26
	ds_read_b32 v25, v27
	ds_read_b32 v27, v28
	v_lshlrev_b32_e32 v28, 16, v12
	v_and_b32_e32 v29, 0xffff0000, v12
	v_lshlrev_b32_e32 v30, 16, v31
	v_and_b32_e32 v31, 0xffff0000, v31
	s_waitcnt lgkmcnt(5)
	v_pk_fma_f32 v[20:21], v[20:21], v[30:31], v[28:29]
	v_lshlrev_b32_e32 v12, 16, v13
	v_and_b32_e32 v13, 0xffff0000, v13
	v_lshlrev_b32_e32 v28, 16, v37
	v_and_b32_e32 v29, 0xffff0000, v37
	s_waitcnt lgkmcnt(1)
	v_pk_fma_f32 v[24:25], v[24:25], v[28:29], v[12:13]
	v_lshlrev_b32_e32 v12, 16, v14
	v_and_b32_e32 v13, 0xffff0000, v14
	v_pk_fma_f32 v[16:17], v[22:23], v[16:17], v[12:13]
	v_lshlrev_b32_e32 v12, 16, v15
	v_and_b32_e32 v13, 0xffff0000, v15
	s_waitcnt lgkmcnt(0)
	v_pk_fma_f32 v[18:19], v[26:27], v[18:19], v[12:13]
	v_cvt_pk_bf16_f32 v12, v20, v21
	v_cvt_pk_bf16_f32 v13, v24, v25
	v_cvt_pk_bf16_f32 v14, v16, v17
	v_cvt_pk_bf16_f32 v15, v18, v19
	s_mov_b64 s[0:1], -1
	s_and_b64 vcc, exec, s[16:17]
	s_cbranch_vccz .LBB0_416
	global_store_dwordx4 v44, v[12:15], s[12:13]
	s_mov_b64 s[0:1], 0

; __device__ __forceinline__ uint4 epi_read(int row, int c16) {
;     const int k = row & 15;
;     uint4 v = *reinterpret_cast<const uint4*>((const char*)shm + row * 512 + ((c16 ^ (k >> 1)) << 4));
;     if (k & 1) v = make_uint4(v.z, v.w, v.x, v.y);
;     return v;
; }
.LBB0_418:
	ds_read_b128 v[12:15], v33 offset:40960
	s_waitcnt vmcnt(7)
	v_bfe_u32 v18, v42, 8, 8
	v_lshl_add_u32 v19, v18, 2, s6
	v_bfe_u32 v18, v43, 8, 8
	v_lshl_add_u32 v20, v18, 2, s6
	v_bfe_u32 v18, v42, 16, 8
	s_waitcnt lgkmcnt(0)
	v_cndmask_b32_e64 v16, v12, v14, s[4:5]
	v_cndmask_b32_e64 v17, v13, v15, s[4:5]
	v_lshl_add_u32 v21, v18, 2, s6
	v_bfe_u32 v18, v43, 16, 8
	v_cndmask_b32_e64 v28, v15, v13, s[4:5]
	v_cndmask_b32_e64 v27, v14, v12, s[4:5]
	v_lshlrev_b32_e32 v12, 16, v16
	v_and_b32_e32 v13, 0xffff0000, v16
	v_lshlrev_b32_e32 v14, 16, v17
	v_and_b32_e32 v15, 0xffff0000, v17
	v_and_b32_e32 v16, 0xff, v42
	v_and_b32_e32 v17, 0xff, v43
	v_lshl_add_u32 v22, v18, 2, s6
	v_lshrrev_b32_e32 v18, 24, v42
	v_lshl_add_u32 v16, v16, 2, s6
	v_lshl_add_u32 v17, v17, 2, s6
	v_lshl_add_u32 v23, v18, 2, s6
	v_lshrrev_b32_e32 v18, 24, v43
	v_lshl_add_u32 v24, v18, 2, s6
	ds_read_b32 v16, v16
	ds_read_b32 v18, v17
	ds_read_b32 v17, v19
	ds_read_b32 v19, v20
	ds_read_b32 v20, v21
	ds_read_b32 v22, v22
	ds_read_b32 v21, v23
	ds_read_b32 v23, v24
	v_lshlrev_b32_e32 v24, 16, v8
	v_and_b32_e32 v25, 0xffff0000, v8
	v_lshlrev_b32_e32 v26, 16, v27
	v_and_b32_e32 v27, 0xffff0000, v27
	s_waitcnt lgkmcnt(5)
	v_pk_fma_f32 v[16:17], v[16:17], v[26:27], v[24:25]
	v_lshlrev_b32_e32 v8, 16, v9
	v_and_b32_e32 v9, 0xffff0000, v9
	v_lshlrev_b32_e32 v24, 16, v28
	v_and_b32_e32 v25, 0xffff0000, v28
	s_waitcnt lgkmcnt(1)
	v_pk_fma_f32 v[20:21], v[20:21], v[24:25], v[8:9]
	v_lshlrev_b32_e32 v8, 16, v10
	v_and_b32_e32 v9, 0xffff0000, v10
	v_pk_fma_f32 v[12:13], v[18:19], v[12:13], v[8:9]
	v_lshlrev_b32_e32 v8, 16, v11
	v_and_b32_e32 v9, 0xffff0000, v11
	s_waitcnt lgkmcnt(0)
	v_pk_fma_f32 v[14:15], v[22:23], v[14:15], v[8:9]
	v_cvt_pk_bf16_f32 v8, v16, v17
	v_cvt_pk_bf16_f32 v9, v20, v21
	v_cvt_pk_bf16_f32 v10, v12, v13
	v_cvt_pk_bf16_f32 v11, v14, v15
	s_mov_b64 s[0:1], -1
	s_and_b64 vcc, exec, s[16:17]
	s_cbranch_vccz .LBB0_420
	global_store_dwordx4 v40, v[8:11], s[12:13]
	s_mov_b64 s[0:1], 0

; __device__ __forceinline__ uint4 epi_read(int row, int c16) {
;     const int k = row & 15;
;     uint4 v = *reinterpret_cast<const uint4*>((const char*)shm + row * 512 + ((c16 ^ (k >> 1)) << 4));
;     if (k & 1) v = make_uint4(v.z, v.w, v.x, v.y);
;     return v;
; }
.LBB0_422:
	ds_read_b128 v[8:11], v33 offset:49152
	s_waitcnt vmcnt(7)
	v_bfe_u32 v14, v38, 8, 8
	v_lshl_add_u32 v15, v14, 2, s6
	v_bfe_u32 v14, v39, 8, 8
	v_lshl_add_u32 v16, v14, 2, s6
	v_bfe_u32 v14, v38, 16, 8
	s_waitcnt lgkmcnt(0)
	v_cndmask_b32_e64 v12, v8, v10, s[4:5]
	v_cndmask_b32_e64 v13, v9, v11, s[4:5]
	v_lshl_add_u32 v17, v14, 2, s6
	v_bfe_u32 v14, v39, 16, 8
	v_cndmask_b32_e64 v24, v11, v9, s[4:5]
	v_cndmask_b32_e64 v23, v10, v8, s[4:5]
	v_lshlrev_b32_e32 v8, 16, v12
	v_and_b32_e32 v9, 0xffff0000, v12
	v_lshlrev_b32_e32 v10, 16, v13
	v_and_b32_e32 v11, 0xffff0000, v13
	v_and_b32_e32 v12, 0xff, v38
	v_and_b32_e32 v13, 0xff, v39
	v_lshl_add_u32 v18, v14, 2, s6
	v_lshrrev_b32_e32 v14, 24, v38
	v_lshl_add_u32 v12, v12, 2, s6
	v_lshl_add_u32 v13, v13, 2, s6
	v_lshl_add_u32 v19, v14, 2, s6
	v_lshrrev_b32_e32 v14, 24, v39
	v_lshl_add_u32 v20, v14, 2, s6
	ds_read_b32 v12, v12
	ds_read_b32 v14, v13
	ds_read_b32 v13, v15
	ds_read_b32 v15, v16
	ds_read_b32 v16, v17
	ds_read_b32 v18, v18
	ds_read_b32 v17, v19
	ds_read_b32 v19, v20
	v_lshlrev_b32_e32 v20, 16, v4
	v_and_b32_e32 v21, 0xffff0000, v4
	v_lshlrev_b32_e32 v22, 16, v23
	v_and_b32_e32 v23, 0xffff0000, v23
	s_waitcnt lgkmcnt(5)
	v_pk_fma_f32 v[12:13], v[12:13], v[22:23], v[20:21]
	v_lshlrev_b32_e32 v4, 16, v5
	v_and_b32_e32 v5, 0xffff0000, v5
	v_lshlrev_b32_e32 v20, 16, v24
	v_and_b32_e32 v21, 0xffff0000, v24
	s_waitcnt lgkmcnt(1)
	v_pk_fma_f32 v[16:17], v[16:17], v[20:21], v[4:5]
	v_lshlrev_b32_e32 v4, 16, v6
	v_and_b32_e32 v5, 0xffff0000, v6
	v_pk_fma_f32 v[8:9], v[14:15], v[8:9], v[4:5]
	v_lshlrev_b32_e32 v4, 16, v7
	v_and_b32_e32 v5, 0xffff0000, v7
	s_waitcnt lgkmcnt(0)
	v_pk_fma_f32 v[10:11], v[18:19], v[10:11], v[4:5]
	v_cvt_pk_bf16_f32 v4, v12, v13
	v_cvt_pk_bf16_f32 v5, v16, v17
	v_cvt_pk_bf16_f32 v6, v8, v9
	v_cvt_pk_bf16_f32 v7, v10, v11
	s_mov_b64 s[0:1], -1
	s_and_b64 vcc, exec, s[16:17]
	s_cbranch_vccz .LBB0_424
	global_store_dwordx4 v36, v[4:7], s[12:13]
	s_mov_b64 s[0:1], 0

; __device__ __forceinline__ uint4 epi_read(int row, int c16) {
;     const int k = row & 15;
;     uint4 v = *reinterpret_cast<const uint4*>((const char*)shm + row * 512 + ((c16 ^ (k >> 1)) << 4));
;     if (k & 1) v = make_uint4(v.z, v.w, v.x, v.y);
;     return v;
; }
.LBB0_426:
	ds_read_b128 v[4:7], v33 offset:57344
	s_waitcnt vmcnt(7)
	v_bfe_u32 v10, v34, 8, 8
	v_lshl_add_u32 v11, v10, 2, s6
	v_bfe_u32 v10, v35, 8, 8
	v_lshl_add_u32 v12, v10, 2, s6
	v_bfe_u32 v10, v34, 16, 8
	s_waitcnt lgkmcnt(0)
	v_cndmask_b32_e64 v8, v4, v6, s[4:5]
	v_cndmask_b32_e64 v9, v5, v7, s[4:5]
	v_lshl_add_u32 v13, v10, 2, s6
	v_bfe_u32 v10, v35, 16, 8
	v_cndmask_b32_e64 v20, v7, v5, s[4:5]
	v_cndmask_b32_e64 v19, v6, v4, s[4:5]
	v_lshlrev_b32_e32 v4, 16, v8
	v_and_b32_e32 v5, 0xffff0000, v8
	v_lshlrev_b32_e32 v6, 16, v9
	v_and_b32_e32 v7, 0xffff0000, v9
	v_and_b32_e32 v8, 0xff, v34
	v_and_b32_e32 v9, 0xff, v35
	v_lshl_add_u32 v14, v10, 2, s6
	v_lshrrev_b32_e32 v10, 24, v34
	v_lshl_add_u32 v8, v8, 2, s6
	v_lshl_add_u32 v9, v9, 2, s6
	v_lshl_add_u32 v15, v10, 2, s6
	v_lshrrev_b32_e32 v10, 24, v35
	v_lshl_add_u32 v16, v10, 2, s6
	ds_read_b32 v8, v8
	ds_read_b32 v10, v9
	ds_read_b32 v9, v11
	ds_read_b32 v11, v12
	ds_read_b32 v12, v13
	ds_read_b32 v14, v14
	ds_read_b32 v13, v15
	ds_read_b32 v15, v16
	v_lshlrev_b32_e32 v16, 16, v0
	v_and_b32_e32 v17, 0xffff0000, v0
	v_lshlrev_b32_e32 v18, 16, v19
	v_and_b32_e32 v19, 0xffff0000, v19
	s_waitcnt lgkmcnt(5)
	v_pk_fma_f32 v[8:9], v[8:9], v[18:19], v[16:17]
	v_lshlrev_b32_e32 v0, 16, v1
	v_and_b32_e32 v1, 0xffff0000, v1
	v_lshlrev_b32_e32 v16, 16, v20
	v_and_b32_e32 v17, 0xffff0000, v20
	s_waitcnt lgkmcnt(1)
	v_pk_fma_f32 v[12:13], v[12:13], v[16:17], v[0:1]
	v_lshlrev_b32_e32 v0, 16, v2
	v_and_b32_e32 v1, 0xffff0000, v2
	v_pk_fma_f32 v[4:5], v[10:11], v[4:5], v[0:1]
	v_lshlrev_b32_e32 v0, 16, v3
	v_and_b32_e32 v1, 0xffff0000, v3
	s_waitcnt lgkmcnt(0)
	v_pk_fma_f32 v[6:7], v[14:15], v[6:7], v[0:1]
	v_cvt_pk_bf16_f32 v0, v8, v9
	v_cvt_pk_bf16_f32 v1, v12, v13
	v_cvt_pk_bf16_f32 v2, v4, v5
	v_cvt_pk_bf16_f32 v3, v6, v7
	s_mov_b64 s[0:1], -1
	s_and_b64 vcc, exec, s[16:17]
	s_cbranch_vccz .LBB0_428
	global_store_dwordx4 v32, v[0:3], s[12:13]
	s_mov_b64 s[0:1], 0
